# static s_setprio 1 for waves 4-7 per GEMM phase, per-segment flips removed (on top of saddr DMA + MFMA pair swap)
# speedup vs baseline: 1.0119x; 1.0060x over previous
; #define LAS __attribute__((address_space(3)))
; #define WS_SETUP unsigned char* ws = P.ws; asm volatile("" : "+s"(ws)); float* R = P.out; asm volatile("" : "+s"(R)); (void)R;
; __global__ void __launch_bounds__(NWAVES * 64, 2) mega_fwd(Params P) {
;     ...
;     { WS_SETUP TID_SETUP
;             LAS float* scr = (LAS float*)wlds;
;             for (long i = gt; i < (long)(3 * MTOK * 2 + 2 * 20480) / 4; i += NGT) { f32x4* z = (i < 3 * MTOK * 2 / 4) ? (f32x4*)STATS + i : (f32x4*)C1 + (i - 3 * MTOK * 2 / 4); *z = (f32x4){0.f, 0.f, 0.f, 0.f}; }
.LBB0_17:
	s_load_dwordx2 s[84:85], s[0:1], 0x90
	s_mov_b64 s[6:7], s[78:79]
	s_mov_b64 s[4:5], s[76:77]
	v_mov_b32_e32 v34, v204
	s_setprio 0
	s_mov_b32 s3, 0
	s_lshl_b64 s[82:83], s[2:3], 9
	v_ashrrev_i32_e32 v35, 31, v34
	s_waitcnt lgkmcnt(0)
	s_ashr_i32 s85, s84, 31
	v_lshl_add_u64 v[32:33], s[82:83], 0, v[34:35]
	s_mov_b64 s[4:5], 0x8800
	s_lshl_b64 s[86:87], s[84:85], 9
	v_readfirstlane_b32 s16, v34
	v_cmp_gt_i64_e32 vcc, s[4:5], v[32:33]
	s_and_saveexec_b64 s[4:5], vcc
	s_cbranch_execz .LBB0_20
	s_lshl_b64 s[8:9], s[2:3], 13
	s_add_u32 s8, s6, s8
	s_addc_u32 s9, s7, s9
	v_mov_b32_e32 v3, 0
	v_lshl_add_u64 v[0:1], v[34:35], 4, s[8:9]
	s_lshl_b64 s[8:9], s[84:85], 13
	s_mov_b64 s[10:11], 0
	s_mov_b64 s[12:13], 0x6000
	v_mov_b32_e32 v6, 0x20000
	v_mov_b32_e32 v7, 0x10000
	v_mov_b32_e32 v8, v3
	v_mov_b32_e32 v9, v3
	v_mov_b32_e32 v10, v3
	v_mov_b32_e32 v11, v3
	s_mov_b64 s[14:15], 0x87ff
	v_mov_b64_e32 v[4:5], v[32:33]

; template <class Epi, class Sched, bool ALIGN_EPI = false, bool SP2 = false>
; __device__ __forceinline__ void gemm_phase(PG8_LAS unsigned char* lds, const Gemm g, const Sched& S, const Epi& E) {
;     int tid_ = threadIdx.x; asm volatile("" : "+v"(tid_));
;     const int tid = tid_, wid = __builtin_amdgcn_readfirstlane(tid >> 6), lane = tid & 63, wr = wid >> 2, wc = wid & 3, fr = lane & 15, fq = lane >> 4;
;     const int K = g.K, nt = K / BK;
;     unsigned voffA[2], voffB[2];
; #pragma unroll
;     for (int i = 0; i < 2; ++i) { int R, C; stage_rc(tid * 16 + i * 8192, R, C); const int Rb = E.perm ? ((R & ~31) + perm32(R & 31)) : R;
;         voffA[i] = (unsigned)(R * K + C) * 2u; voffB[i] = (unsigned)(Rb * K + C) * 2u; }
;     const size_t kstep = (size_t)(BK * 2);
;     const size_t hstep = (size_t)HALF * K * 2;
;     const size_t tstep = 2 * hstep;
;     const unsigned ldsw = (unsigned)wid * 1024u;
;     const int aoff = lds_byte(wr * 64 + fr, fq * 8), boff = lds_byte(wc * 32 + fr, fq * 8);
;     ...
;     Unit cur, nxt; int ui = 0;
;     if (!S.next(0, cur)) return;
;     f32x4 acc[2][2][4][2];
; #pragma unroll
;     for (int a = 0; a < 2; ++a)
; #pragma unroll
;         for (int b = 0; b < 2; ++b)
; #pragma unroll
;             for (int m = 0; m < 4; ++m)
; #pragma unroll
;                 for (int n = 0; n < 2; ++n) acc[a][b][m][n] = (f32x4){0.f, 0.f, 0.f, 0.f};
;     bf16x8 At[4][2], B0[2][2], B1[2][2];
;     const char* cA = (const char*)g.A + (size_t)cur.pm * tstep; const char* cB = (const char*)g.Bt + (size_t)cur.pn * tstep;
;     S.a_ready(cur);
;     if constexpr (SP2) {
;         PG8_STAGE(PG8_SB(0, 0), cB, voffB); PG8_STAGE(PG8_SB(0, 1), cB + hstep, voffB); PG8_STAGE(PG8_SA(0, 0), cA, voffA); PG8_STAGE(PG8_SA(0, 1), cA + hstep, voffA);
;         if (wr == 1) PG8_BAR;
;         PG8_WAIT_V(2); PG8_BAR;
;         PG8_STAGE(PG8_SB(1, 0), cB + kstep, voffB); PG8_STAGE(PG8_SA(1, 0), cA + kstep, voffA); PG8_STAGE(PG8_SB(1, 1), cB + hstep + kstep, voffB);
;         PG8_WAIT_V(6); PG8_BAR;
; __global__ void __launch_bounds__(NWAVES * 64, 2) mega_fwd(Params P) {
;     ...
;     { WS_SETUP pg8::Gemm g{XB, (const h16*)(ws + WS_W_EIN), MTOK, EVEN_IN, DM}; pg8::EpiAny<0, 0> E{}; E.O = H; E.ldc = EVEN_IN;
;       pg8::StaticOrder S; S.init(MTOK, EVEN_IN, G, (int)blockIdx.x, WGM_IN);
;       pg8::gemm_phase<pg8::EpiAny<0, 0>, pg8::StaticOrder, true, true>(lds, g, S, E); }
.LBB0_137:
	s_or_b64 exec, exec, s[0:1]
	s_mov_b64 s[4:5], s[78:79]
	s_mov_b64 s[0:1], s[76:77]
	v_mov_b32_e32 v8, v204
	s_setprio 0
	v_readfirstlane_b32 s98, v204
	s_lshr_b32 s98, s98, 8
	s_cmp_lg_u32 s98, 0
	s_cbranch_scc0 .Lsprio_skip_0
	s_setprio 1
.Lsprio_skip_0:
	s_waitcnt lgkmcnt(0)
	s_barrier
	s_cmpk_gt_i32 s2, 0x5bf
	v_readfirstlane_b32 s11, v8
	s_cbranch_scc1 .LBB0_153
	v_lshlrev_b32_e32 v0, 4, v8
	v_add_u32_e32 v1, 0x2000, v0
	v_ashrrev_i32_e32 v2, 31, v1
	v_lshrrev_b32_e32 v2, 22, v2
	v_add_u32_e32 v2, v1, v2
	v_ashrrev_i32_e32 v9, 10, v2
	v_mul_i32_i24_e32 v2, 0x400, v9
	v_sub_u32_e32 v1, v1, v2
	v_lshrrev_b32_e32 v2, 4, v1
	v_bitop3_b32 v1, v2, v1, 32 bitop3:0x6c
	v_ashrrev_i32_e32 v2, 31, v1
	v_lshrrev_b32_e32 v2, 26, v2
	v_add_u32_e32 v2, v1, v2
	v_lshlrev_b32_e32 v3, 3, v9
	v_ashrrev_i32_e32 v10, 6, v2
	v_and_b32_e32 v3, -16, v3
	v_add_u32_e32 v3, v10, v3
	v_and_b32_e32 v4, 3, v10
	s_mov_b32 s0, 0xfffe0
	v_lshrrev_b32_e32 v5, 2, v3
	v_lshlrev_b32_e32 v6, 1, v3
	v_and_b32_e32 v2, 0xc0, v2
	v_and_or_b32 v4, v3, s0, v4
	v_and_b32_e32 v5, 4, v5
	v_and_b32_e32 v6, 24, v6
	v_sub_u32_e32 v1, v1, v2
	v_mov_b32_e32 v2, 1
	v_or3_b32 v4, v4, v5, v6
	v_lshlrev_b32_e32 v5, 5, v9
	v_ashrrev_i16_sdwa v1, v2, sext(v1) dst_sel:DWORD dst_unused:UNUSED_PAD src0_sel:DWORD src1_sel:BYTE_0
	v_and_b32_e32 v5, 32, v5
	v_bfe_i32 v11, v1, 0, 16
	v_add_lshl_u32 v1, v5, v11, 1
	v_lshl_add_u32 v128, v4, 12, v1
	v_lshl_add_u32 v130, v3, 12, v1
	v_bfe_i32 v1, v8, 27, 1
	v_lshrrev_b32_e32 v1, 22, v1
	v_add_u32_e32 v1, v0, v1
	v_and_b32_e32 v1, 0xfffffc00, v1
	v_sub_u32_e32 v0, v0, v1
	v_lshrrev_b32_e32 v1, 4, v0
	v_ashrrev_i32_e32 v3, 31, v8
	v_bitop3_b32 v0, v1, v0, 32 bitop3:0x6c
	v_lshrrev_b32_e32 v3, 26, v3
	v_ashrrev_i32_e32 v1, 31, v0
	v_add_u32_e32 v3, v8, v3
	s_add_u32 s28, s4, 0xba00000
	v_lshrrev_b32_e32 v1, 26, v1
	v_ashrrev_i32_e32 v13, 6, v3
	s_addc_u32 s29, s5, 0
	v_add_u32_e32 v1, v0, v1
	v_lshlrev_b32_e32 v3, 3, v13
	s_add_u32 s30, s4, 0x5d00000
	v_ashrrev_i32_e32 v12, 6, v1
	v_and_b32_e32 v3, -16, v3
	s_addc_u32 s31, s5, 0
	v_add_u32_e32 v3, v12, v3
	v_and_b32_e32 v4, 3, v12
	s_ashr_i32 s35, s2, 31
	v_and_or_b32 v4, v3, s0, v4
	s_lshr_b32 s0, s35, 29
	s_add_i32 s0, s2, s0
	s_ashr_i32 s8, s11, 6
	s_ashr_i32 s1, s0, 3
	s_and_b32 s0, s0, -8
	s_ashr_i32 s14, s11, 8
	s_lshl_b32 s34, s8, 10
	s_sub_i32 s0, s2, s0
	s_cmp_lt_i32 s0, 0
	s_movk_i32 s36, 0xb9
	s_cselect_b32 s6, s36, 0xb8
	s_mul_i32 s0, s0, s6
	s_add_i32 s0, s0, s1
	s_mul_hi_i32 s1, s0, 0xb21642c9
	s_add_i32 s1, s1, s0
	s_lshr_b32 s6, s1, 31
	s_ashr_i32 s1, s1, 6
	s_add_i32 s1, s1, s6
	s_lshl_b32 s6, s1, 2
	s_mulk_i32 s1, 0x5c
	s_sub_i32 s0, s0, s1
	s_bfe_i32 s1, s0, 0x80000
	s_bfe_u32 s1, s1, 0x2000d
	s_add_i32 s1, s0, s1
	s_bfe_i32 s7, s1, 0x80000
	s_and_b32 s1, s1, 0xfc
	s_sub_i32 s0, s0, s1
	s_sext_i32_i16 s7, s7
	s_sext_i32_i8 s0, s0
	v_lshrrev_b32_e32 v5, 2, v3
	v_lshlrev_b32_e32 v6, 1, v3
	v_and_b32_e32 v1, 0xc0, v1
	s_lshr_b32 s10, s7, 2
	s_add_i32 s12, s6, s0
	v_and_b32_e32 v5, 4, v5
	v_and_b32_e32 v6, 24, v6
	v_sub_u32_e32 v0, v0, v1
	s_ashr_i32 s13, s12, 31
	s_bfe_i64 s[6:7], s[10:11], 0x100000
	v_or3_b32 v4, v4, v5, v6
	v_lshlrev_b32_e32 v5, 5, v13
	v_ashrrev_i16_sdwa v0, v2, sext(v0) dst_sel:DWORD dst_unused:UNUSED_PAD src0_sel:DWORD src1_sel:BYTE_0
	s_lshl_b64 s[0:1], s[12:13], 20
	s_lshl_b64 s[6:7], s[6:7], 20
	v_and_b32_e32 v5, 32, v5
	v_bfe_i32 v14, v0, 0, 16
	s_add_u32 s22, s30, s6
	v_add_lshl_u32 v0, v5, v14, 1
	s_addc_u32 s23, s31, s7
	s_add_i32 s13, s34, 0
	v_lshl_add_u32 v132, v4, 12, v0
	s_add_i32 m0, s13, 0x10000
	v_lshl_add_u32 v134, v3, 12, v0
	global_load_lds_dwordx4 v132, s[22:23]
	s_add_i32 m0, s13, 0x12000
	s_add_u32 s6, s22, 0x80000
	global_load_lds_dwordx4 v128, s[22:23]
	s_addc_u32 s7, s23, 0
	s_add_i32 m0, s13, 0x14000
	v_mov_b32_e32 v133, 0
	global_load_lds_dwordx4 v132, s[6:7]
	s_add_i32 m0, s13, 0x16000
	s_add_u32 s24, s28, s0
	s_addc_u32 s25, s29, s1
	s_add_i32 s37, s13, 0x2000
	global_load_lds_dwordx4 v128, s[6:7]
	s_mov_b32 m0, s13
	s_add_u32 s0, s24, 0x80000
	global_load_lds_dwordx4 v134, s[24:25]
	s_mov_b32 m0, s37
	s_addc_u32 s1, s25, 0
	s_add_i32 s38, s13, 0x4000
	global_load_lds_dwordx4 v130, s[24:25]
	s_mov_b32 m0, s38
	s_add_i32 s39, s13, 0x6000
	global_load_lds_dwordx4 v134, s[0:1]
	s_mov_b32 m0, s39
	v_mov_b32_e32 v129, v133
	global_load_lds_dwordx4 v130, s[0:1]
	v_mov_b32_e32 v135, v133
	v_mov_b32_e32 v131, v133
	s_cmp_eq_u32 s14, 1
	s_mov_b32 s40, 0
	v_lshl_add_u64 v[6:7], s[22:23], 0, v[132:133]
	v_lshl_add_u64 v[4:5], s[22:23], 0, v[128:129]
	v_lshl_add_u64 v[0:1], s[24:25], 0, v[134:135]
	s_cselect_b64 s[0:1], -1, 0
	s_cmp_lg_u32 s14, 1
	v_lshl_add_u64 v[2:3], s[24:25], 0, v[130:131]
	s_cbranch_scc1 .LBB0_140
	s_barrier

; #define PG8_STAGE(bufoff, gbase, voff) do { _Pragma("unroll") for (int _i = 0; _i < 2; ++_i) \
;         __builtin_amdgcn_global_load_lds((const unsigned*)((const char*)(gbase) + (voff)[_i]), (PG8_LAS unsigned*)(lds + (bufoff) + ldsw + _i * 8192), 16, 0, 0); } while (0)
; #define PG8_LDA(dst, b, h) do { _Pragma("unroll") for (int m = 0; m < 4; ++m) _Pragma("unroll") for (int k = 0; k < 2; ++k) dst[m][k] = *(const PG8_LAS bf16x8*)(lds + PG8_SA(b, h) + aoff + m * 2048 + k * 1024); } while (0)
; #define PG8_LDB(dst, b, h) do { _Pragma("unroll") for (int n = 0; n < 2; ++n) _Pragma("unroll") for (int k = 0; k < 2; ++k) dst[n][k] = *(const PG8_LAS bf16x8*)(lds + PG8_SB(b, h) + boff + n * 2048 + k * 1024); } while (0)
; #define PG8_MMA(ai, bj, At, Bt) do { __builtin_amdgcn_s_setprio(1); _Pragma("unroll") for (int m = 0; m < 4; ++m) _Pragma("unroll") for (int n = 0; n < 2; ++n) _Pragma("unroll") for (int k = 0; k < 2; ++k) \
;         acc[ai][bj][m][n] = __builtin_amdgcn_mfma_f32_16x16x32_f16(Bt[n][k], At[m][k], acc[ai][bj][m][n], 0, 0, 0); __builtin_amdgcn_s_setprio(0); } while (0)
; #define PG8_WAIT_V(n) asm volatile("s_waitcnt vmcnt(" #n ")" ::: "memory")
; #define PG8_WAIT_L(n) asm volatile("s_waitcnt lgkmcnt(" #n ")" ::: "memory")
; #define PG8_BAR __builtin_amdgcn_s_barrier()
; #define PG8_SCHED __builtin_amdgcn_sched_barrier(0)
; template <class Epi, class Sched, bool ALIGN_EPI = false, bool SP2 = false>
; __device__ __forceinline__ void gemm_phase(PG8_LAS unsigned char* lds, const Gemm g, const Sched& S, const Epi& E) {
;     ...
;             PG8_LDB(B0, 0, 0); PG8_LDB(B1, 0, 1); PG8_SCHED; PG8_LDA(At, 0, 0); PG8_STAGE(PG8_SA(1, 1), a1 + hstep, voffA);
;             PG8_WAIT_V(8); PG8_WAIT_L(0); PG8_BAR; PG8_MMA(0, 0, At, B0); PG8_MMA(0, 1, At, B1); PG8_BAR; PG8_SCHED;
;             PG8_LDA(At, 0, 1); PG8_STAGE(PG8_SB(0, 0), b2, voffB); PG8_STAGE(PG8_SB(0, 1), b2 + hstep, voffB); PG8_STAGE(PG8_SA(0, 0), a2, voffA);
;             PG8_WAIT_V(8); PG8_WAIT_L(0); PG8_BAR; PG8_MMA(1, 0, At, B0); PG8_MMA(1, 1, At, B1); PG8_BAR; PG8_SCHED;
.LBB0_146:
	ds_read_b128 v[150:153], v147
	ds_read_b128 v[154:157], v147 offset:1024
	ds_read_b128 v[158:161], v147 offset:2048
	ds_read_b128 v[162:165], v147 offset:3072
	ds_read_b128 v[166:169], v148
	ds_read_b128 v[170:173], v148 offset:1024
	ds_read_b128 v[174:177], v148 offset:2048
	ds_read_b128 v[178:181], v148 offset:3072
	s_add_u32 s24, s22, 0xfff80080
	s_addc_u32 s25, s23, -1
	s_cmp_eq_u32 s62, 28
	s_cselect_b32 s27, s17, s25
	s_cselect_b32 s26, s54, s24
	s_cselect_b32 s25, s15, s61
	s_cselect_b32 s24, s55, s60
	s_add_i32 m0, s13, 0xc000
	ds_read_b128 v[182:185], v149
	ds_read_b128 v[186:189], v149 offset:1024
	ds_read_b128 v[190:193], v149 offset:2048
	ds_read_b128 v[194:197], v149 offset:3072
	ds_read_b128 v[198:201], v149 offset:4096
	ds_read_b128 v[206:209], v149 offset:5120
	ds_read_b128 v[210:213], v149 offset:6144
	ds_read_b128 v[214:217], v149 offset:7168
	global_load_lds_dwordx4 v138, s[22:23]
	s_add_i32 m0, s13, 0xe000
	s_nop 0
	global_load_lds_dwordx4 v136, s[22:23]
	s_waitcnt vmcnt(8)
	s_waitcnt lgkmcnt(0)
	s_barrier
	s_waitcnt lgkmcnt(0)
	v_mfma_f32_16x16x32_f16 v[120:123], v[158:161], v[182:185], v[120:123]
	v_mfma_f32_16x16x32_f16 v[124:127], v[150:153], v[182:185], v[124:127]
	v_mfma_f32_16x16x32_f16 v[112:115], v[158:161], v[190:193], v[112:115]
	v_mfma_f32_16x16x32_f16 v[116:119], v[150:153], v[190:193], v[116:119]
	v_mfma_f32_16x16x32_f16 v[96:99], v[158:161], v[198:201], v[96:99]
	v_mfma_f32_16x16x32_f16 v[100:103], v[150:153], v[198:201], v[100:103]
	v_mfma_f32_16x16x32_f16 v[80:83], v[158:161], v[210:213], v[80:83]
	v_mfma_f32_16x16x32_f16 v[84:87], v[150:153], v[210:213], v[84:87]
	v_mfma_f32_16x16x32_f16 v[120:123], v[162:165], v[186:189], v[120:123]
	v_mfma_f32_16x16x32_f16 v[124:127], v[154:157], v[186:189], v[124:127]
	v_mfma_f32_16x16x32_f16 v[112:115], v[162:165], v[194:197], v[112:115]
	v_mfma_f32_16x16x32_f16 v[116:119], v[154:157], v[194:197], v[116:119]
	v_mfma_f32_16x16x32_f16 v[96:99], v[162:165], v[206:209], v[96:99]
	v_mfma_f32_16x16x32_f16 v[100:103], v[154:157], v[206:209], v[100:103]
	v_mfma_f32_16x16x32_f16 v[80:83], v[162:165], v[214:217], v[80:83]
	v_mfma_f32_16x16x32_f16 v[84:87], v[154:157], v[214:217], v[84:87]
	v_mfma_f32_16x16x32_f16 v[104:107], v[174:177], v[182:185], v[104:107]
	v_mfma_f32_16x16x32_f16 v[108:111], v[166:169], v[182:185], v[108:111]
	v_mfma_f32_16x16x32_f16 v[88:91], v[174:177], v[190:193], v[88:91]
	v_mfma_f32_16x16x32_f16 v[92:95], v[166:169], v[190:193], v[92:95]
	v_mfma_f32_16x16x32_f16 v[72:75], v[174:177], v[198:201], v[72:75]
	v_mfma_f32_16x16x32_f16 v[76:79], v[166:169], v[198:201], v[76:79]
	v_mfma_f32_16x16x32_f16 v[64:67], v[174:177], v[210:213], v[64:67]
	v_mfma_f32_16x16x32_f16 v[68:71], v[166:169], v[210:213], v[68:71]
	v_mfma_f32_16x16x32_f16 v[104:107], v[178:181], v[186:189], v[104:107]
	v_mfma_f32_16x16x32_f16 v[108:111], v[170:173], v[186:189], v[108:111]
	v_mfma_f32_16x16x32_f16 v[88:91], v[178:181], v[194:197], v[88:91]
	v_mfma_f32_16x16x32_f16 v[92:95], v[170:173], v[194:197], v[92:95]
	v_mfma_f32_16x16x32_f16 v[72:75], v[178:181], v[206:209], v[72:75]
	v_mfma_f32_16x16x32_f16 v[76:79], v[170:173], v[206:209], v[76:79]
	v_mfma_f32_16x16x32_f16 v[64:67], v[178:181], v[214:217], v[64:67]
	v_mfma_f32_16x16x32_f16 v[68:71], v[170:173], v[214:217], v[68:71]
	s_barrier
	s_add_i32 s63, s44, s34
	s_add_u32 s98, s24, s8
	s_addc_u32 s99, s25, s9
	s_mov_b32 m0, s63
	ds_read_b128 v[182:185], v149 offset:16384
	ds_read_b128 v[186:189], v149 offset:17408
	ds_read_b128 v[190:193], v149 offset:18432
	ds_read_b128 v[194:197], v149 offset:19456
	ds_read_b128 v[198:201], v149 offset:20480
	ds_read_b128 v[206:209], v149 offset:21504
	ds_read_b128 v[210:213], v149 offset:22528
	ds_read_b128 v[214:217], v149 offset:23552
	global_load_lds_dwordx4 v132, s[24:25]
	s_add_i32 m0, s63, 0x2000
	s_add_u32 s66, s24, 0x80000
	s_addc_u32 s67, s25, 0
	s_add_i32 s63, s45, s34
	global_load_lds_dwordx4 v128, s[24:25]
	s_mov_b32 m0, s63
	s_nop 0
	global_load_lds_dwordx4 v132, s[66:67]
	s_add_i32 m0, s63, 0x2000
	s_nop 0
	global_load_lds_dwordx4 v128, s[66:67]
	s_add_u32 s100, s26, s8
	s_addc_u32 s101, s27, s9
	s_mov_b32 m0, s13
	s_nop 0
	global_load_lds_dwordx4 v134, s[26:27]
	s_mov_b32 m0, s37
	s_nop 0
	global_load_lds_dwordx4 v130, s[26:27]
	s_waitcnt vmcnt(8)
	s_waitcnt lgkmcnt(0)
	s_barrier
	s_waitcnt lgkmcnt(0)
	v_mfma_f32_16x16x32_f16 v[56:59], v[158:161], v[182:185], v[56:59]
	v_mfma_f32_16x16x32_f16 v[60:63], v[150:153], v[182:185], v[60:63]
	v_mfma_f32_16x16x32_f16 v[48:51], v[158:161], v[190:193], v[48:51]
	v_mfma_f32_16x16x32_f16 v[52:55], v[150:153], v[190:193], v[52:55]
	v_mfma_f32_16x16x32_f16 v[32:35], v[158:161], v[198:201], v[32:35]
	v_mfma_f32_16x16x32_f16 v[36:39], v[150:153], v[198:201], v[36:39]
	v_mfma_f32_16x16x32_f16 v[16:19], v[158:161], v[210:213], v[16:19]
	v_mfma_f32_16x16x32_f16 v[20:23], v[150:153], v[210:213], v[20:23]
	v_mfma_f32_16x16x32_f16 v[56:59], v[162:165], v[186:189], v[56:59]
	v_mfma_f32_16x16x32_f16 v[60:63], v[154:157], v[186:189], v[60:63]
	v_mfma_f32_16x16x32_f16 v[48:51], v[162:165], v[194:197], v[48:51]
	v_mfma_f32_16x16x32_f16 v[52:55], v[154:157], v[194:197], v[52:55]
	v_mfma_f32_16x16x32_f16 v[32:35], v[162:165], v[206:209], v[32:35]
	v_mfma_f32_16x16x32_f16 v[36:39], v[154:157], v[206:209], v[36:39]
	v_mfma_f32_16x16x32_f16 v[16:19], v[162:165], v[214:217], v[16:19]
	v_mfma_f32_16x16x32_f16 v[20:23], v[154:157], v[214:217], v[20:23]
	v_mfma_f32_16x16x32_f16 v[40:43], v[174:177], v[182:185], v[40:43]
	v_mfma_f32_16x16x32_f16 v[44:47], v[166:169], v[182:185], v[44:47]
	v_mfma_f32_16x16x32_f16 v[24:27], v[174:177], v[190:193], v[24:27]
	v_mfma_f32_16x16x32_f16 v[28:31], v[166:169], v[190:193], v[28:31]
	v_mfma_f32_16x16x32_f16 v[8:11], v[174:177], v[198:201], v[8:11]
	v_mfma_f32_16x16x32_f16 v[12:15], v[166:169], v[198:201], v[12:15]
	v_mfma_f32_16x16x32_f16 v[0:3], v[174:177], v[210:213], v[0:3]
	v_mfma_f32_16x16x32_f16 v[4:7], v[166:169], v[210:213], v[4:7]
	v_mfma_f32_16x16x32_f16 v[40:43], v[178:181], v[186:189], v[40:43]
	v_mfma_f32_16x16x32_f16 v[44:47], v[170:173], v[186:189], v[44:47]
	v_mfma_f32_16x16x32_f16 v[24:27], v[178:181], v[194:197], v[24:27]
	v_mfma_f32_16x16x32_f16 v[28:31], v[170:173], v[194:197], v[28:31]
	v_mfma_f32_16x16x32_f16 v[8:11], v[178:181], v[206:209], v[8:11]
	v_mfma_f32_16x16x32_f16 v[12:15], v[170:173], v[206:209], v[12:15]
	v_mfma_f32_16x16x32_f16 v[0:3], v[178:181], v[214:217], v[0:3]
	v_mfma_f32_16x16x32_f16 v[4:7], v[170:173], v[214:217], v[4:7]
	s_barrier
; #define PG8_STAGE(bufoff, gbase, voff) do { _Pragma("unroll") for (int _i = 0; _i < 2; ++_i) \
;         __builtin_amdgcn_global_load_lds((const unsigned*)((const char*)(gbase) + (voff)[_i]), (PG8_LAS unsigned*)(lds + (bufoff) + ldsw + _i * 8192), 16, 0, 0); } while (0)
; #define PG8_LDA(dst, b, h) do { _Pragma("unroll") for (int m = 0; m < 4; ++m) _Pragma("unroll") for (int k = 0; k < 2; ++k) dst[m][k] = *(const PG8_LAS bf16x8*)(lds + PG8_SA(b, h) + aoff + m * 2048 + k * 1024); } while (0)
; #define PG8_LDB(dst, b, h) do { _Pragma("unroll") for (int n = 0; n < 2; ++n) _Pragma("unroll") for (int k = 0; k < 2; ++k) dst[n][k] = *(const PG8_LAS bf16x8*)(lds + PG8_SB(b, h) + boff + n * 2048 + k * 1024); } while (0)
; #define PG8_MMA(ai, bj, At, Bt) do { __builtin_amdgcn_s_setprio(1); _Pragma("unroll") for (int m = 0; m < 4; ++m) _Pragma("unroll") for (int n = 0; n < 2; ++n) _Pragma("unroll") for (int k = 0; k < 2; ++k) \
;         acc[ai][bj][m][n] = __builtin_amdgcn_mfma_f32_16x16x32_f16(Bt[n][k], At[m][k], acc[ai][bj][m][n], 0, 0, 0); __builtin_amdgcn_s_setprio(0); } while (0)
; #define PG8_WAIT_V(n) asm volatile("s_waitcnt vmcnt(" #n ")" ::: "memory")
; #define PG8_WAIT_L(n) asm volatile("s_waitcnt lgkmcnt(" #n ")" ::: "memory")
; #define PG8_BAR __builtin_amdgcn_s_barrier()
; #define PG8_SCHED __builtin_amdgcn_sched_barrier(0)
; template <class Epi, class Sched, bool ALIGN_EPI = false, bool SP2 = false>
; __device__ __forceinline__ void gemm_phase(PG8_LAS unsigned char* lds, const Gemm g, const Sched& S, const Epi& E) {
;     ...
;         for (int t = 0; t < nt; t += 2) {
;     ...
;             PG8_LDB(B0, 1, 0); PG8_LDB(B1, 1, 1); PG8_SCHED; PG8_LDA(At, 1, 0); PG8_STAGE(PG8_SA(0, 1), a2 + hstep, voffA);
;             PG8_WAIT_V(8); PG8_WAIT_L(0); PG8_BAR; PG8_MMA(0, 0, At, B0); PG8_MMA(0, 1, At, B1); PG8_BAR; PG8_SCHED;
;             PG8_LDA(At, 1, 1); PG8_STAGE(PG8_SB(1, 0), b3, voffB); PG8_STAGE(PG8_SB(1, 1), b3 + hstep, voffB); PG8_STAGE(PG8_SA(1, 0), a3, voffA);
;             PG8_WAIT_V(8); PG8_WAIT_L(0); PG8_BAR; PG8_MMA(1, 0, At, B0); PG8_MMA(1, 1, At, B1); PG8_BAR; PG8_SCHED;
	s_add_i32 s63, 0, 0x18000
	s_add_i32 s66, 0, 0x1c000
	v_add_u32_e32 v162, s63, v145
	v_add_u32_e32 v178, s66, v145
	ds_read_b128 v[150:153], v162
	ds_read_b128 v[154:157], v162 offset:1024
	ds_read_b128 v[158:161], v162 offset:2048
	ds_read_b128 v[162:165], v162 offset:3072
	ds_read_b128 v[166:169], v178
	ds_read_b128 v[170:173], v178 offset:1024
	ds_read_b128 v[174:177], v178 offset:2048
	ds_read_b128 v[178:181], v178 offset:3072
	s_add_u32 s26, s26, 0x80000
	s_addc_u32 s27, s27, 0
	s_mov_b32 m0, s38
	ds_read_b128 v[182:185], v149 offset:32768
	ds_read_b128 v[186:189], v149 offset:33792
	ds_read_b128 v[190:193], v149 offset:34816
	ds_read_b128 v[194:197], v149 offset:35840
	ds_read_b128 v[198:201], v149 offset:36864
	ds_read_b128 v[206:209], v149 offset:37888
	ds_read_b128 v[210:213], v149 offset:38912
	ds_read_b128 v[214:217], v149 offset:39936
	global_load_lds_dwordx4 v134, s[26:27]
	s_mov_b32 m0, s39
	s_nop 0
	global_load_lds_dwordx4 v130, s[26:27]
	s_waitcnt vmcnt(8)
	s_waitcnt lgkmcnt(0)
	s_barrier
	s_waitcnt lgkmcnt(0)
	v_mfma_f32_16x16x32_f16 v[120:123], v[158:161], v[182:185], v[120:123]
	v_mfma_f32_16x16x32_f16 v[124:127], v[150:153], v[182:185], v[124:127]
	v_mfma_f32_16x16x32_f16 v[112:115], v[158:161], v[190:193], v[112:115]
	v_mfma_f32_16x16x32_f16 v[116:119], v[150:153], v[190:193], v[116:119]
	v_mfma_f32_16x16x32_f16 v[96:99], v[158:161], v[198:201], v[96:99]
	v_mfma_f32_16x16x32_f16 v[100:103], v[150:153], v[198:201], v[100:103]
	v_mfma_f32_16x16x32_f16 v[80:83], v[158:161], v[210:213], v[80:83]
	v_mfma_f32_16x16x32_f16 v[84:87], v[150:153], v[210:213], v[84:87]
	v_mfma_f32_16x16x32_f16 v[120:123], v[162:165], v[186:189], v[120:123]
	v_mfma_f32_16x16x32_f16 v[124:127], v[154:157], v[186:189], v[124:127]
	v_mfma_f32_16x16x32_f16 v[112:115], v[162:165], v[194:197], v[112:115]
	v_mfma_f32_16x16x32_f16 v[116:119], v[154:157], v[194:197], v[116:119]
	v_mfma_f32_16x16x32_f16 v[96:99], v[162:165], v[206:209], v[96:99]
	v_mfma_f32_16x16x32_f16 v[100:103], v[154:157], v[206:209], v[100:103]
	v_mfma_f32_16x16x32_f16 v[80:83], v[162:165], v[214:217], v[80:83]
	v_mfma_f32_16x16x32_f16 v[84:87], v[154:157], v[214:217], v[84:87]
	v_mfma_f32_16x16x32_f16 v[104:107], v[174:177], v[182:185], v[104:107]
	v_mfma_f32_16x16x32_f16 v[108:111], v[166:169], v[182:185], v[108:111]
	v_mfma_f32_16x16x32_f16 v[88:91], v[174:177], v[190:193], v[88:91]
	v_mfma_f32_16x16x32_f16 v[92:95], v[166:169], v[190:193], v[92:95]
	v_mfma_f32_16x16x32_f16 v[72:75], v[174:177], v[198:201], v[72:75]
	v_mfma_f32_16x16x32_f16 v[76:79], v[166:169], v[198:201], v[76:79]
	v_mfma_f32_16x16x32_f16 v[64:67], v[174:177], v[210:213], v[64:67]
	v_mfma_f32_16x16x32_f16 v[68:71], v[166:169], v[210:213], v[68:71]
	v_mfma_f32_16x16x32_f16 v[104:107], v[178:181], v[186:189], v[104:107]
	v_mfma_f32_16x16x32_f16 v[108:111], v[170:173], v[186:189], v[108:111]
	v_mfma_f32_16x16x32_f16 v[88:91], v[178:181], v[194:197], v[88:91]
	v_mfma_f32_16x16x32_f16 v[92:95], v[170:173], v[194:197], v[92:95]
	v_mfma_f32_16x16x32_f16 v[72:75], v[178:181], v[206:209], v[72:75]
	v_mfma_f32_16x16x32_f16 v[76:79], v[170:173], v[206:209], v[76:79]
	v_mfma_f32_16x16x32_f16 v[64:67], v[178:181], v[214:217], v[64:67]
	v_mfma_f32_16x16x32_f16 v[68:71], v[170:173], v[214:217], v[68:71]
	s_barrier
	s_add_i32 s26, s63, s34
	s_mov_b32 m0, s26
	ds_read_b128 v[182:185], v149 offset:49152
	ds_read_b128 v[186:189], v149 offset:50176
	ds_read_b128 v[190:193], v149 offset:51200
	ds_read_b128 v[194:197], v149 offset:52224
	ds_read_b128 v[198:201], v149 offset:53248
	ds_read_b128 v[206:209], v149 offset:54272
	ds_read_b128 v[210:213], v149 offset:55296
	ds_read_b128 v[214:217], v149 offset:56320
	global_load_lds_dwordx4 v132, s[98:99]
	s_add_i32 m0, s26, 0x2000
	s_add_u32 s24, s24, 0x80080
	s_addc_u32 s25, s25, 0
	s_add_i32 s26, s66, s34
	global_load_lds_dwordx4 v128, s[98:99]
	s_mov_b32 m0, s26
	s_nop 0
	global_load_lds_dwordx4 v132, s[24:25]
	s_add_i32 m0, s26, 0x2000
	s_nop 0
	global_load_lds_dwordx4 v128, s[24:25]
	s_mov_b32 m0, s41
	s_nop 0
	global_load_lds_dwordx4 v134, s[100:101]
	s_mov_b32 m0, s42
	s_nop 0
	global_load_lds_dwordx4 v130, s[100:101]
	s_waitcnt vmcnt(8)
	s_waitcnt lgkmcnt(0)
	s_barrier
	s_waitcnt lgkmcnt(0)
	v_mfma_f32_16x16x32_f16 v[56:59], v[158:161], v[182:185], v[56:59]
	v_mfma_f32_16x16x32_f16 v[60:63], v[150:153], v[182:185], v[60:63]
	v_mfma_f32_16x16x32_f16 v[48:51], v[158:161], v[190:193], v[48:51]
	v_mfma_f32_16x16x32_f16 v[52:55], v[150:153], v[190:193], v[52:55]
	v_mfma_f32_16x16x32_f16 v[32:35], v[158:161], v[198:201], v[32:35]
	v_mfma_f32_16x16x32_f16 v[36:39], v[150:153], v[198:201], v[36:39]
	v_mfma_f32_16x16x32_f16 v[16:19], v[158:161], v[210:213], v[16:19]
	v_mfma_f32_16x16x32_f16 v[20:23], v[150:153], v[210:213], v[20:23]
	v_mfma_f32_16x16x32_f16 v[56:59], v[162:165], v[186:189], v[56:59]
	v_mfma_f32_16x16x32_f16 v[60:63], v[154:157], v[186:189], v[60:63]
	v_mfma_f32_16x16x32_f16 v[48:51], v[162:165], v[194:197], v[48:51]
	v_mfma_f32_16x16x32_f16 v[52:55], v[154:157], v[194:197], v[52:55]
	v_mfma_f32_16x16x32_f16 v[32:35], v[162:165], v[206:209], v[32:35]
	v_mfma_f32_16x16x32_f16 v[36:39], v[154:157], v[206:209], v[36:39]
	v_mfma_f32_16x16x32_f16 v[16:19], v[162:165], v[214:217], v[16:19]
	v_mfma_f32_16x16x32_f16 v[20:23], v[154:157], v[214:217], v[20:23]
	v_mfma_f32_16x16x32_f16 v[40:43], v[174:177], v[182:185], v[40:43]
	v_mfma_f32_16x16x32_f16 v[44:47], v[166:169], v[182:185], v[44:47]
	v_mfma_f32_16x16x32_f16 v[24:27], v[174:177], v[190:193], v[24:27]
	v_mfma_f32_16x16x32_f16 v[28:31], v[166:169], v[190:193], v[28:31]
	v_mfma_f32_16x16x32_f16 v[8:11], v[174:177], v[198:201], v[8:11]
	v_mfma_f32_16x16x32_f16 v[12:15], v[166:169], v[198:201], v[12:15]
	v_mfma_f32_16x16x32_f16 v[0:3], v[174:177], v[210:213], v[0:3]
	v_mfma_f32_16x16x32_f16 v[4:7], v[166:169], v[210:213], v[4:7]
	v_mfma_f32_16x16x32_f16 v[40:43], v[178:181], v[186:189], v[40:43]
	v_mfma_f32_16x16x32_f16 v[44:47], v[170:173], v[186:189], v[44:47]
	v_mfma_f32_16x16x32_f16 v[24:27], v[178:181], v[194:197], v[24:27]
	v_mfma_f32_16x16x32_f16 v[28:31], v[170:173], v[194:197], v[28:31]
	v_mfma_f32_16x16x32_f16 v[8:11], v[178:181], v[206:209], v[8:11]
	v_mfma_f32_16x16x32_f16 v[12:15], v[170:173], v[206:209], v[12:15]
	v_mfma_f32_16x16x32_f16 v[0:3], v[178:181], v[214:217], v[0:3]
	v_mfma_f32_16x16x32_f16 v[4:7], v[170:173], v[214:217], v[4:7]
	s_barrier
	s_add_i32 s62, s62, 2
	s_add_u32 s60, s60, 0x100
	s_addc_u32 s61, s61, 0
	s_add_u32 s22, s22, 0x100
	s_addc_u32 s23, s23, 0
	s_cmp_gt_u32 s62, 29
	s_cbranch_scc0 .LBB0_146
	s_and_b64 vcc, exec, s[10:11]
	s_cbranch_vccz .LBB0_149
	s_barrier

; #define LAS __attribute__((address_space(3)))
; __device__ __forceinline__ void ab_phase(const h16* H, const float* sinks, h16* Y, h16* PO16, float* LSE, LAS unsigned char* lds, int G) {
;     ...
;     int tid = threadIdx.x; asm volatile("" : "+v"(tid));
;     const int lane = tid & 63, w = __builtin_amdgcn_readfirstlane(tid >> 6), r32 = lane & 31, hi = lane >> 5;
;     const int isV = tid >> 8, lrow = (tid & 255) >> 3, lcc = tid & 7;
;     const int q4 = (lane & 15) >> 2, p4 = lane & 3, dblk = (lane >> 4) & 1;
;     const int vrd_off = (4 * hi + q4) * VP + dblk * 32 + p4 * 8;
;     LAS unsigned char* wdst = lds + (isV ? 0 : 32 * VP) + lrow * VP + lcc * 16;
;     u32x4 tr[12]; h8 qn[4];
;     ...
;     int U = ((gridDim.x % 8 == 0) ? (int)((blockIdx.x % 8) * (gridDim.x / 8) + blockIdx.x / 8) : (int)blockIdx.x);
;     if (U < NU) AB_ISSUE(U);
.LBB0_205:
	s_or_b64 exec, exec, s[0:1]
	s_and_b32 s0, s84, 7
	s_cmp_eq_u32 s0, 0
	s_mov_b64 s[8:9], s[78:79]
	s_mov_b64 s[44:45], s[76:77]
	s_waitcnt lgkmcnt(0)
	v_mov_b32_e32 v0, v204
	s_setprio 0
	v_mov_b32_e32 v5, v204
	s_cselect_b64 s[4:5], -1, 0
	s_barrier
	v_writelane_b32 v234, s4, 6
	v_readfirstlane_b32 s13, v5
	s_cmp_lg_u32 s0, 0
	s_mov_b32 s12, s33
	v_writelane_b32 v234, s5, 7
	s_cbranch_scc1 .LBB0_207
	s_and_b32 s0, s2, 7
	s_lshr_b32 s1, s84, 3
	s_mul_i32 s0, s1, s0
	s_lshr_b32 s1, s2, 3
	s_add_i32 s12, s0, s1

; #define WS_SETUP unsigned char* ws = P.ws; asm volatile("" : "+s"(ws)); float* R = P.out; asm volatile("" : "+s"(R)); (void)R;
; __global__ void __launch_bounds__(NWAVES * 64, 2) mega_fwd(Params P) {
;     ...
;     { WS_SETUP TID_SETUP
;             for (long i = gt; i < (long)MTOK * 128; i += NGT) { const size_t tok = (size_t)(i >> 7); const int h = (int)((i >> 4) & 7), dg = (int)(i & 15);
;                 const float l0 = LSE[tok * 8 + h], l1 = LSE[((size_t)MTOK + tok) * 8 + h], l2 = LSE[((size_t)2 * MTOK + tok) * 8 + h];
;                 const float mx = fmaxf(l0, fmaxf(l1, l2)); const float w0 = __expf(l0 - mx), w1 = __expf(l1 - mx), w2 = __expf(l2 - mx); const float iw = 1.f / (w0 + w1 + w2);
;                 const size_t po = tok * 512 + h * 64 + dg * 4;
.LBB0_400:
	s_or_b64 exec, exec, s[0:1]
	s_mov_b64 s[0:1], s[78:79]
	s_mov_b64 s[4:5], s[76:77]
	v_mov_b32_e32 v8, v204
	s_setprio 0
	v_readfirstlane_b32 s98, v204
	s_lshr_b32 s98, s98, 8
	s_cmp_lg_u32 s98, 0
	s_cbranch_scc0 .Lsprio_skip_1
	s_setprio 1
.Lsprio_skip_1:
	s_waitcnt lgkmcnt(0)
	s_barrier
	s_mov_b64 s[6:7], 0x200000
	v_ashrrev_i32_e32 v9, 31, v8
	v_lshl_add_u64 v[0:1], s[82:83], 0, v[8:9]
	v_readfirstlane_b32 s20, v8
	v_cmp_gt_i64_e32 vcc, s[6:7], v[0:1]
	s_and_saveexec_b64 s[6:7], vcc
	s_cbranch_execz .LBB0_403
	s_add_u32 s8, s4, 0x6000000
	s_addc_u32 s9, s5, 0
	s_add_u32 s10, s4, 0x1000000
	s_addc_u32 s11, s5, 0
	s_add_u32 s12, s4, 0x2000000
	s_addc_u32 s13, s5, 0
	s_lshl_b64 s[14:15], s[2:3], 11
	v_lshl_add_u64 v[2:3], v[8:9], 2, s[14:15]
	s_lshl_b64 s[14:15], s[84:85], 11
	s_mov_b64 s[16:17], 0
	v_mov_b32_e32 v5, 0
	s_movk_i32 s3, 0xc00
	v_mov_b64_e32 v[6:7], s[0:1]
	s_mov_b64 s[18:19], 0x1fffff

; #define WS_SETUP unsigned char* ws = P.ws; asm volatile("" : "+s"(ws)); float* R = P.out; asm volatile("" : "+s"(R)); (void)R;
;     __host__ __device__ bool next(int i, Unit& u) const {
;         const long L = (long)i * G + c; if (L >= nwg) return false;
;         int wgid = (int)L; { const int q = nwg / NXCD, r = nwg % NXCD, xcd = wgid % NXCD, off = wgid / NXCD; wgid = (xcd < r ? xcd * (q + 1) : r * (q + 1) + (xcd - r) * q) + off; }
;         const int nig = wgm * nN, gid = wgid / nig, fm = gid * wgm, gsz = (nM - fm) < wgm ? (nM - fm) : wgm;
;         u.pm = fm + ((wgid % nig) % gsz); u.pn = (wgid % nig) / gsz; return true;
; __global__ void __launch_bounds__(NWAVES * 64, 2) mega_fwd(Params P) {
;     ...
;     { WS_SETUP pg8::Gemm g{Y, (const h16*)(ws + WS_W_EOUT), MTOK, DM, EVEN_OUT}; pg8::EpiAny<2, 0> E{}; E.xbase = XB  ; E.ldc = DM; E.alpha = ALPHA; E.xb = XB; E.st_out = STATS;
;       pg8::StaticOrder S; S.init(MTOK, DM, G, (int)blockIdx.x, WGM_N2048);
;       pg8::gemm_phase<pg8::EpiAny<2, 0>, pg8::StaticOrder, true, true>(lds, g, S, E); }
.Lsprio_skip_2:
	s_cmpk_lt_i32 s2, 0x200
	s_waitcnt lgkmcnt(0)
	s_barrier
	s_cselect_b64 s[6:7], -1, 0
	s_cmpk_gt_i32 s2, 0x1ff
	v_readfirstlane_b32 s8, v8
	s_cbranch_scc1 .LBB0_468
	s_ashr_i32 s3, s2, 31
	s_lshr_b32 s3, s3, 29
	s_add_i32 s3, s2, s3
	s_and_b32 s4, s3, -8
	s_sub_i32 s9, s2, s4
	s_cmp_gt_i32 s9, -1
	s_cbranch_scc0 .LBB0_465
	s_lshl_b32 s10, s9, 6
	s_cbranch_execz .LBB0_466
	s_branch .LBB0_467

; #define PG8_STAGE(bufoff, gbase, voff) do { _Pragma("unroll") for (int _i = 0; _i < 2; ++_i) \
;         __builtin_amdgcn_global_load_lds((const unsigned*)((const char*)(gbase) + (voff)[_i]), (PG8_LAS unsigned*)(lds + (bufoff) + ldsw + _i * 8192), 16, 0, 0); } while (0)
; #define PG8_LDA(dst, b, h) do { _Pragma("unroll") for (int m = 0; m < 4; ++m) _Pragma("unroll") for (int k = 0; k < 2; ++k) dst[m][k] = *(const PG8_LAS bf16x8*)(lds + PG8_SA(b, h) + aoff + m * 2048 + k * 1024); } while (0)
; #define PG8_LDB(dst, b, h) do { _Pragma("unroll") for (int n = 0; n < 2; ++n) _Pragma("unroll") for (int k = 0; k < 2; ++k) dst[n][k] = *(const PG8_LAS bf16x8*)(lds + PG8_SB(b, h) + boff + n * 2048 + k * 1024); } while (0)
; #define PG8_MMA(ai, bj, At, Bt) do { __builtin_amdgcn_s_setprio(1); _Pragma("unroll") for (int m = 0; m < 4; ++m) _Pragma("unroll") for (int n = 0; n < 2; ++n) _Pragma("unroll") for (int k = 0; k < 2; ++k) \
;         acc[ai][bj][m][n] = __builtin_amdgcn_mfma_f32_16x16x32_f16(Bt[n][k], At[m][k], acc[ai][bj][m][n], 0, 0, 0); __builtin_amdgcn_s_setprio(0); } while (0)
; #define PG8_WAIT_V(n) asm volatile("s_waitcnt vmcnt(" #n ")" ::: "memory")
; #define PG8_WAIT_L(n) asm volatile("s_waitcnt lgkmcnt(" #n ")" ::: "memory")
; #define PG8_BAR __builtin_amdgcn_s_barrier()
; #define PG8_SCHED __builtin_amdgcn_sched_barrier(0)
; template <class Epi, class Sched, bool ALIGN_EPI = false, bool SP2 = false>
; __device__ __forceinline__ void gemm_phase(PG8_LAS unsigned char* lds, const Gemm g, const Sched& S, const Epi& E) {
;     ...
;             PG8_LDB(B0, 0, 0); PG8_LDB(B1, 0, 1); PG8_SCHED; PG8_LDA(At, 0, 0); PG8_STAGE(PG8_SA(1, 1), a1 + hstep, voffA);
;             PG8_WAIT_V(8); PG8_WAIT_L(0); PG8_BAR; PG8_MMA(0, 0, At, B0); PG8_MMA(0, 1, At, B1); PG8_BAR; PG8_SCHED;
;             PG8_LDA(At, 0, 1); PG8_STAGE(PG8_SB(0, 0), b2, voffB); PG8_STAGE(PG8_SB(0, 1), b2 + hstep, voffB); PG8_STAGE(PG8_SA(0, 0), a2, voffA);
;             PG8_WAIT_V(8); PG8_WAIT_L(0); PG8_BAR; PG8_MMA(1, 0, At, B0); PG8_MMA(1, 1, At, B1); PG8_BAR; PG8_SCHED;
.LBB0_485:
	ds_read_b128 v[128:131], v163
	ds_read_b128 v[132:135], v163 offset:1024
	ds_read_b128 v[152:155], v163 offset:2048
	ds_read_b128 v[156:159], v163 offset:3072
	ds_read_b128 v[166:169], v164
	ds_read_b128 v[170:173], v164 offset:1024
	ds_read_b128 v[174:177], v164 offset:2048
	ds_read_b128 v[178:181], v164 offset:3072
	s_add_u32 s26, s24, 0x100
	s_addc_u32 s27, s25, 0
	s_cmp_eq_u32 s65, 20
	s_cselect_b32 s31, s1, s27
	s_cselect_b32 s30, s0, s26
	s_cselect_b32 s29, s23, s64
	s_cselect_b32 s28, s22, s63
	s_add_i32 m0, s37, 0xc000
	ds_read_b128 v[182:185], v165
	ds_read_b128 v[186:189], v165 offset:1024
	ds_read_b128 v[190:193], v165 offset:2048
	ds_read_b128 v[194:197], v165 offset:3072
	ds_read_b128 v[198:201], v165 offset:4096
	ds_read_b128 v[208:211], v165 offset:5120
	ds_read_b128 v[212:215], v165 offset:6144
	ds_read_b128 v[216:219], v165 offset:7168
	global_load_lds_dwordx4 v146, s[24:25]
	s_add_i32 m0, s37, 0xe000
	s_nop 0
	global_load_lds_dwordx4 v144, s[24:25]
	s_waitcnt vmcnt(8)
	s_waitcnt lgkmcnt(0)
	s_barrier
	s_waitcnt lgkmcnt(0)
	v_mfma_f32_16x16x32_f16 v[120:123], v[152:155], v[182:185], v[120:123]
	v_mfma_f32_16x16x32_f16 v[124:127], v[128:131], v[182:185], v[124:127]
	v_mfma_f32_16x16x32_f16 v[104:107], v[152:155], v[190:193], v[104:107]
	v_mfma_f32_16x16x32_f16 v[108:111], v[128:131], v[190:193], v[108:111]
	v_mfma_f32_16x16x32_f16 v[88:91], v[152:155], v[198:201], v[88:91]
	v_mfma_f32_16x16x32_f16 v[92:95], v[128:131], v[198:201], v[92:95]
	v_mfma_f32_16x16x32_f16 v[72:75], v[152:155], v[212:215], v[72:75]
	v_mfma_f32_16x16x32_f16 v[76:79], v[128:131], v[212:215], v[76:79]
	v_mfma_f32_16x16x32_f16 v[120:123], v[156:159], v[186:189], v[120:123]
	v_mfma_f32_16x16x32_f16 v[124:127], v[132:135], v[186:189], v[124:127]
	v_mfma_f32_16x16x32_f16 v[104:107], v[156:159], v[194:197], v[104:107]
	v_mfma_f32_16x16x32_f16 v[108:111], v[132:135], v[194:197], v[108:111]
	v_mfma_f32_16x16x32_f16 v[88:91], v[156:159], v[208:211], v[88:91]
	v_mfma_f32_16x16x32_f16 v[92:95], v[132:135], v[208:211], v[92:95]
	v_mfma_f32_16x16x32_f16 v[72:75], v[156:159], v[216:219], v[72:75]
	v_mfma_f32_16x16x32_f16 v[76:79], v[132:135], v[216:219], v[76:79]
	v_mfma_f32_16x16x32_f16 v[112:115], v[174:177], v[182:185], v[112:115]
	v_mfma_f32_16x16x32_f16 v[116:119], v[166:169], v[182:185], v[116:119]
	v_mfma_f32_16x16x32_f16 v[96:99], v[174:177], v[190:193], v[96:99]
	v_mfma_f32_16x16x32_f16 v[100:103], v[166:169], v[190:193], v[100:103]
	v_mfma_f32_16x16x32_f16 v[80:83], v[174:177], v[198:201], v[80:83]
	v_mfma_f32_16x16x32_f16 v[84:87], v[166:169], v[198:201], v[84:87]
	v_mfma_f32_16x16x32_f16 v[64:67], v[174:177], v[212:215], v[64:67]
	v_mfma_f32_16x16x32_f16 v[68:71], v[166:169], v[212:215], v[68:71]
	v_mfma_f32_16x16x32_f16 v[112:115], v[178:181], v[186:189], v[112:115]
	v_mfma_f32_16x16x32_f16 v[116:119], v[170:173], v[186:189], v[116:119]
	v_mfma_f32_16x16x32_f16 v[96:99], v[178:181], v[194:197], v[96:99]
	v_mfma_f32_16x16x32_f16 v[100:103], v[170:173], v[194:197], v[100:103]
	v_mfma_f32_16x16x32_f16 v[80:83], v[178:181], v[208:211], v[80:83]
	v_mfma_f32_16x16x32_f16 v[84:87], v[170:173], v[208:211], v[84:87]
	v_mfma_f32_16x16x32_f16 v[64:67], v[178:181], v[216:219], v[64:67]
	v_mfma_f32_16x16x32_f16 v[68:71], v[170:173], v[216:219], v[68:71]
	s_barrier
	s_add_i32 s24, s45, s36
	s_add_u32 s98, s28, s16
	s_addc_u32 s99, s29, s17
	s_mov_b32 m0, s24
	ds_read_b128 v[182:185], v165 offset:16384
	ds_read_b128 v[186:189], v165 offset:17408
	ds_read_b128 v[190:193], v165 offset:18432
	ds_read_b128 v[194:197], v165 offset:19456
	ds_read_b128 v[198:201], v165 offset:20480
	ds_read_b128 v[208:211], v165 offset:21504
	ds_read_b128 v[212:215], v165 offset:22528
	ds_read_b128 v[216:219], v165 offset:23552
	global_load_lds_dwordx4 v138, s[28:29]
	s_add_i32 m0, s24, 0x2000
	s_add_u32 s24, s28, 0x60000
	s_addc_u32 s25, s29, 0
	s_add_i32 s66, s52, s36
	global_load_lds_dwordx4 v142, s[28:29]
	s_mov_b32 m0, s66
	s_nop 0
	global_load_lds_dwordx4 v138, s[24:25]
	s_add_i32 m0, s66, 0x2000
	s_nop 0
	global_load_lds_dwordx4 v142, s[24:25]
	s_add_u32 s100, s30, s16
	s_addc_u32 s101, s31, s17
	s_mov_b32 m0, s37
	s_nop 0
	global_load_lds_dwordx4 v136, s[30:31]
	s_mov_b32 m0, s38
	s_nop 0
	global_load_lds_dwordx4 v140, s[30:31]
	s_waitcnt vmcnt(8)
	s_waitcnt lgkmcnt(0)
	s_barrier
	s_waitcnt lgkmcnt(0)
	v_mfma_f32_16x16x32_f16 v[56:59], v[152:155], v[182:185], v[56:59]
	v_mfma_f32_16x16x32_f16 v[60:63], v[128:131], v[182:185], v[60:63]
	v_mfma_f32_16x16x32_f16 v[40:43], v[152:155], v[190:193], v[40:43]
	v_mfma_f32_16x16x32_f16 v[44:47], v[128:131], v[190:193], v[44:47]
	v_mfma_f32_16x16x32_f16 v[24:27], v[152:155], v[198:201], v[24:27]
	v_mfma_f32_16x16x32_f16 v[28:31], v[128:131], v[198:201], v[28:31]
	v_mfma_f32_16x16x32_f16 v[8:11], v[152:155], v[212:215], v[8:11]
	v_mfma_f32_16x16x32_f16 v[12:15], v[128:131], v[212:215], v[12:15]
	v_mfma_f32_16x16x32_f16 v[56:59], v[156:159], v[186:189], v[56:59]
	v_mfma_f32_16x16x32_f16 v[60:63], v[132:135], v[186:189], v[60:63]
	v_mfma_f32_16x16x32_f16 v[40:43], v[156:159], v[194:197], v[40:43]
	v_mfma_f32_16x16x32_f16 v[44:47], v[132:135], v[194:197], v[44:47]
	v_mfma_f32_16x16x32_f16 v[24:27], v[156:159], v[208:211], v[24:27]
	v_mfma_f32_16x16x32_f16 v[28:31], v[132:135], v[208:211], v[28:31]
	v_mfma_f32_16x16x32_f16 v[8:11], v[156:159], v[216:219], v[8:11]
	v_mfma_f32_16x16x32_f16 v[12:15], v[132:135], v[216:219], v[12:15]
	v_mfma_f32_16x16x32_f16 v[48:51], v[174:177], v[182:185], v[48:51]
	v_mfma_f32_16x16x32_f16 v[52:55], v[166:169], v[182:185], v[52:55]
	v_mfma_f32_16x16x32_f16 v[32:35], v[174:177], v[190:193], v[32:35]
	v_mfma_f32_16x16x32_f16 v[36:39], v[166:169], v[190:193], v[36:39]
	v_mfma_f32_16x16x32_f16 v[16:19], v[174:177], v[198:201], v[16:19]
	v_mfma_f32_16x16x32_f16 v[20:23], v[166:169], v[198:201], v[20:23]
	v_mfma_f32_16x16x32_f16 v[0:3], v[174:177], v[212:215], v[0:3]
	v_mfma_f32_16x16x32_f16 v[4:7], v[166:169], v[212:215], v[4:7]
	v_mfma_f32_16x16x32_f16 v[48:51], v[178:181], v[186:189], v[48:51]
	v_mfma_f32_16x16x32_f16 v[52:55], v[170:173], v[186:189], v[52:55]
	v_mfma_f32_16x16x32_f16 v[32:35], v[178:181], v[194:197], v[32:35]
	v_mfma_f32_16x16x32_f16 v[36:39], v[170:173], v[194:197], v[36:39]
	v_mfma_f32_16x16x32_f16 v[16:19], v[178:181], v[208:211], v[16:19]
	v_mfma_f32_16x16x32_f16 v[20:23], v[170:173], v[208:211], v[20:23]
	v_mfma_f32_16x16x32_f16 v[0:3], v[178:181], v[216:219], v[0:3]
	v_mfma_f32_16x16x32_f16 v[4:7], v[170:173], v[216:219], v[4:7]
	s_barrier
; #define PG8_STAGE(bufoff, gbase, voff) do { _Pragma("unroll") for (int _i = 0; _i < 2; ++_i) \
;         __builtin_amdgcn_global_load_lds((const unsigned*)((const char*)(gbase) + (voff)[_i]), (PG8_LAS unsigned*)(lds + (bufoff) + ldsw + _i * 8192), 16, 0, 0); } while (0)
; #define PG8_LDA(dst, b, h) do { _Pragma("unroll") for (int m = 0; m < 4; ++m) _Pragma("unroll") for (int k = 0; k < 2; ++k) dst[m][k] = *(const PG8_LAS bf16x8*)(lds + PG8_SA(b, h) + aoff + m * 2048 + k * 1024); } while (0)
; #define PG8_LDB(dst, b, h) do { _Pragma("unroll") for (int n = 0; n < 2; ++n) _Pragma("unroll") for (int k = 0; k < 2; ++k) dst[n][k] = *(const PG8_LAS bf16x8*)(lds + PG8_SB(b, h) + boff + n * 2048 + k * 1024); } while (0)
; #define PG8_MMA(ai, bj, At, Bt) do { __builtin_amdgcn_s_setprio(1); _Pragma("unroll") for (int m = 0; m < 4; ++m) _Pragma("unroll") for (int n = 0; n < 2; ++n) _Pragma("unroll") for (int k = 0; k < 2; ++k) \
;         acc[ai][bj][m][n] = __builtin_amdgcn_mfma_f32_16x16x32_f16(Bt[n][k], At[m][k], acc[ai][bj][m][n], 0, 0, 0); __builtin_amdgcn_s_setprio(0); } while (0)
; #define PG8_WAIT_V(n) asm volatile("s_waitcnt vmcnt(" #n ")" ::: "memory")
; #define PG8_WAIT_L(n) asm volatile("s_waitcnt lgkmcnt(" #n ")" ::: "memory")
; #define PG8_BAR __builtin_amdgcn_s_barrier()
; #define PG8_SCHED __builtin_amdgcn_sched_barrier(0)
; template <class Epi, class Sched, bool ALIGN_EPI = false, bool SP2 = false>
; __device__ __forceinline__ void gemm_phase(PG8_LAS unsigned char* lds, const Gemm g, const Sched& S, const Epi& E) {
;     ...
;         for (int t = 0; t < nt; t += 2) {
;     ...
;             PG8_LDB(B0, 1, 0); PG8_LDB(B1, 1, 1); PG8_SCHED; PG8_LDA(At, 1, 0); PG8_STAGE(PG8_SA(0, 1), a2 + hstep, voffA);
;             PG8_WAIT_V(8); PG8_WAIT_L(0); PG8_BAR; PG8_MMA(0, 0, At, B0); PG8_MMA(0, 1, At, B1); PG8_BAR; PG8_SCHED;
;             PG8_LDA(At, 1, 1); PG8_STAGE(PG8_SB(1, 0), b3, voffB); PG8_STAGE(PG8_SB(1, 1), b3 + hstep, voffB); PG8_STAGE(PG8_SA(1, 0), a3, voffA);
;             PG8_WAIT_V(8); PG8_WAIT_L(0); PG8_BAR; PG8_MMA(1, 0, At, B0); PG8_MMA(1, 1, At, B1); PG8_BAR; PG8_SCHED;
	s_add_i32 s66, 0, 0x18000
	s_add_i32 s67, 0, 0x1c000
	v_add_u32_e32 v156, s66, v161
	v_add_u32_e32 v178, s67, v161
	ds_read_b128 v[128:131], v156
	ds_read_b128 v[132:135], v156 offset:1024
	ds_read_b128 v[152:155], v156 offset:2048
	ds_read_b128 v[156:159], v156 offset:3072
	ds_read_b128 v[166:169], v178
	ds_read_b128 v[170:173], v178 offset:1024
	ds_read_b128 v[174:177], v178 offset:2048
	ds_read_b128 v[178:181], v178 offset:3072
	s_add_u32 s24, s30, 0x60000
	s_addc_u32 s25, s31, 0
	s_mov_b32 m0, s39
	ds_read_b128 v[182:185], v165 offset:32768
	ds_read_b128 v[186:189], v165 offset:33792
	ds_read_b128 v[190:193], v165 offset:34816
	ds_read_b128 v[194:197], v165 offset:35840
	ds_read_b128 v[198:201], v165 offset:36864
	ds_read_b128 v[208:211], v165 offset:37888
	ds_read_b128 v[212:215], v165 offset:38912
	ds_read_b128 v[216:219], v165 offset:39936
	global_load_lds_dwordx4 v136, s[24:25]
	s_mov_b32 m0, s40
	s_nop 0
	global_load_lds_dwordx4 v140, s[24:25]
	s_waitcnt vmcnt(8)
	s_waitcnt lgkmcnt(0)
	s_barrier
	s_waitcnt lgkmcnt(0)
	v_mfma_f32_16x16x32_f16 v[120:123], v[152:155], v[182:185], v[120:123]
	v_mfma_f32_16x16x32_f16 v[124:127], v[128:131], v[182:185], v[124:127]
	v_mfma_f32_16x16x32_f16 v[104:107], v[152:155], v[190:193], v[104:107]
	v_mfma_f32_16x16x32_f16 v[108:111], v[128:131], v[190:193], v[108:111]
	v_mfma_f32_16x16x32_f16 v[88:91], v[152:155], v[198:201], v[88:91]
	v_mfma_f32_16x16x32_f16 v[92:95], v[128:131], v[198:201], v[92:95]
	v_mfma_f32_16x16x32_f16 v[72:75], v[152:155], v[212:215], v[72:75]
	v_mfma_f32_16x16x32_f16 v[76:79], v[128:131], v[212:215], v[76:79]
	v_mfma_f32_16x16x32_f16 v[120:123], v[156:159], v[186:189], v[120:123]
	v_mfma_f32_16x16x32_f16 v[124:127], v[132:135], v[186:189], v[124:127]
	v_mfma_f32_16x16x32_f16 v[104:107], v[156:159], v[194:197], v[104:107]
	v_mfma_f32_16x16x32_f16 v[108:111], v[132:135], v[194:197], v[108:111]
	v_mfma_f32_16x16x32_f16 v[88:91], v[156:159], v[208:211], v[88:91]
	v_mfma_f32_16x16x32_f16 v[92:95], v[132:135], v[208:211], v[92:95]
	v_mfma_f32_16x16x32_f16 v[72:75], v[156:159], v[216:219], v[72:75]
	v_mfma_f32_16x16x32_f16 v[76:79], v[132:135], v[216:219], v[76:79]
	v_mfma_f32_16x16x32_f16 v[112:115], v[174:177], v[182:185], v[112:115]
	v_mfma_f32_16x16x32_f16 v[116:119], v[166:169], v[182:185], v[116:119]
	v_mfma_f32_16x16x32_f16 v[96:99], v[174:177], v[190:193], v[96:99]
	v_mfma_f32_16x16x32_f16 v[100:103], v[166:169], v[190:193], v[100:103]
	v_mfma_f32_16x16x32_f16 v[80:83], v[174:177], v[198:201], v[80:83]
	v_mfma_f32_16x16x32_f16 v[84:87], v[166:169], v[198:201], v[84:87]
	v_mfma_f32_16x16x32_f16 v[64:67], v[174:177], v[212:215], v[64:67]
	v_mfma_f32_16x16x32_f16 v[68:71], v[166:169], v[212:215], v[68:71]
	v_mfma_f32_16x16x32_f16 v[112:115], v[178:181], v[186:189], v[112:115]
	v_mfma_f32_16x16x32_f16 v[116:119], v[170:173], v[186:189], v[116:119]
	v_mfma_f32_16x16x32_f16 v[96:99], v[178:181], v[194:197], v[96:99]
	v_mfma_f32_16x16x32_f16 v[100:103], v[170:173], v[194:197], v[100:103]
	v_mfma_f32_16x16x32_f16 v[80:83], v[178:181], v[208:211], v[80:83]
	v_mfma_f32_16x16x32_f16 v[84:87], v[170:173], v[208:211], v[84:87]
	v_mfma_f32_16x16x32_f16 v[64:67], v[178:181], v[216:219], v[64:67]
	v_mfma_f32_16x16x32_f16 v[68:71], v[170:173], v[216:219], v[68:71]
	s_barrier
	s_add_i32 s24, s66, s36
	s_mov_b32 m0, s24
	ds_read_b128 v[182:185], v165 offset:49152
	ds_read_b128 v[186:189], v165 offset:50176
	ds_read_b128 v[190:193], v165 offset:51200
	ds_read_b128 v[194:197], v165 offset:52224
	ds_read_b128 v[198:201], v165 offset:53248
	ds_read_b128 v[208:211], v165 offset:54272
	ds_read_b128 v[212:215], v165 offset:55296
	ds_read_b128 v[216:219], v165 offset:56320
	global_load_lds_dwordx4 v138, s[98:99]
	s_add_i32 m0, s24, 0x2000
	s_add_u32 s24, s28, 0x60080
	s_addc_u32 s25, s29, 0
	s_add_i32 s28, s67, s36
	global_load_lds_dwordx4 v142, s[98:99]
	s_mov_b32 m0, s28
	s_nop 0
	global_load_lds_dwordx4 v138, s[24:25]
	s_add_i32 m0, s28, 0x2000
	s_nop 0
	global_load_lds_dwordx4 v142, s[24:25]
	s_mov_b32 m0, s42
	s_nop 0
	global_load_lds_dwordx4 v136, s[100:101]
	s_mov_b32 m0, s43
	s_nop 0
	global_load_lds_dwordx4 v140, s[100:101]
	s_waitcnt vmcnt(8)
	s_waitcnt lgkmcnt(0)
	s_barrier
	s_waitcnt lgkmcnt(0)
	v_mfma_f32_16x16x32_f16 v[56:59], v[152:155], v[182:185], v[56:59]
	v_mfma_f32_16x16x32_f16 v[60:63], v[128:131], v[182:185], v[60:63]
	v_mfma_f32_16x16x32_f16 v[40:43], v[152:155], v[190:193], v[40:43]
	v_mfma_f32_16x16x32_f16 v[44:47], v[128:131], v[190:193], v[44:47]
	v_mfma_f32_16x16x32_f16 v[24:27], v[152:155], v[198:201], v[24:27]
	v_mfma_f32_16x16x32_f16 v[28:31], v[128:131], v[198:201], v[28:31]
	v_mfma_f32_16x16x32_f16 v[8:11], v[152:155], v[212:215], v[8:11]
	v_mfma_f32_16x16x32_f16 v[12:15], v[128:131], v[212:215], v[12:15]
	v_mfma_f32_16x16x32_f16 v[56:59], v[156:159], v[186:189], v[56:59]
	v_mfma_f32_16x16x32_f16 v[60:63], v[132:135], v[186:189], v[60:63]
	v_mfma_f32_16x16x32_f16 v[40:43], v[156:159], v[194:197], v[40:43]
	v_mfma_f32_16x16x32_f16 v[44:47], v[132:135], v[194:197], v[44:47]
	v_mfma_f32_16x16x32_f16 v[24:27], v[156:159], v[208:211], v[24:27]
	v_mfma_f32_16x16x32_f16 v[28:31], v[132:135], v[208:211], v[28:31]
	v_mfma_f32_16x16x32_f16 v[8:11], v[156:159], v[216:219], v[8:11]
	v_mfma_f32_16x16x32_f16 v[12:15], v[132:135], v[216:219], v[12:15]
	v_mfma_f32_16x16x32_f16 v[48:51], v[174:177], v[182:185], v[48:51]
	v_mfma_f32_16x16x32_f16 v[52:55], v[166:169], v[182:185], v[52:55]
	v_mfma_f32_16x16x32_f16 v[32:35], v[174:177], v[190:193], v[32:35]
	v_mfma_f32_16x16x32_f16 v[36:39], v[166:169], v[190:193], v[36:39]
	v_mfma_f32_16x16x32_f16 v[16:19], v[174:177], v[198:201], v[16:19]
	v_mfma_f32_16x16x32_f16 v[20:23], v[166:169], v[198:201], v[20:23]
	v_mfma_f32_16x16x32_f16 v[0:3], v[174:177], v[212:215], v[0:3]
	v_mfma_f32_16x16x32_f16 v[4:7], v[166:169], v[212:215], v[4:7]
	v_mfma_f32_16x16x32_f16 v[48:51], v[178:181], v[186:189], v[48:51]
	v_mfma_f32_16x16x32_f16 v[52:55], v[170:173], v[186:189], v[52:55]
	v_mfma_f32_16x16x32_f16 v[32:35], v[178:181], v[194:197], v[32:35]
	v_mfma_f32_16x16x32_f16 v[36:39], v[170:173], v[194:197], v[36:39]
	v_mfma_f32_16x16x32_f16 v[16:19], v[178:181], v[208:211], v[16:19]
	v_mfma_f32_16x16x32_f16 v[20:23], v[170:173], v[208:211], v[20:23]
	v_mfma_f32_16x16x32_f16 v[0:3], v[178:181], v[216:219], v[0:3]
	v_mfma_f32_16x16x32_f16 v[4:7], v[170:173], v[216:219], v[4:7]
	s_barrier
	s_add_i32 s65, s65, 2
	s_add_u32 s63, s63, 0x100
	s_addc_u32 s64, s64, 0
	s_cmp_gt_u32 s65, 21
	s_mov_b64 s[24:25], s[26:27]
	s_cbranch_scc0 .LBB0_485
	s_and_b64 vcc, exec, s[18:19]
	s_cbranch_vccz .LBB0_488
	s_barrier

; #define WS_SETUP unsigned char* ws = P.ws; asm volatile("" : "+s"(ws)); float* R = P.out; asm volatile("" : "+s"(R)); (void)R;
;     __host__ __device__ bool next(int i, Unit& u) const {
;         const long L = (long)i * G + c; if (L >= nwg) return false;
;         int wgid = (int)L; { const int q = nwg / NXCD, r = nwg % NXCD, xcd = wgid % NXCD, off = wgid / NXCD; wgid = (xcd < r ? xcd * (q + 1) : r * (q + 1) + (xcd - r) * q) + off; }
;         const int nig = wgm * nN, gid = wgid / nig, fm = gid * wgm, gsz = (nM - fm) < wgm ? (nM - fm) : wgm;
;         u.pm = fm + ((wgid % nig) % gsz); u.pn = (wgid % nig) / gsz; return true;
; __global__ void __launch_bounds__(NWAVES * 64, 2) mega_fwd(Params P) {
;     ...
;     { WS_SETUP pg8::Gemm g{XB, (const h16*)(ws + WS_W_W1A), MTOK, DFF, DM}; pg8::EpiAny<1, 1> E{}; E.O = HID; E.ldc = DFF; E.st_in = STATS; E.c1 = C1; E.c2 = C2;
;       pg8::StaticOrder S; S.init(MTOK, DFF, G, (int)blockIdx.x, WGM_UP);
;       pg8::gemm_phase<pg8::EpiAny<1, 1>, pg8::StaticOrder, true, true>(lds, g, S, E); }
.LBB0_560:
	s_or_b64 exec, exec, s[0:1]
	s_mov_b64 s[6:7], s[78:79]
	s_mov_b64 s[0:1], s[76:77]
	v_mov_b32_e32 v8, v204
	s_setprio 0
	v_readfirstlane_b32 s98, v204
	s_lshr_b32 s98, s98, 8
	s_cmp_lg_u32 s98, 0
	s_cbranch_scc0 .Lsprio_skip_3
	s_setprio 1
.Lsprio_skip_3:
	s_cmpk_lt_i32 s2, 0x800
	s_waitcnt lgkmcnt(0)
	s_barrier
	s_cselect_b64 s[52:53], -1, 0
	s_cmpk_gt_i32 s2, 0x7ff
	v_readfirstlane_b32 s19, v8
	s_cbranch_scc1 .LBB0_584
	s_ashr_i32 s3, s2, 31
	s_lshr_b32 s0, s3, 29
	s_add_i32 s9, s2, s0
	s_and_b32 s0, s9, -8
	s_sub_i32 s10, s2, s0
	s_cmp_gt_i32 s10, -1
	s_cbranch_scc0 .LBB0_563
	s_lshl_b32 s8, s10, 8
	s_cbranch_execz .LBB0_564
	s_branch .LBB0_565

; #define PG8_STAGE(bufoff, gbase, voff) do { _Pragma("unroll") for (int _i = 0; _i < 2; ++_i) \
;         __builtin_amdgcn_global_load_lds((const unsigned*)((const char*)(gbase) + (voff)[_i]), (PG8_LAS unsigned*)(lds + (bufoff) + ldsw + _i * 8192), 16, 0, 0); } while (0)
; #define PG8_LDA(dst, b, h) do { _Pragma("unroll") for (int m = 0; m < 4; ++m) _Pragma("unroll") for (int k = 0; k < 2; ++k) dst[m][k] = *(const PG8_LAS bf16x8*)(lds + PG8_SA(b, h) + aoff + m * 2048 + k * 1024); } while (0)
; #define PG8_LDB(dst, b, h) do { _Pragma("unroll") for (int n = 0; n < 2; ++n) _Pragma("unroll") for (int k = 0; k < 2; ++k) dst[n][k] = *(const PG8_LAS bf16x8*)(lds + PG8_SB(b, h) + boff + n * 2048 + k * 1024); } while (0)
; #define PG8_MMA(ai, bj, At, Bt) do { __builtin_amdgcn_s_setprio(1); _Pragma("unroll") for (int m = 0; m < 4; ++m) _Pragma("unroll") for (int n = 0; n < 2; ++n) _Pragma("unroll") for (int k = 0; k < 2; ++k) \
;         acc[ai][bj][m][n] = __builtin_amdgcn_mfma_f32_16x16x32_f16(Bt[n][k], At[m][k], acc[ai][bj][m][n], 0, 0, 0); __builtin_amdgcn_s_setprio(0); } while (0)
; #define PG8_WAIT_V(n) asm volatile("s_waitcnt vmcnt(" #n ")" ::: "memory")
; #define PG8_WAIT_L(n) asm volatile("s_waitcnt lgkmcnt(" #n ")" ::: "memory")
; #define PG8_BAR __builtin_amdgcn_s_barrier()
; #define PG8_SCHED __builtin_amdgcn_sched_barrier(0)
; template <class Epi, class Sched, bool ALIGN_EPI = false, bool SP2 = false>
; __device__ __forceinline__ void gemm_phase(PG8_LAS unsigned char* lds, const Gemm g, const Sched& S, const Epi& E) {
;     ...
;             PG8_LDB(B0, 0, 0); PG8_LDB(B1, 0, 1); PG8_SCHED; PG8_LDA(At, 0, 0); PG8_STAGE(PG8_SA(1, 1), a1 + hstep, voffA);
;             PG8_WAIT_V(8); PG8_WAIT_L(0); PG8_BAR; PG8_MMA(0, 0, At, B0); PG8_MMA(0, 1, At, B1); PG8_BAR; PG8_SCHED;
;             PG8_LDA(At, 0, 1); PG8_STAGE(PG8_SB(0, 0), b2, voffB); PG8_STAGE(PG8_SB(0, 1), b2 + hstep, voffB); PG8_STAGE(PG8_SA(0, 0), a2, voffA);
;             PG8_WAIT_V(8); PG8_WAIT_L(0); PG8_BAR; PG8_MMA(1, 0, At, B0); PG8_MMA(1, 1, At, B1); PG8_BAR; PG8_SCHED;
.LBB0_577:
	ds_read_b128 v[128:131], v198
	ds_read_b128 v[132:135], v198 offset:1024
	ds_read_b128 v[136:139], v198 offset:2048
	ds_read_b128 v[140:143], v198 offset:3072
	ds_read_b128 v[144:147], v199
	ds_read_b128 v[148:151], v199 offset:1024
	ds_read_b128 v[152:155], v199 offset:2048
	ds_read_b128 v[156:159], v199 offset:3072
	s_add_u32 s42, s40, 0xfff80080
	s_addc_u32 s43, s41, -1
	s_cmp_eq_u32 s91, 28
	s_cselect_b32 s45, s31, s43
	s_cselect_b32 s44, s87, s42
	s_cselect_b32 s43, s29, s90
	s_cselect_b32 s42, s88, s89
	s_add_i32 m0, s39, 0xc000
	ds_read_b128 v[176:179], v200
	ds_read_b128 v[180:183], v200 offset:1024
	ds_read_b128 v[184:187], v200 offset:2048
	ds_read_b128 v[188:191], v200 offset:3072
	ds_read_b128 v[208:211], v200 offset:4096
	ds_read_b128 v[212:215], v200 offset:5120
	ds_read_b128 v[216:219], v200 offset:6144
	ds_read_b128 v[220:223], v200 offset:7168
	global_load_lds_dwordx4 v170, s[40:41]
	s_add_i32 m0, s39, 0xe000
	s_nop 0
	global_load_lds_dwordx4 v168, s[40:41]
	s_waitcnt vmcnt(8)
	s_waitcnt lgkmcnt(0)
	s_barrier
	s_waitcnt lgkmcnt(0)
	v_mfma_f32_16x16x32_f16 v[120:123], v[136:139], v[176:179], v[120:123]
	v_mfma_f32_16x16x32_f16 v[124:127], v[128:131], v[176:179], v[124:127]
	v_mfma_f32_16x16x32_f16 v[104:107], v[136:139], v[184:187], v[104:107]
	v_mfma_f32_16x16x32_f16 v[108:111], v[128:131], v[184:187], v[108:111]
	v_mfma_f32_16x16x32_f16 v[88:91], v[136:139], v[208:211], v[88:91]
	v_mfma_f32_16x16x32_f16 v[92:95], v[128:131], v[208:211], v[92:95]
	v_mfma_f32_16x16x32_f16 v[72:75], v[136:139], v[216:219], v[72:75]
	v_mfma_f32_16x16x32_f16 v[76:79], v[128:131], v[216:219], v[76:79]
	v_mfma_f32_16x16x32_f16 v[120:123], v[140:143], v[180:183], v[120:123]
	v_mfma_f32_16x16x32_f16 v[124:127], v[132:135], v[180:183], v[124:127]
	v_mfma_f32_16x16x32_f16 v[104:107], v[140:143], v[188:191], v[104:107]
	v_mfma_f32_16x16x32_f16 v[108:111], v[132:135], v[188:191], v[108:111]
	v_mfma_f32_16x16x32_f16 v[88:91], v[140:143], v[212:215], v[88:91]
	v_mfma_f32_16x16x32_f16 v[92:95], v[132:135], v[212:215], v[92:95]
	v_mfma_f32_16x16x32_f16 v[72:75], v[140:143], v[220:223], v[72:75]
	v_mfma_f32_16x16x32_f16 v[76:79], v[132:135], v[220:223], v[76:79]
	v_mfma_f32_16x16x32_f16 v[112:115], v[152:155], v[176:179], v[112:115]
	v_mfma_f32_16x16x32_f16 v[116:119], v[144:147], v[176:179], v[116:119]
	v_mfma_f32_16x16x32_f16 v[96:99], v[152:155], v[184:187], v[96:99]
	v_mfma_f32_16x16x32_f16 v[100:103], v[144:147], v[184:187], v[100:103]
	v_mfma_f32_16x16x32_f16 v[80:83], v[152:155], v[208:211], v[80:83]
	v_mfma_f32_16x16x32_f16 v[84:87], v[144:147], v[208:211], v[84:87]
	v_mfma_f32_16x16x32_f16 v[64:67], v[152:155], v[216:219], v[64:67]
	v_mfma_f32_16x16x32_f16 v[68:71], v[144:147], v[216:219], v[68:71]
	v_mfma_f32_16x16x32_f16 v[112:115], v[156:159], v[180:183], v[112:115]
	v_mfma_f32_16x16x32_f16 v[116:119], v[148:151], v[180:183], v[116:119]
	v_mfma_f32_16x16x32_f16 v[96:99], v[156:159], v[188:191], v[96:99]
	v_mfma_f32_16x16x32_f16 v[100:103], v[148:151], v[188:191], v[100:103]
	v_mfma_f32_16x16x32_f16 v[80:83], v[156:159], v[212:215], v[80:83]
	v_mfma_f32_16x16x32_f16 v[84:87], v[148:151], v[212:215], v[84:87]
	v_mfma_f32_16x16x32_f16 v[64:67], v[156:159], v[220:223], v[64:67]
	v_mfma_f32_16x16x32_f16 v[68:71], v[148:151], v[220:223], v[68:71]
	s_barrier
	s_add_i32 s92, s74, s63
	s_add_u32 s98, s42, s16
	s_addc_u32 s99, s43, s17
	s_mov_b32 m0, s92
	ds_read_b128 v[176:179], v200 offset:16384
	ds_read_b128 v[180:183], v200 offset:17408
	ds_read_b128 v[184:187], v200 offset:18432
	ds_read_b128 v[188:191], v200 offset:19456
	ds_read_b128 v[208:211], v200 offset:20480
	ds_read_b128 v[212:215], v200 offset:21504
	ds_read_b128 v[216:219], v200 offset:22528
	ds_read_b128 v[220:223], v200 offset:23552
	global_load_lds_dwordx4 v162, s[42:43]
	s_add_i32 m0, s92, 0x2000
	s_add_u32 s92, s42, 0x80000
	s_addc_u32 s93, s43, 0
	s_add_i32 s94, s75, s63
	global_load_lds_dwordx4 v166, s[42:43]
	s_mov_b32 m0, s94
	s_nop 0
	global_load_lds_dwordx4 v162, s[92:93]
	s_add_i32 m0, s94, 0x2000
	s_nop 0
	global_load_lds_dwordx4 v166, s[92:93]
	s_add_u32 s100, s44, s16
	s_addc_u32 s101, s45, s17
	s_mov_b32 m0, s39
	s_nop 0
	global_load_lds_dwordx4 v160, s[44:45]
	s_mov_b32 m0, s64
	s_nop 0
	global_load_lds_dwordx4 v164, s[44:45]
	s_waitcnt vmcnt(8)
	s_waitcnt lgkmcnt(0)
	s_barrier
	s_waitcnt lgkmcnt(0)
	v_mfma_f32_16x16x32_f16 v[56:59], v[136:139], v[176:179], v[56:59]
	v_mfma_f32_16x16x32_f16 v[60:63], v[128:131], v[176:179], v[60:63]
	v_mfma_f32_16x16x32_f16 v[40:43], v[136:139], v[184:187], v[40:43]
	v_mfma_f32_16x16x32_f16 v[44:47], v[128:131], v[184:187], v[44:47]
	v_mfma_f32_16x16x32_f16 v[24:27], v[136:139], v[208:211], v[24:27]
	v_mfma_f32_16x16x32_f16 v[28:31], v[128:131], v[208:211], v[28:31]
	v_mfma_f32_16x16x32_f16 v[8:11], v[136:139], v[216:219], v[8:11]
	v_mfma_f32_16x16x32_f16 v[12:15], v[128:131], v[216:219], v[12:15]
	v_mfma_f32_16x16x32_f16 v[56:59], v[140:143], v[180:183], v[56:59]
	v_mfma_f32_16x16x32_f16 v[60:63], v[132:135], v[180:183], v[60:63]
	v_mfma_f32_16x16x32_f16 v[40:43], v[140:143], v[188:191], v[40:43]
	v_mfma_f32_16x16x32_f16 v[44:47], v[132:135], v[188:191], v[44:47]
	v_mfma_f32_16x16x32_f16 v[24:27], v[140:143], v[212:215], v[24:27]
	v_mfma_f32_16x16x32_f16 v[28:31], v[132:135], v[212:215], v[28:31]
	v_mfma_f32_16x16x32_f16 v[8:11], v[140:143], v[220:223], v[8:11]
	v_mfma_f32_16x16x32_f16 v[12:15], v[132:135], v[220:223], v[12:15]
	v_mfma_f32_16x16x32_f16 v[48:51], v[152:155], v[176:179], v[48:51]
	v_mfma_f32_16x16x32_f16 v[52:55], v[144:147], v[176:179], v[52:55]
	v_mfma_f32_16x16x32_f16 v[32:35], v[152:155], v[184:187], v[32:35]
	v_mfma_f32_16x16x32_f16 v[36:39], v[144:147], v[184:187], v[36:39]
	v_mfma_f32_16x16x32_f16 v[16:19], v[152:155], v[208:211], v[16:19]
	v_mfma_f32_16x16x32_f16 v[20:23], v[144:147], v[208:211], v[20:23]
	v_mfma_f32_16x16x32_f16 v[0:3], v[152:155], v[216:219], v[0:3]
	v_mfma_f32_16x16x32_f16 v[4:7], v[144:147], v[216:219], v[4:7]
	v_mfma_f32_16x16x32_f16 v[48:51], v[156:159], v[180:183], v[48:51]
	v_mfma_f32_16x16x32_f16 v[52:55], v[148:151], v[180:183], v[52:55]
	v_mfma_f32_16x16x32_f16 v[32:35], v[156:159], v[188:191], v[32:35]
	v_mfma_f32_16x16x32_f16 v[36:39], v[148:151], v[188:191], v[36:39]
	v_mfma_f32_16x16x32_f16 v[16:19], v[156:159], v[212:215], v[16:19]
	v_mfma_f32_16x16x32_f16 v[20:23], v[148:151], v[212:215], v[20:23]
	v_mfma_f32_16x16x32_f16 v[0:3], v[156:159], v[220:223], v[0:3]
	v_mfma_f32_16x16x32_f16 v[4:7], v[148:151], v[220:223], v[4:7]
	s_barrier
; #define PG8_STAGE(bufoff, gbase, voff) do { _Pragma("unroll") for (int _i = 0; _i < 2; ++_i) \
;         __builtin_amdgcn_global_load_lds((const unsigned*)((const char*)(gbase) + (voff)[_i]), (PG8_LAS unsigned*)(lds + (bufoff) + ldsw + _i * 8192), 16, 0, 0); } while (0)
; #define PG8_LDA(dst, b, h) do { _Pragma("unroll") for (int m = 0; m < 4; ++m) _Pragma("unroll") for (int k = 0; k < 2; ++k) dst[m][k] = *(const PG8_LAS bf16x8*)(lds + PG8_SA(b, h) + aoff + m * 2048 + k * 1024); } while (0)
; #define PG8_LDB(dst, b, h) do { _Pragma("unroll") for (int n = 0; n < 2; ++n) _Pragma("unroll") for (int k = 0; k < 2; ++k) dst[n][k] = *(const PG8_LAS bf16x8*)(lds + PG8_SB(b, h) + boff + n * 2048 + k * 1024); } while (0)
; #define PG8_MMA(ai, bj, At, Bt) do { __builtin_amdgcn_s_setprio(1); _Pragma("unroll") for (int m = 0; m < 4; ++m) _Pragma("unroll") for (int n = 0; n < 2; ++n) _Pragma("unroll") for (int k = 0; k < 2; ++k) \
;         acc[ai][bj][m][n] = __builtin_amdgcn_mfma_f32_16x16x32_f16(Bt[n][k], At[m][k], acc[ai][bj][m][n], 0, 0, 0); __builtin_amdgcn_s_setprio(0); } while (0)
; #define PG8_WAIT_V(n) asm volatile("s_waitcnt vmcnt(" #n ")" ::: "memory")
; #define PG8_WAIT_L(n) asm volatile("s_waitcnt lgkmcnt(" #n ")" ::: "memory")
; #define PG8_BAR __builtin_amdgcn_s_barrier()
; #define PG8_SCHED __builtin_amdgcn_sched_barrier(0)
; template <class Epi, class Sched, bool ALIGN_EPI = false, bool SP2 = false>
; __device__ __forceinline__ void gemm_phase(PG8_LAS unsigned char* lds, const Gemm g, const Sched& S, const Epi& E) {
;     ...
;         for (int t = 0; t < nt; t += 2) {
;     ...
;             PG8_LDB(B0, 1, 0); PG8_LDB(B1, 1, 1); PG8_SCHED; PG8_LDA(At, 1, 0); PG8_STAGE(PG8_SA(0, 1), a2 + hstep, voffA);
;             PG8_WAIT_V(8); PG8_WAIT_L(0); PG8_BAR; PG8_MMA(0, 0, At, B0); PG8_MMA(0, 1, At, B1); PG8_BAR; PG8_SCHED;
;             PG8_LDA(At, 1, 1); PG8_STAGE(PG8_SB(1, 0), b3, voffB); PG8_STAGE(PG8_SB(1, 1), b3 + hstep, voffB); PG8_STAGE(PG8_SA(1, 0), a3, voffA);
;             PG8_WAIT_V(8); PG8_WAIT_L(0); PG8_BAR; PG8_MMA(1, 0, At, B0); PG8_MMA(1, 1, At, B1); PG8_BAR; PG8_SCHED;
	s_add_i32 s92, 0, 0x18000
	s_add_i32 s93, 0, 0x1c000
	v_add_u32_e32 v140, s92, v196
	v_add_u32_e32 v156, s93, v196
	ds_read_b128 v[128:131], v140
	ds_read_b128 v[132:135], v140 offset:1024
	ds_read_b128 v[136:139], v140 offset:2048
	ds_read_b128 v[140:143], v140 offset:3072
	ds_read_b128 v[144:147], v156
	ds_read_b128 v[148:151], v156 offset:1024
	ds_read_b128 v[152:155], v156 offset:2048
	ds_read_b128 v[156:159], v156 offset:3072
	s_add_u32 s44, s44, 0x80000
	s_addc_u32 s45, s45, 0
	s_mov_b32 m0, s65
	ds_read_b128 v[176:179], v200 offset:32768
	ds_read_b128 v[180:183], v200 offset:33792
	ds_read_b128 v[184:187], v200 offset:34816
	ds_read_b128 v[188:191], v200 offset:35840
	ds_read_b128 v[208:211], v200 offset:36864
	ds_read_b128 v[212:215], v200 offset:37888
	ds_read_b128 v[216:219], v200 offset:38912
	ds_read_b128 v[220:223], v200 offset:39936
	global_load_lds_dwordx4 v160, s[44:45]
	s_mov_b32 m0, s66
	s_nop 0
	global_load_lds_dwordx4 v164, s[44:45]
	s_waitcnt vmcnt(8)
	s_waitcnt lgkmcnt(0)
	s_barrier
	s_waitcnt lgkmcnt(0)
	v_mfma_f32_16x16x32_f16 v[120:123], v[136:139], v[176:179], v[120:123]
	v_mfma_f32_16x16x32_f16 v[124:127], v[128:131], v[176:179], v[124:127]
	v_mfma_f32_16x16x32_f16 v[104:107], v[136:139], v[184:187], v[104:107]
	v_mfma_f32_16x16x32_f16 v[108:111], v[128:131], v[184:187], v[108:111]
	v_mfma_f32_16x16x32_f16 v[88:91], v[136:139], v[208:211], v[88:91]
	v_mfma_f32_16x16x32_f16 v[92:95], v[128:131], v[208:211], v[92:95]
	v_mfma_f32_16x16x32_f16 v[72:75], v[136:139], v[216:219], v[72:75]
	v_mfma_f32_16x16x32_f16 v[76:79], v[128:131], v[216:219], v[76:79]
	v_mfma_f32_16x16x32_f16 v[120:123], v[140:143], v[180:183], v[120:123]
	v_mfma_f32_16x16x32_f16 v[124:127], v[132:135], v[180:183], v[124:127]
	v_mfma_f32_16x16x32_f16 v[104:107], v[140:143], v[188:191], v[104:107]
	v_mfma_f32_16x16x32_f16 v[108:111], v[132:135], v[188:191], v[108:111]
	v_mfma_f32_16x16x32_f16 v[88:91], v[140:143], v[212:215], v[88:91]
	v_mfma_f32_16x16x32_f16 v[92:95], v[132:135], v[212:215], v[92:95]
	v_mfma_f32_16x16x32_f16 v[72:75], v[140:143], v[220:223], v[72:75]
	v_mfma_f32_16x16x32_f16 v[76:79], v[132:135], v[220:223], v[76:79]
	v_mfma_f32_16x16x32_f16 v[112:115], v[152:155], v[176:179], v[112:115]
	v_mfma_f32_16x16x32_f16 v[116:119], v[144:147], v[176:179], v[116:119]
	v_mfma_f32_16x16x32_f16 v[96:99], v[152:155], v[184:187], v[96:99]
	v_mfma_f32_16x16x32_f16 v[100:103], v[144:147], v[184:187], v[100:103]
	v_mfma_f32_16x16x32_f16 v[80:83], v[152:155], v[208:211], v[80:83]
	v_mfma_f32_16x16x32_f16 v[84:87], v[144:147], v[208:211], v[84:87]
	v_mfma_f32_16x16x32_f16 v[64:67], v[152:155], v[216:219], v[64:67]
	v_mfma_f32_16x16x32_f16 v[68:71], v[144:147], v[216:219], v[68:71]
	v_mfma_f32_16x16x32_f16 v[112:115], v[156:159], v[180:183], v[112:115]
	v_mfma_f32_16x16x32_f16 v[116:119], v[148:151], v[180:183], v[116:119]
	v_mfma_f32_16x16x32_f16 v[96:99], v[156:159], v[188:191], v[96:99]
	v_mfma_f32_16x16x32_f16 v[100:103], v[148:151], v[188:191], v[100:103]
	v_mfma_f32_16x16x32_f16 v[80:83], v[156:159], v[212:215], v[80:83]
	v_mfma_f32_16x16x32_f16 v[84:87], v[148:151], v[212:215], v[84:87]
	v_mfma_f32_16x16x32_f16 v[64:67], v[156:159], v[220:223], v[64:67]
	v_mfma_f32_16x16x32_f16 v[68:71], v[148:151], v[220:223], v[68:71]
	s_barrier
	s_add_i32 s44, s92, s63
	s_mov_b32 m0, s44
	ds_read_b128 v[176:179], v200 offset:49152
	ds_read_b128 v[180:183], v200 offset:50176
	ds_read_b128 v[184:187], v200 offset:51200
	ds_read_b128 v[188:191], v200 offset:52224
	ds_read_b128 v[208:211], v200 offset:53248
	ds_read_b128 v[212:215], v200 offset:54272
	ds_read_b128 v[216:219], v200 offset:55296
	ds_read_b128 v[220:223], v200 offset:56320
	global_load_lds_dwordx4 v162, s[98:99]
	s_add_i32 m0, s44, 0x2000
	s_add_u32 s42, s42, 0x80080
	s_addc_u32 s43, s43, 0
	s_add_i32 s44, s93, s63
	global_load_lds_dwordx4 v166, s[98:99]
	s_mov_b32 m0, s44
	s_nop 0
	global_load_lds_dwordx4 v162, s[42:43]
	s_add_i32 m0, s44, 0x2000
	s_nop 0
	global_load_lds_dwordx4 v166, s[42:43]
	s_mov_b32 m0, s68
	s_nop 0
	global_load_lds_dwordx4 v160, s[100:101]
	s_mov_b32 m0, s69
	s_nop 0
	global_load_lds_dwordx4 v164, s[100:101]
	s_waitcnt vmcnt(8)
	s_waitcnt lgkmcnt(0)
	s_barrier
	s_waitcnt lgkmcnt(0)
	v_mfma_f32_16x16x32_f16 v[56:59], v[136:139], v[176:179], v[56:59]
	v_mfma_f32_16x16x32_f16 v[60:63], v[128:131], v[176:179], v[60:63]
	v_mfma_f32_16x16x32_f16 v[40:43], v[136:139], v[184:187], v[40:43]
	v_mfma_f32_16x16x32_f16 v[44:47], v[128:131], v[184:187], v[44:47]
	v_mfma_f32_16x16x32_f16 v[24:27], v[136:139], v[208:211], v[24:27]
	v_mfma_f32_16x16x32_f16 v[28:31], v[128:131], v[208:211], v[28:31]
	v_mfma_f32_16x16x32_f16 v[8:11], v[136:139], v[216:219], v[8:11]
	v_mfma_f32_16x16x32_f16 v[12:15], v[128:131], v[216:219], v[12:15]
	v_mfma_f32_16x16x32_f16 v[56:59], v[140:143], v[180:183], v[56:59]
	v_mfma_f32_16x16x32_f16 v[60:63], v[132:135], v[180:183], v[60:63]
	v_mfma_f32_16x16x32_f16 v[40:43], v[140:143], v[188:191], v[40:43]
	v_mfma_f32_16x16x32_f16 v[44:47], v[132:135], v[188:191], v[44:47]
	v_mfma_f32_16x16x32_f16 v[24:27], v[140:143], v[212:215], v[24:27]
	v_mfma_f32_16x16x32_f16 v[28:31], v[132:135], v[212:215], v[28:31]
	v_mfma_f32_16x16x32_f16 v[8:11], v[140:143], v[220:223], v[8:11]
	v_mfma_f32_16x16x32_f16 v[12:15], v[132:135], v[220:223], v[12:15]
	v_mfma_f32_16x16x32_f16 v[48:51], v[152:155], v[176:179], v[48:51]
	v_mfma_f32_16x16x32_f16 v[52:55], v[144:147], v[176:179], v[52:55]
	v_mfma_f32_16x16x32_f16 v[32:35], v[152:155], v[184:187], v[32:35]
	v_mfma_f32_16x16x32_f16 v[36:39], v[144:147], v[184:187], v[36:39]
	v_mfma_f32_16x16x32_f16 v[16:19], v[152:155], v[208:211], v[16:19]
	v_mfma_f32_16x16x32_f16 v[20:23], v[144:147], v[208:211], v[20:23]
	v_mfma_f32_16x16x32_f16 v[0:3], v[152:155], v[216:219], v[0:3]
	v_mfma_f32_16x16x32_f16 v[4:7], v[144:147], v[216:219], v[4:7]
	v_mfma_f32_16x16x32_f16 v[48:51], v[156:159], v[180:183], v[48:51]
	v_mfma_f32_16x16x32_f16 v[52:55], v[148:151], v[180:183], v[52:55]
	v_mfma_f32_16x16x32_f16 v[32:35], v[156:159], v[188:191], v[32:35]
	v_mfma_f32_16x16x32_f16 v[36:39], v[148:151], v[188:191], v[36:39]
	v_mfma_f32_16x16x32_f16 v[16:19], v[156:159], v[212:215], v[16:19]
	v_mfma_f32_16x16x32_f16 v[20:23], v[148:151], v[212:215], v[20:23]
	v_mfma_f32_16x16x32_f16 v[0:3], v[156:159], v[220:223], v[0:3]
	v_mfma_f32_16x16x32_f16 v[4:7], v[148:151], v[220:223], v[4:7]
	s_barrier
	s_add_i32 s91, s91, 2
	s_add_u32 s89, s89, 0x100
	s_addc_u32 s90, s90, 0
	s_add_u32 s40, s40, 0x100
	s_addc_u32 s41, s41, 0
	s_cmp_gt_u32 s91, 29
	s_cbranch_scc0 .LBB0_577
	s_and_b64 vcc, exec, s[18:19]
	s_cbranch_vccz .LBB0_580
	s_barrier

; #define WS_SETUP unsigned char* ws = P.ws; asm volatile("" : "+s"(ws)); float* R = P.out; asm volatile("" : "+s"(R)); (void)R;
;     __host__ __device__ bool next(int i, Unit& u) const {
;         const long L = (long)i * G + c; if (L >= nwg) return false;
;         int wgid = (int)L; { const int q = nwg / NXCD, r = nwg % NXCD, xcd = wgid % NXCD, off = wgid / NXCD; wgid = (xcd < r ? xcd * (q + 1) : r * (q + 1) + (xcd - r) * q) + off; }
;         const int nig = wgm * nN, gid = wgid / nig, fm = gid * wgm, gsz = (nM - fm) < wgm ? (nM - fm) : wgm;
;         u.pm = fm + ((wgid % nig) % gsz); u.pn = (wgid % nig) / gsz; return true;
; __global__ void __launch_bounds__(NWAVES * 64, 2) mega_fwd(Params P) {
;     ...
;     { WS_SETUP pg8::Gemm g{HID, (const h16*)(ws + WS_W_W2A), MTOK, DM, DFF}; pg8::EpiAny<2, 1> E{}; E.xbase = XB; E.ldc = DM; E.alpha = ALPHA; E.st_in = STATS; E.g = P.in[10]; E.b = P.in[11]; E.xb = XR; E.st_out = STATS + 2 * MTOK;
;       pg8::StaticOrder S; S.init(MTOK, DM, G, (int)blockIdx.x, WGM_N2048);
;       pg8::gemm_phase<pg8::EpiAny<2, 1>, pg8::StaticOrder, true, true>(lds, g, S, E); }
.Lsprio_skip_4:
	s_waitcnt lgkmcnt(0)
	s_barrier
	s_and_b64 vcc, exec, s[4:5]
	v_readfirstlane_b32 s20, v8
	s_cbranch_vccnz .LBB0_642
	s_ashr_i32 s3, s2, 31
	s_lshr_b32 s3, s3, 29
	s_add_i32 s3, s2, s3
	s_and_b32 s8, s3, -8
	s_sub_i32 s10, s2, s8
	s_cmp_gt_i32 s10, -1
	s_cbranch_scc0 .LBB0_639
	s_lshl_b32 s11, s10, 6
	s_cbranch_execz .LBB0_640
	s_branch .LBB0_641

; #define PG8_STAGE(bufoff, gbase, voff) do { _Pragma("unroll") for (int _i = 0; _i < 2; ++_i) \
;         __builtin_amdgcn_global_load_lds((const unsigned*)((const char*)(gbase) + (voff)[_i]), (PG8_LAS unsigned*)(lds + (bufoff) + ldsw + _i * 8192), 16, 0, 0); } while (0)
; #define PG8_LDA(dst, b, h) do { _Pragma("unroll") for (int m = 0; m < 4; ++m) _Pragma("unroll") for (int k = 0; k < 2; ++k) dst[m][k] = *(const PG8_LAS bf16x8*)(lds + PG8_SA(b, h) + aoff + m * 2048 + k * 1024); } while (0)
; #define PG8_LDB(dst, b, h) do { _Pragma("unroll") for (int n = 0; n < 2; ++n) _Pragma("unroll") for (int k = 0; k < 2; ++k) dst[n][k] = *(const PG8_LAS bf16x8*)(lds + PG8_SB(b, h) + boff + n * 2048 + k * 1024); } while (0)
; #define PG8_MMA(ai, bj, At, Bt) do { __builtin_amdgcn_s_setprio(1); _Pragma("unroll") for (int m = 0; m < 4; ++m) _Pragma("unroll") for (int n = 0; n < 2; ++n) _Pragma("unroll") for (int k = 0; k < 2; ++k) \
;         acc[ai][bj][m][n] = __builtin_amdgcn_mfma_f32_16x16x32_f16(Bt[n][k], At[m][k], acc[ai][bj][m][n], 0, 0, 0); __builtin_amdgcn_s_setprio(0); } while (0)
; #define PG8_WAIT_V(n) asm volatile("s_waitcnt vmcnt(" #n ")" ::: "memory")
; #define PG8_WAIT_L(n) asm volatile("s_waitcnt lgkmcnt(" #n ")" ::: "memory")
; #define PG8_BAR __builtin_amdgcn_s_barrier()
; #define PG8_SCHED __builtin_amdgcn_sched_barrier(0)
; template <class Epi, class Sched, bool ALIGN_EPI = false, bool SP2 = false>
; __device__ __forceinline__ void gemm_phase(PG8_LAS unsigned char* lds, const Gemm g, const Sched& S, const Epi& E) {
;     ...
;             PG8_LDB(B0, 0, 0); PG8_LDB(B1, 0, 1); PG8_SCHED; PG8_LDA(At, 0, 0); PG8_STAGE(PG8_SA(1, 1), a1 + hstep, voffA);
;             PG8_WAIT_V(8); PG8_WAIT_L(0); PG8_BAR; PG8_MMA(0, 0, At, B0); PG8_MMA(0, 1, At, B1); PG8_BAR; PG8_SCHED;
;             PG8_LDA(At, 0, 1); PG8_STAGE(PG8_SB(0, 0), b2, voffB); PG8_STAGE(PG8_SB(0, 1), b2 + hstep, voffB); PG8_STAGE(PG8_SA(0, 0), a2, voffA);
;             PG8_WAIT_V(8); PG8_WAIT_L(0); PG8_BAR; PG8_MMA(1, 0, At, B0); PG8_MMA(1, 1, At, B1); PG8_BAR; PG8_SCHED;
.LBB0_655:
	ds_read_b128 v[128:131], v211
	ds_read_b128 v[132:135], v211 offset:1024
	ds_read_b128 v[136:139], v211 offset:2048
	ds_read_b128 v[140:143], v211 offset:3072
	ds_read_b128 v[144:147], v212
	ds_read_b128 v[148:151], v212 offset:1024
	ds_read_b128 v[152:155], v212 offset:2048
	ds_read_b128 v[156:159], v212 offset:3072
	s_add_u32 s42, s40, 0xffe00080
	s_addc_u32 s43, s41, -1
	s_cmpk_eq_i32 s86, 0x7c
	s_cselect_b32 s45, s29, s43
	s_cselect_b32 s44, s37, s42
	s_cselect_b32 s43, s27, s83
	s_cselect_b32 s42, s81, s82
	s_add_i32 m0, s39, 0xc000
	ds_read_b128 v[160:163], v213
	ds_read_b128 v[164:167], v213 offset:1024
	ds_read_b128 v[184:187], v213 offset:2048
	ds_read_b128 v[188:191], v213 offset:3072
	ds_read_b128 v[192:195], v213 offset:4096
	ds_read_b128 v[196:199], v213 offset:5120
	ds_read_b128 v[200:203], v213 offset:6144
	ds_read_b128 v[214:217], v213 offset:7168
	global_load_lds_dwordx4 v178, s[40:41]
	s_add_i32 m0, s39, 0xe000
	s_nop 0
	global_load_lds_dwordx4 v176, s[40:41]
	s_waitcnt vmcnt(8)
	s_waitcnt lgkmcnt(0)
	s_barrier
	s_waitcnt lgkmcnt(0)
	v_mfma_f32_16x16x32_f16 v[120:123], v[136:139], v[160:163], v[120:123]
	v_mfma_f32_16x16x32_f16 v[124:127], v[128:131], v[160:163], v[124:127]
	v_mfma_f32_16x16x32_f16 v[104:107], v[136:139], v[184:187], v[104:107]
	v_mfma_f32_16x16x32_f16 v[108:111], v[128:131], v[184:187], v[108:111]
	v_mfma_f32_16x16x32_f16 v[88:91], v[136:139], v[192:195], v[88:91]
	v_mfma_f32_16x16x32_f16 v[92:95], v[128:131], v[192:195], v[92:95]
	v_mfma_f32_16x16x32_f16 v[72:75], v[136:139], v[200:203], v[72:75]
	v_mfma_f32_16x16x32_f16 v[76:79], v[128:131], v[200:203], v[76:79]
	v_mfma_f32_16x16x32_f16 v[120:123], v[140:143], v[164:167], v[120:123]
	v_mfma_f32_16x16x32_f16 v[124:127], v[132:135], v[164:167], v[124:127]
	v_mfma_f32_16x16x32_f16 v[104:107], v[140:143], v[188:191], v[104:107]
	v_mfma_f32_16x16x32_f16 v[108:111], v[132:135], v[188:191], v[108:111]
	v_mfma_f32_16x16x32_f16 v[88:91], v[140:143], v[196:199], v[88:91]
	v_mfma_f32_16x16x32_f16 v[92:95], v[132:135], v[196:199], v[92:95]
	v_mfma_f32_16x16x32_f16 v[72:75], v[140:143], v[214:217], v[72:75]
	v_mfma_f32_16x16x32_f16 v[76:79], v[132:135], v[214:217], v[76:79]
	v_mfma_f32_16x16x32_f16 v[112:115], v[152:155], v[160:163], v[112:115]
	v_mfma_f32_16x16x32_f16 v[116:119], v[144:147], v[160:163], v[116:119]
	v_mfma_f32_16x16x32_f16 v[96:99], v[152:155], v[184:187], v[96:99]
	v_mfma_f32_16x16x32_f16 v[100:103], v[144:147], v[184:187], v[100:103]
	v_mfma_f32_16x16x32_f16 v[80:83], v[152:155], v[192:195], v[80:83]
	v_mfma_f32_16x16x32_f16 v[84:87], v[144:147], v[192:195], v[84:87]
	v_mfma_f32_16x16x32_f16 v[64:67], v[152:155], v[200:203], v[64:67]
	v_mfma_f32_16x16x32_f16 v[68:71], v[144:147], v[200:203], v[68:71]
	v_mfma_f32_16x16x32_f16 v[112:115], v[156:159], v[164:167], v[112:115]
	v_mfma_f32_16x16x32_f16 v[116:119], v[148:151], v[164:167], v[116:119]
	v_mfma_f32_16x16x32_f16 v[96:99], v[156:159], v[188:191], v[96:99]
	v_mfma_f32_16x16x32_f16 v[100:103], v[148:151], v[188:191], v[100:103]
	v_mfma_f32_16x16x32_f16 v[80:83], v[156:159], v[196:199], v[80:83]
	v_mfma_f32_16x16x32_f16 v[84:87], v[148:151], v[196:199], v[84:87]
	v_mfma_f32_16x16x32_f16 v[64:67], v[156:159], v[214:217], v[64:67]
	v_mfma_f32_16x16x32_f16 v[68:71], v[148:151], v[214:217], v[68:71]
	s_barrier
	s_add_i32 s87, s69, s61
	s_add_u32 s98, s42, s18
	s_addc_u32 s99, s43, s19
	s_mov_b32 m0, s87
	ds_read_b128 v[160:163], v213 offset:16384
	ds_read_b128 v[164:167], v213 offset:17408
	ds_read_b128 v[184:187], v213 offset:18432
	ds_read_b128 v[188:191], v213 offset:19456
	ds_read_b128 v[192:195], v213 offset:20480
	ds_read_b128 v[196:199], v213 offset:21504
	ds_read_b128 v[200:203], v213 offset:22528
	ds_read_b128 v[214:217], v213 offset:23552
	global_load_lds_dwordx4 v170, s[42:43]
	s_add_i32 m0, s87, 0x2000
	s_add_u32 s88, s42, 0x200000
	s_addc_u32 s89, s43, 0
	s_add_i32 s87, s74, s61
	global_load_lds_dwordx4 v174, s[42:43]
	s_mov_b32 m0, s87
	s_nop 0
	global_load_lds_dwordx4 v170, s[88:89]
	s_add_i32 m0, s87, 0x2000
	s_nop 0
	global_load_lds_dwordx4 v174, s[88:89]
	s_add_u32 s100, s44, s18
	s_addc_u32 s101, s45, s19
	s_mov_b32 m0, s39
	s_nop 0
	global_load_lds_dwordx4 v168, s[44:45]
	s_mov_b32 m0, s62
	s_nop 0
	global_load_lds_dwordx4 v172, s[44:45]
	s_waitcnt vmcnt(8)
	s_waitcnt lgkmcnt(0)
	s_barrier
	s_waitcnt lgkmcnt(0)
	v_mfma_f32_16x16x32_f16 v[56:59], v[136:139], v[160:163], v[56:59]
	v_mfma_f32_16x16x32_f16 v[60:63], v[128:131], v[160:163], v[60:63]
	v_mfma_f32_16x16x32_f16 v[40:43], v[136:139], v[184:187], v[40:43]
	v_mfma_f32_16x16x32_f16 v[44:47], v[128:131], v[184:187], v[44:47]
	v_mfma_f32_16x16x32_f16 v[24:27], v[136:139], v[192:195], v[24:27]
	v_mfma_f32_16x16x32_f16 v[28:31], v[128:131], v[192:195], v[28:31]
	v_mfma_f32_16x16x32_f16 v[8:11], v[136:139], v[200:203], v[8:11]
	v_mfma_f32_16x16x32_f16 v[12:15], v[128:131], v[200:203], v[12:15]
	v_mfma_f32_16x16x32_f16 v[56:59], v[140:143], v[164:167], v[56:59]
	v_mfma_f32_16x16x32_f16 v[60:63], v[132:135], v[164:167], v[60:63]
	v_mfma_f32_16x16x32_f16 v[40:43], v[140:143], v[188:191], v[40:43]
	v_mfma_f32_16x16x32_f16 v[44:47], v[132:135], v[188:191], v[44:47]
	v_mfma_f32_16x16x32_f16 v[24:27], v[140:143], v[196:199], v[24:27]
	v_mfma_f32_16x16x32_f16 v[28:31], v[132:135], v[196:199], v[28:31]
	v_mfma_f32_16x16x32_f16 v[8:11], v[140:143], v[214:217], v[8:11]
	v_mfma_f32_16x16x32_f16 v[12:15], v[132:135], v[214:217], v[12:15]
	v_mfma_f32_16x16x32_f16 v[48:51], v[152:155], v[160:163], v[48:51]
	v_mfma_f32_16x16x32_f16 v[52:55], v[144:147], v[160:163], v[52:55]
	v_mfma_f32_16x16x32_f16 v[32:35], v[152:155], v[184:187], v[32:35]
	v_mfma_f32_16x16x32_f16 v[36:39], v[144:147], v[184:187], v[36:39]
	v_mfma_f32_16x16x32_f16 v[16:19], v[152:155], v[192:195], v[16:19]
	v_mfma_f32_16x16x32_f16 v[20:23], v[144:147], v[192:195], v[20:23]
	v_mfma_f32_16x16x32_f16 v[0:3], v[152:155], v[200:203], v[0:3]
	v_mfma_f32_16x16x32_f16 v[4:7], v[144:147], v[200:203], v[4:7]
	v_mfma_f32_16x16x32_f16 v[48:51], v[156:159], v[164:167], v[48:51]
	v_mfma_f32_16x16x32_f16 v[52:55], v[148:151], v[164:167], v[52:55]
	v_mfma_f32_16x16x32_f16 v[32:35], v[156:159], v[188:191], v[32:35]
	v_mfma_f32_16x16x32_f16 v[36:39], v[148:151], v[188:191], v[36:39]
	v_mfma_f32_16x16x32_f16 v[16:19], v[156:159], v[196:199], v[16:19]
	v_mfma_f32_16x16x32_f16 v[20:23], v[148:151], v[196:199], v[20:23]
	v_mfma_f32_16x16x32_f16 v[0:3], v[156:159], v[214:217], v[0:3]
	v_mfma_f32_16x16x32_f16 v[4:7], v[148:151], v[214:217], v[4:7]
	s_barrier
; #define PG8_STAGE(bufoff, gbase, voff) do { _Pragma("unroll") for (int _i = 0; _i < 2; ++_i) \
;         __builtin_amdgcn_global_load_lds((const unsigned*)((const char*)(gbase) + (voff)[_i]), (PG8_LAS unsigned*)(lds + (bufoff) + ldsw + _i * 8192), 16, 0, 0); } while (0)
; #define PG8_LDA(dst, b, h) do { _Pragma("unroll") for (int m = 0; m < 4; ++m) _Pragma("unroll") for (int k = 0; k < 2; ++k) dst[m][k] = *(const PG8_LAS bf16x8*)(lds + PG8_SA(b, h) + aoff + m * 2048 + k * 1024); } while (0)
; #define PG8_LDB(dst, b, h) do { _Pragma("unroll") for (int n = 0; n < 2; ++n) _Pragma("unroll") for (int k = 0; k < 2; ++k) dst[n][k] = *(const PG8_LAS bf16x8*)(lds + PG8_SB(b, h) + boff + n * 2048 + k * 1024); } while (0)
; #define PG8_MMA(ai, bj, At, Bt) do { __builtin_amdgcn_s_setprio(1); _Pragma("unroll") for (int m = 0; m < 4; ++m) _Pragma("unroll") for (int n = 0; n < 2; ++n) _Pragma("unroll") for (int k = 0; k < 2; ++k) \
;         acc[ai][bj][m][n] = __builtin_amdgcn_mfma_f32_16x16x32_f16(Bt[n][k], At[m][k], acc[ai][bj][m][n], 0, 0, 0); __builtin_amdgcn_s_setprio(0); } while (0)
; #define PG8_WAIT_V(n) asm volatile("s_waitcnt vmcnt(" #n ")" ::: "memory")
; #define PG8_WAIT_L(n) asm volatile("s_waitcnt lgkmcnt(" #n ")" ::: "memory")
; #define PG8_BAR __builtin_amdgcn_s_barrier()
; #define PG8_SCHED __builtin_amdgcn_sched_barrier(0)
; template <class Epi, class Sched, bool ALIGN_EPI = false, bool SP2 = false>
; __device__ __forceinline__ void gemm_phase(PG8_LAS unsigned char* lds, const Gemm g, const Sched& S, const Epi& E) {
;     ...
;         for (int t = 0; t < nt; t += 2) {
;     ...
;             PG8_LDB(B0, 1, 0); PG8_LDB(B1, 1, 1); PG8_SCHED; PG8_LDA(At, 1, 0); PG8_STAGE(PG8_SA(0, 1), a2 + hstep, voffA);
;             PG8_WAIT_V(8); PG8_WAIT_L(0); PG8_BAR; PG8_MMA(0, 0, At, B0); PG8_MMA(0, 1, At, B1); PG8_BAR; PG8_SCHED;
;             PG8_LDA(At, 1, 1); PG8_STAGE(PG8_SB(1, 0), b3, voffB); PG8_STAGE(PG8_SB(1, 1), b3 + hstep, voffB); PG8_STAGE(PG8_SA(1, 0), a3, voffA);
;             PG8_WAIT_V(8); PG8_WAIT_L(0); PG8_BAR; PG8_MMA(1, 0, At, B0); PG8_MMA(1, 1, At, B1); PG8_BAR; PG8_SCHED;
	s_add_i32 s87, 0, 0x18000
	s_add_i32 s88, 0, 0x1c000
	v_add_u32_e32 v140, s87, v209
	v_add_u32_e32 v156, s88, v209
	ds_read_b128 v[128:131], v140
	ds_read_b128 v[132:135], v140 offset:1024
	ds_read_b128 v[136:139], v140 offset:2048
	ds_read_b128 v[140:143], v140 offset:3072
	ds_read_b128 v[144:147], v156
	ds_read_b128 v[148:151], v156 offset:1024
	ds_read_b128 v[152:155], v156 offset:2048
	ds_read_b128 v[156:159], v156 offset:3072
	s_add_u32 s44, s44, 0x200000
	s_addc_u32 s45, s45, 0
	s_mov_b32 m0, s63
	ds_read_b128 v[160:163], v213 offset:32768
	ds_read_b128 v[164:167], v213 offset:33792
	ds_read_b128 v[184:187], v213 offset:34816
	ds_read_b128 v[188:191], v213 offset:35840
	ds_read_b128 v[192:195], v213 offset:36864
	ds_read_b128 v[196:199], v213 offset:37888
	ds_read_b128 v[200:203], v213 offset:38912
	ds_read_b128 v[214:217], v213 offset:39936
	global_load_lds_dwordx4 v168, s[44:45]
	s_mov_b32 m0, s64
	s_nop 0
	global_load_lds_dwordx4 v172, s[44:45]
	s_waitcnt vmcnt(8)
	s_waitcnt lgkmcnt(0)
	s_barrier
	s_waitcnt lgkmcnt(0)
	v_mfma_f32_16x16x32_f16 v[120:123], v[136:139], v[160:163], v[120:123]
	v_mfma_f32_16x16x32_f16 v[124:127], v[128:131], v[160:163], v[124:127]
	v_mfma_f32_16x16x32_f16 v[104:107], v[136:139], v[184:187], v[104:107]
	v_mfma_f32_16x16x32_f16 v[108:111], v[128:131], v[184:187], v[108:111]
	v_mfma_f32_16x16x32_f16 v[88:91], v[136:139], v[192:195], v[88:91]
	v_mfma_f32_16x16x32_f16 v[92:95], v[128:131], v[192:195], v[92:95]
	v_mfma_f32_16x16x32_f16 v[72:75], v[136:139], v[200:203], v[72:75]
	v_mfma_f32_16x16x32_f16 v[76:79], v[128:131], v[200:203], v[76:79]
	v_mfma_f32_16x16x32_f16 v[120:123], v[140:143], v[164:167], v[120:123]
	v_mfma_f32_16x16x32_f16 v[124:127], v[132:135], v[164:167], v[124:127]
	v_mfma_f32_16x16x32_f16 v[104:107], v[140:143], v[188:191], v[104:107]
	v_mfma_f32_16x16x32_f16 v[108:111], v[132:135], v[188:191], v[108:111]
	v_mfma_f32_16x16x32_f16 v[88:91], v[140:143], v[196:199], v[88:91]
	v_mfma_f32_16x16x32_f16 v[92:95], v[132:135], v[196:199], v[92:95]
	v_mfma_f32_16x16x32_f16 v[72:75], v[140:143], v[214:217], v[72:75]
	v_mfma_f32_16x16x32_f16 v[76:79], v[132:135], v[214:217], v[76:79]
	v_mfma_f32_16x16x32_f16 v[112:115], v[152:155], v[160:163], v[112:115]
	v_mfma_f32_16x16x32_f16 v[116:119], v[144:147], v[160:163], v[116:119]
	v_mfma_f32_16x16x32_f16 v[96:99], v[152:155], v[184:187], v[96:99]
	v_mfma_f32_16x16x32_f16 v[100:103], v[144:147], v[184:187], v[100:103]
	v_mfma_f32_16x16x32_f16 v[80:83], v[152:155], v[192:195], v[80:83]
	v_mfma_f32_16x16x32_f16 v[84:87], v[144:147], v[192:195], v[84:87]
	v_mfma_f32_16x16x32_f16 v[64:67], v[152:155], v[200:203], v[64:67]
	v_mfma_f32_16x16x32_f16 v[68:71], v[144:147], v[200:203], v[68:71]
	v_mfma_f32_16x16x32_f16 v[112:115], v[156:159], v[164:167], v[112:115]
	v_mfma_f32_16x16x32_f16 v[116:119], v[148:151], v[164:167], v[116:119]
	v_mfma_f32_16x16x32_f16 v[96:99], v[156:159], v[188:191], v[96:99]
	v_mfma_f32_16x16x32_f16 v[100:103], v[148:151], v[188:191], v[100:103]
	v_mfma_f32_16x16x32_f16 v[80:83], v[156:159], v[196:199], v[80:83]
	v_mfma_f32_16x16x32_f16 v[84:87], v[148:151], v[196:199], v[84:87]
	v_mfma_f32_16x16x32_f16 v[64:67], v[156:159], v[214:217], v[64:67]
	v_mfma_f32_16x16x32_f16 v[68:71], v[148:151], v[214:217], v[68:71]
	s_barrier
	s_add_i32 s44, s87, s61
	s_mov_b32 m0, s44
	ds_read_b128 v[160:163], v213 offset:49152
	ds_read_b128 v[164:167], v213 offset:50176
	ds_read_b128 v[184:187], v213 offset:51200
	ds_read_b128 v[188:191], v213 offset:52224
	ds_read_b128 v[192:195], v213 offset:53248
	ds_read_b128 v[196:199], v213 offset:54272
	ds_read_b128 v[200:203], v213 offset:55296
	ds_read_b128 v[214:217], v213 offset:56320
	global_load_lds_dwordx4 v170, s[98:99]
	s_add_i32 m0, s44, 0x2000
	s_add_u32 s42, s42, 0x200080
	s_addc_u32 s43, s43, 0
	s_add_i32 s44, s88, s61
	global_load_lds_dwordx4 v174, s[98:99]
	s_mov_b32 m0, s44
	s_nop 0
	global_load_lds_dwordx4 v170, s[42:43]
	s_add_i32 m0, s44, 0x2000
	s_nop 0
	global_load_lds_dwordx4 v174, s[42:43]
	s_mov_b32 m0, s66
	s_nop 0
	global_load_lds_dwordx4 v168, s[100:101]
	s_mov_b32 m0, s67
	s_nop 0
	global_load_lds_dwordx4 v172, s[100:101]
	s_waitcnt vmcnt(8)
	s_waitcnt lgkmcnt(0)
	s_barrier
	s_waitcnt lgkmcnt(0)
	v_mfma_f32_16x16x32_f16 v[56:59], v[136:139], v[160:163], v[56:59]
	v_mfma_f32_16x16x32_f16 v[60:63], v[128:131], v[160:163], v[60:63]
	v_mfma_f32_16x16x32_f16 v[40:43], v[136:139], v[184:187], v[40:43]
	v_mfma_f32_16x16x32_f16 v[44:47], v[128:131], v[184:187], v[44:47]
	v_mfma_f32_16x16x32_f16 v[24:27], v[136:139], v[192:195], v[24:27]
	v_mfma_f32_16x16x32_f16 v[28:31], v[128:131], v[192:195], v[28:31]
	v_mfma_f32_16x16x32_f16 v[8:11], v[136:139], v[200:203], v[8:11]
	v_mfma_f32_16x16x32_f16 v[12:15], v[128:131], v[200:203], v[12:15]
	v_mfma_f32_16x16x32_f16 v[56:59], v[140:143], v[164:167], v[56:59]
	v_mfma_f32_16x16x32_f16 v[60:63], v[132:135], v[164:167], v[60:63]
	v_mfma_f32_16x16x32_f16 v[40:43], v[140:143], v[188:191], v[40:43]
	v_mfma_f32_16x16x32_f16 v[44:47], v[132:135], v[188:191], v[44:47]
	v_mfma_f32_16x16x32_f16 v[24:27], v[140:143], v[196:199], v[24:27]
	v_mfma_f32_16x16x32_f16 v[28:31], v[132:135], v[196:199], v[28:31]
	v_mfma_f32_16x16x32_f16 v[8:11], v[140:143], v[214:217], v[8:11]
	v_mfma_f32_16x16x32_f16 v[12:15], v[132:135], v[214:217], v[12:15]
	v_mfma_f32_16x16x32_f16 v[48:51], v[152:155], v[160:163], v[48:51]
	v_mfma_f32_16x16x32_f16 v[52:55], v[144:147], v[160:163], v[52:55]
	v_mfma_f32_16x16x32_f16 v[32:35], v[152:155], v[184:187], v[32:35]
	v_mfma_f32_16x16x32_f16 v[36:39], v[144:147], v[184:187], v[36:39]
	v_mfma_f32_16x16x32_f16 v[16:19], v[152:155], v[192:195], v[16:19]
	v_mfma_f32_16x16x32_f16 v[20:23], v[144:147], v[192:195], v[20:23]
	v_mfma_f32_16x16x32_f16 v[0:3], v[152:155], v[200:203], v[0:3]
	v_mfma_f32_16x16x32_f16 v[4:7], v[144:147], v[200:203], v[4:7]
	v_mfma_f32_16x16x32_f16 v[48:51], v[156:159], v[164:167], v[48:51]
	v_mfma_f32_16x16x32_f16 v[52:55], v[148:151], v[164:167], v[52:55]
	v_mfma_f32_16x16x32_f16 v[32:35], v[156:159], v[188:191], v[32:35]
	v_mfma_f32_16x16x32_f16 v[36:39], v[148:151], v[188:191], v[36:39]
	v_mfma_f32_16x16x32_f16 v[16:19], v[156:159], v[196:199], v[16:19]
	v_mfma_f32_16x16x32_f16 v[20:23], v[148:151], v[196:199], v[20:23]
	v_mfma_f32_16x16x32_f16 v[0:3], v[156:159], v[214:217], v[0:3]
	v_mfma_f32_16x16x32_f16 v[4:7], v[148:151], v[214:217], v[4:7]
	s_barrier
	s_add_i32 s86, s86, 2
	s_add_u32 s82, s82, 0x100
	s_addc_u32 s83, s83, 0
	s_add_u32 s40, s40, 0x100
	s_addc_u32 s41, s41, 0
	s_cmpk_gt_u32 s86, 0x7d
	s_cbranch_scc0 .LBB0_655
	s_and_b64 vcc, exec, s[20:21]
	s_cbranch_vccz .LBB0_658
	s_barrier

; #define WS_SETUP unsigned char* ws = P.ws; asm volatile("" : "+s"(ws)); float* R = P.out; asm volatile("" : "+s"(R)); (void)R;
;     __host__ __device__ bool next(int i, Unit& u) const {
;         const long L = (long)i * G + c; if (L >= nwg) return false;
;         int wgid = (int)L; { const int q = nwg / NXCD, r = nwg % NXCD, xcd = wgid % NXCD, off = wgid / NXCD; wgid = (xcd < r ? xcd * (q + 1) : r * (q + 1) + (xcd - r) * q) + off; }
;         const int nig = wgm * nN, gid = wgid / nig, fm = gid * wgm, gsz = (nM - fm) < wgm ? (nM - fm) : wgm;
;         u.pm = fm + ((wgid % nig) % gsz); u.pn = (wgid % nig) / gsz; return true;
; __global__ void __launch_bounds__(NWAVES * 64, 2) mega_fwd(Params P) {
;     ...
;     { WS_SETUP pg8::Gemm g{XR, (const h16*)(ws + WS_W_OIN), MTOK, ODD_INP, DM}; pg8::EpiAny<0, 1> E{}; E.O = H2; E.ldc = ODD_INP; E.st_in = STATS + 2 * MTOK; E.c1 = C1 + 8192; E.c2 = C2 + 8192;
;       pg8::StaticOrder S; S.init(MTOK, ODD_INP, G, (int)blockIdx.x, WGM_IN);
;       pg8::gemm_phase<pg8::EpiAny<0, 1>, pg8::StaticOrder, true, true>(lds, g, S, E); }
.Lsprio_skip_5:
	s_waitcnt lgkmcnt(0)
	s_barrier
	s_cmpk_gt_i32 s2, 0x3ff
	v_readfirstlane_b32 s21, v8
	s_cbranch_scc1 .LBB0_754
	s_ashr_i32 s3, s2, 31
	s_lshr_b32 s8, s3, 29
	s_add_i32 s11, s2, s8
	s_and_b32 s8, s11, -8
	s_sub_i32 s12, s2, s8
	s_cmp_gt_i32 s12, -1
	s_cbranch_scc0 .LBB0_733
	s_lshl_b32 s10, s12, 7
	s_cbranch_execz .LBB0_734
	s_branch .LBB0_735

; #define PG8_STAGE(bufoff, gbase, voff) do { _Pragma("unroll") for (int _i = 0; _i < 2; ++_i) \
;         __builtin_amdgcn_global_load_lds((const unsigned*)((const char*)(gbase) + (voff)[_i]), (PG8_LAS unsigned*)(lds + (bufoff) + ldsw + _i * 8192), 16, 0, 0); } while (0)
; #define PG8_LDA(dst, b, h) do { _Pragma("unroll") for (int m = 0; m < 4; ++m) _Pragma("unroll") for (int k = 0; k < 2; ++k) dst[m][k] = *(const PG8_LAS bf16x8*)(lds + PG8_SA(b, h) + aoff + m * 2048 + k * 1024); } while (0)
; #define PG8_LDB(dst, b, h) do { _Pragma("unroll") for (int n = 0; n < 2; ++n) _Pragma("unroll") for (int k = 0; k < 2; ++k) dst[n][k] = *(const PG8_LAS bf16x8*)(lds + PG8_SB(b, h) + boff + n * 2048 + k * 1024); } while (0)
; #define PG8_MMA(ai, bj, At, Bt) do { __builtin_amdgcn_s_setprio(1); _Pragma("unroll") for (int m = 0; m < 4; ++m) _Pragma("unroll") for (int n = 0; n < 2; ++n) _Pragma("unroll") for (int k = 0; k < 2; ++k) \
;         acc[ai][bj][m][n] = __builtin_amdgcn_mfma_f32_16x16x32_f16(Bt[n][k], At[m][k], acc[ai][bj][m][n], 0, 0, 0); __builtin_amdgcn_s_setprio(0); } while (0)
; #define PG8_WAIT_V(n) asm volatile("s_waitcnt vmcnt(" #n ")" ::: "memory")
; #define PG8_WAIT_L(n) asm volatile("s_waitcnt lgkmcnt(" #n ")" ::: "memory")
; #define PG8_BAR __builtin_amdgcn_s_barrier()
; #define PG8_SCHED __builtin_amdgcn_sched_barrier(0)
; template <class Epi, class Sched, bool ALIGN_EPI = false, bool SP2 = false>
; __device__ __forceinline__ void gemm_phase(PG8_LAS unsigned char* lds, const Gemm g, const Sched& S, const Epi& E) {
;     ...
;             PG8_LDB(B0, 0, 0); PG8_LDB(B1, 0, 1); PG8_SCHED; PG8_LDA(At, 0, 0); PG8_STAGE(PG8_SA(1, 1), a1 + hstep, voffA);
;             PG8_WAIT_V(8); PG8_WAIT_L(0); PG8_BAR; PG8_MMA(0, 0, At, B0); PG8_MMA(0, 1, At, B1); PG8_BAR; PG8_SCHED;
;             PG8_LDA(At, 0, 1); PG8_STAGE(PG8_SB(0, 0), b2, voffB); PG8_STAGE(PG8_SB(0, 1), b2 + hstep, voffB); PG8_STAGE(PG8_SA(0, 0), a2, voffA);
;             PG8_WAIT_V(8); PG8_WAIT_L(0); PG8_BAR; PG8_MMA(1, 0, At, B0); PG8_MMA(1, 1, At, B1); PG8_BAR; PG8_SCHED;
.LBB0_747:
	ds_read_b128 v[128:131], v191
	ds_read_b128 v[132:135], v191 offset:1024
	ds_read_b128 v[136:139], v191 offset:2048
	ds_read_b128 v[140:143], v191 offset:3072
	ds_read_b128 v[144:147], v192
	ds_read_b128 v[148:151], v192 offset:1024
	ds_read_b128 v[152:155], v192 offset:2048
	ds_read_b128 v[156:159], v192 offset:3072
	s_add_u32 s48, s44, 0xfff80080
	s_addc_u32 s49, s45, -1
	s_cmp_eq_u32 s90, 28
	s_cselect_b32 s51, s37, s49
	s_cselect_b32 s50, s86, s48
	s_cselect_b32 s49, s35, s89
	s_cselect_b32 s48, s87, s88
	s_add_i32 m0, s43, 0xc000
	ds_read_b128 v[176:179], v193
	ds_read_b128 v[180:183], v193 offset:1024
	ds_read_b128 v[184:187], v193 offset:2048
	ds_read_b128 v[194:197], v193 offset:3072
	ds_read_b128 v[198:201], v193 offset:4096
	ds_read_b128 v[208:211], v193 offset:5120
	ds_read_b128 v[212:215], v193 offset:6144
	ds_read_b128 v[216:219], v193 offset:7168
	global_load_lds_dwordx4 v170, s[44:45]
	s_add_i32 m0, s43, 0xe000
	s_nop 0
	global_load_lds_dwordx4 v168, s[44:45]
	s_waitcnt vmcnt(8)
	s_waitcnt lgkmcnt(0)
	s_barrier
	s_waitcnt lgkmcnt(0)
	v_mfma_f32_16x16x32_f16 v[120:123], v[136:139], v[176:179], v[120:123]
	v_mfma_f32_16x16x32_f16 v[124:127], v[128:131], v[176:179], v[124:127]
	v_mfma_f32_16x16x32_f16 v[104:107], v[136:139], v[184:187], v[104:107]
	v_mfma_f32_16x16x32_f16 v[112:115], v[128:131], v[184:187], v[112:115]
	v_mfma_f32_16x16x32_f16 v[88:91], v[136:139], v[198:201], v[88:91]
	v_mfma_f32_16x16x32_f16 v[96:99], v[128:131], v[198:201], v[96:99]
	v_mfma_f32_16x16x32_f16 v[72:75], v[136:139], v[212:215], v[72:75]
	v_mfma_f32_16x16x32_f16 v[80:83], v[128:131], v[212:215], v[80:83]
	v_mfma_f32_16x16x32_f16 v[120:123], v[140:143], v[180:183], v[120:123]
	v_mfma_f32_16x16x32_f16 v[124:127], v[132:135], v[180:183], v[124:127]
	v_mfma_f32_16x16x32_f16 v[104:107], v[140:143], v[194:197], v[104:107]
	v_mfma_f32_16x16x32_f16 v[112:115], v[132:135], v[194:197], v[112:115]
	v_mfma_f32_16x16x32_f16 v[88:91], v[140:143], v[208:211], v[88:91]
	v_mfma_f32_16x16x32_f16 v[96:99], v[132:135], v[208:211], v[96:99]
	v_mfma_f32_16x16x32_f16 v[72:75], v[140:143], v[216:219], v[72:75]
	v_mfma_f32_16x16x32_f16 v[80:83], v[132:135], v[216:219], v[80:83]
	v_mfma_f32_16x16x32_f16 v[108:111], v[152:155], v[176:179], v[108:111]
	v_mfma_f32_16x16x32_f16 v[116:119], v[144:147], v[176:179], v[116:119]
	v_mfma_f32_16x16x32_f16 v[92:95], v[152:155], v[184:187], v[92:95]
	v_mfma_f32_16x16x32_f16 v[100:103], v[144:147], v[184:187], v[100:103]
	v_mfma_f32_16x16x32_f16 v[76:79], v[152:155], v[198:201], v[76:79]
	v_mfma_f32_16x16x32_f16 v[84:87], v[144:147], v[198:201], v[84:87]
	v_mfma_f32_16x16x32_f16 v[64:67], v[152:155], v[212:215], v[64:67]
	v_mfma_f32_16x16x32_f16 v[68:71], v[144:147], v[212:215], v[68:71]
	v_mfma_f32_16x16x32_f16 v[108:111], v[156:159], v[180:183], v[108:111]
	v_mfma_f32_16x16x32_f16 v[116:119], v[148:151], v[180:183], v[116:119]
	v_mfma_f32_16x16x32_f16 v[92:95], v[156:159], v[194:197], v[92:95]
	v_mfma_f32_16x16x32_f16 v[100:103], v[148:151], v[194:197], v[100:103]
	v_mfma_f32_16x16x32_f16 v[76:79], v[156:159], v[208:211], v[76:79]
	v_mfma_f32_16x16x32_f16 v[84:87], v[148:151], v[208:211], v[84:87]
	v_mfma_f32_16x16x32_f16 v[64:67], v[156:159], v[216:219], v[64:67]
	v_mfma_f32_16x16x32_f16 v[68:71], v[148:151], v[216:219], v[68:71]
	s_barrier
	s_add_i32 s91, s68, s61
	s_add_u32 s98, s48, s18
	s_addc_u32 s99, s49, s19
	s_mov_b32 m0, s91
	ds_read_b128 v[176:179], v193 offset:16384
	ds_read_b128 v[180:183], v193 offset:17408
	ds_read_b128 v[184:187], v193 offset:18432
	ds_read_b128 v[194:197], v193 offset:19456
	ds_read_b128 v[198:201], v193 offset:20480
	ds_read_b128 v[208:211], v193 offset:21504
	ds_read_b128 v[212:215], v193 offset:22528
	ds_read_b128 v[216:219], v193 offset:23552
	global_load_lds_dwordx4 v162, s[48:49]
	s_add_i32 m0, s91, 0x2000
	s_add_u32 s92, s48, 0x80000
	s_addc_u32 s93, s49, 0
	s_add_i32 s91, s69, s61
	global_load_lds_dwordx4 v166, s[48:49]
	s_mov_b32 m0, s91
	s_nop 0
	global_load_lds_dwordx4 v162, s[92:93]
	s_add_i32 m0, s91, 0x2000
	s_nop 0
	global_load_lds_dwordx4 v166, s[92:93]
	s_add_u32 s100, s50, s18
	s_addc_u32 s101, s51, s19
	s_mov_b32 m0, s43
	s_nop 0
	global_load_lds_dwordx4 v160, s[50:51]
	s_mov_b32 m0, s62
	s_nop 0
	global_load_lds_dwordx4 v164, s[50:51]
	s_waitcnt vmcnt(8)
	s_waitcnt lgkmcnt(0)
	s_barrier
	s_waitcnt lgkmcnt(0)
	v_mfma_f32_16x16x32_f16 v[56:59], v[136:139], v[176:179], v[56:59]
	v_mfma_f32_16x16x32_f16 v[60:63], v[128:131], v[176:179], v[60:63]
	v_mfma_f32_16x16x32_f16 v[44:47], v[136:139], v[184:187], v[44:47]
	v_mfma_f32_16x16x32_f16 v[52:55], v[128:131], v[184:187], v[52:55]
	v_mfma_f32_16x16x32_f16 v[28:31], v[136:139], v[198:201], v[28:31]
	v_mfma_f32_16x16x32_f16 v[36:39], v[128:131], v[198:201], v[36:39]
	v_mfma_f32_16x16x32_f16 v[12:15], v[136:139], v[212:215], v[12:15]
	v_mfma_f32_16x16x32_f16 v[20:23], v[128:131], v[212:215], v[20:23]
	v_mfma_f32_16x16x32_f16 v[56:59], v[140:143], v[180:183], v[56:59]
	v_mfma_f32_16x16x32_f16 v[60:63], v[132:135], v[180:183], v[60:63]
	v_mfma_f32_16x16x32_f16 v[44:47], v[140:143], v[194:197], v[44:47]
	v_mfma_f32_16x16x32_f16 v[52:55], v[132:135], v[194:197], v[52:55]
	v_mfma_f32_16x16x32_f16 v[28:31], v[140:143], v[208:211], v[28:31]
	v_mfma_f32_16x16x32_f16 v[36:39], v[132:135], v[208:211], v[36:39]
	v_mfma_f32_16x16x32_f16 v[12:15], v[140:143], v[216:219], v[12:15]
	v_mfma_f32_16x16x32_f16 v[20:23], v[132:135], v[216:219], v[20:23]
	v_mfma_f32_16x16x32_f16 v[40:43], v[152:155], v[176:179], v[40:43]
	v_mfma_f32_16x16x32_f16 v[48:51], v[144:147], v[176:179], v[48:51]
	v_mfma_f32_16x16x32_f16 v[24:27], v[152:155], v[184:187], v[24:27]
	v_mfma_f32_16x16x32_f16 v[32:35], v[144:147], v[184:187], v[32:35]
	v_mfma_f32_16x16x32_f16 v[8:11], v[152:155], v[198:201], v[8:11]
	v_mfma_f32_16x16x32_f16 v[16:19], v[144:147], v[198:201], v[16:19]
	v_mfma_f32_16x16x32_f16 v[0:3], v[152:155], v[212:215], v[0:3]
	v_mfma_f32_16x16x32_f16 v[4:7], v[144:147], v[212:215], v[4:7]
	v_mfma_f32_16x16x32_f16 v[40:43], v[156:159], v[180:183], v[40:43]
	v_mfma_f32_16x16x32_f16 v[48:51], v[148:151], v[180:183], v[48:51]
	v_mfma_f32_16x16x32_f16 v[24:27], v[156:159], v[194:197], v[24:27]
	v_mfma_f32_16x16x32_f16 v[32:35], v[148:151], v[194:197], v[32:35]
	v_mfma_f32_16x16x32_f16 v[8:11], v[156:159], v[208:211], v[8:11]
	v_mfma_f32_16x16x32_f16 v[16:19], v[148:151], v[208:211], v[16:19]
	v_mfma_f32_16x16x32_f16 v[0:3], v[156:159], v[216:219], v[0:3]
	v_mfma_f32_16x16x32_f16 v[4:7], v[148:151], v[216:219], v[4:7]
	s_barrier
; #define PG8_STAGE(bufoff, gbase, voff) do { _Pragma("unroll") for (int _i = 0; _i < 2; ++_i) \
;         __builtin_amdgcn_global_load_lds((const unsigned*)((const char*)(gbase) + (voff)[_i]), (PG8_LAS unsigned*)(lds + (bufoff) + ldsw + _i * 8192), 16, 0, 0); } while (0)
; #define PG8_LDA(dst, b, h) do { _Pragma("unroll") for (int m = 0; m < 4; ++m) _Pragma("unroll") for (int k = 0; k < 2; ++k) dst[m][k] = *(const PG8_LAS bf16x8*)(lds + PG8_SA(b, h) + aoff + m * 2048 + k * 1024); } while (0)
; #define PG8_LDB(dst, b, h) do { _Pragma("unroll") for (int n = 0; n < 2; ++n) _Pragma("unroll") for (int k = 0; k < 2; ++k) dst[n][k] = *(const PG8_LAS bf16x8*)(lds + PG8_SB(b, h) + boff + n * 2048 + k * 1024); } while (0)
; #define PG8_MMA(ai, bj, At, Bt) do { __builtin_amdgcn_s_setprio(1); _Pragma("unroll") for (int m = 0; m < 4; ++m) _Pragma("unroll") for (int n = 0; n < 2; ++n) _Pragma("unroll") for (int k = 0; k < 2; ++k) \
;         acc[ai][bj][m][n] = __builtin_amdgcn_mfma_f32_16x16x32_f16(Bt[n][k], At[m][k], acc[ai][bj][m][n], 0, 0, 0); __builtin_amdgcn_s_setprio(0); } while (0)
; #define PG8_WAIT_V(n) asm volatile("s_waitcnt vmcnt(" #n ")" ::: "memory")
; #define PG8_WAIT_L(n) asm volatile("s_waitcnt lgkmcnt(" #n ")" ::: "memory")
; #define PG8_BAR __builtin_amdgcn_s_barrier()
; #define PG8_SCHED __builtin_amdgcn_sched_barrier(0)
; template <class Epi, class Sched, bool ALIGN_EPI = false, bool SP2 = false>
; __device__ __forceinline__ void gemm_phase(PG8_LAS unsigned char* lds, const Gemm g, const Sched& S, const Epi& E) {
;     ...
;             PG8_LDB(B0, 1, 0); PG8_LDB(B1, 1, 1); PG8_SCHED; PG8_LDA(At, 1, 0); PG8_STAGE(PG8_SA(0, 1), a2 + hstep, voffA);
;             PG8_WAIT_V(8); PG8_WAIT_L(0); PG8_BAR; PG8_MMA(0, 0, At, B0); PG8_MMA(0, 1, At, B1); PG8_BAR; PG8_SCHED;
;             PG8_LDA(At, 1, 1); PG8_STAGE(PG8_SB(1, 0), b3, voffB); PG8_STAGE(PG8_SB(1, 1), b3 + hstep, voffB); PG8_STAGE(PG8_SA(1, 0), a3, voffA);
;             PG8_WAIT_V(8); PG8_WAIT_L(0); PG8_BAR; PG8_MMA(1, 0, At, B0); PG8_MMA(1, 1, At, B1); PG8_BAR; PG8_SCHED;
	s_add_i32 s91, 0, 0x18000
	s_add_i32 s92, 0, 0x1c000
	v_add_u32_e32 v140, s91, v189
	v_add_u32_e32 v156, s92, v189
	ds_read_b128 v[128:131], v140
	ds_read_b128 v[132:135], v140 offset:1024
	ds_read_b128 v[136:139], v140 offset:2048
	ds_read_b128 v[140:143], v140 offset:3072
	ds_read_b128 v[144:147], v156
	ds_read_b128 v[148:151], v156 offset:1024
	ds_read_b128 v[152:155], v156 offset:2048
	ds_read_b128 v[156:159], v156 offset:3072
	s_add_u32 s50, s50, 0x80000
	s_addc_u32 s51, s51, 0
	s_mov_b32 m0, s63
	ds_read_b128 v[176:179], v193 offset:32768
	ds_read_b128 v[180:183], v193 offset:33792
	ds_read_b128 v[184:187], v193 offset:34816
	ds_read_b128 v[194:197], v193 offset:35840
	ds_read_b128 v[198:201], v193 offset:36864
	ds_read_b128 v[208:211], v193 offset:37888
	ds_read_b128 v[212:215], v193 offset:38912
	ds_read_b128 v[216:219], v193 offset:39936
	global_load_lds_dwordx4 v160, s[50:51]
	s_mov_b32 m0, s64
	s_nop 0
	global_load_lds_dwordx4 v164, s[50:51]
	s_waitcnt vmcnt(8)
	s_waitcnt lgkmcnt(0)
	s_barrier
	s_waitcnt lgkmcnt(0)
	v_mfma_f32_16x16x32_f16 v[120:123], v[136:139], v[176:179], v[120:123]
	v_mfma_f32_16x16x32_f16 v[124:127], v[128:131], v[176:179], v[124:127]
	v_mfma_f32_16x16x32_f16 v[104:107], v[136:139], v[184:187], v[104:107]
	v_mfma_f32_16x16x32_f16 v[112:115], v[128:131], v[184:187], v[112:115]
	v_mfma_f32_16x16x32_f16 v[88:91], v[136:139], v[198:201], v[88:91]
	v_mfma_f32_16x16x32_f16 v[96:99], v[128:131], v[198:201], v[96:99]
	v_mfma_f32_16x16x32_f16 v[72:75], v[136:139], v[212:215], v[72:75]
	v_mfma_f32_16x16x32_f16 v[80:83], v[128:131], v[212:215], v[80:83]
	v_mfma_f32_16x16x32_f16 v[120:123], v[140:143], v[180:183], v[120:123]
	v_mfma_f32_16x16x32_f16 v[124:127], v[132:135], v[180:183], v[124:127]
	v_mfma_f32_16x16x32_f16 v[104:107], v[140:143], v[194:197], v[104:107]
	v_mfma_f32_16x16x32_f16 v[112:115], v[132:135], v[194:197], v[112:115]
	v_mfma_f32_16x16x32_f16 v[88:91], v[140:143], v[208:211], v[88:91]
	v_mfma_f32_16x16x32_f16 v[96:99], v[132:135], v[208:211], v[96:99]
	v_mfma_f32_16x16x32_f16 v[72:75], v[140:143], v[216:219], v[72:75]
	v_mfma_f32_16x16x32_f16 v[80:83], v[132:135], v[216:219], v[80:83]
	v_mfma_f32_16x16x32_f16 v[108:111], v[152:155], v[176:179], v[108:111]
	v_mfma_f32_16x16x32_f16 v[116:119], v[144:147], v[176:179], v[116:119]
	v_mfma_f32_16x16x32_f16 v[92:95], v[152:155], v[184:187], v[92:95]
	v_mfma_f32_16x16x32_f16 v[100:103], v[144:147], v[184:187], v[100:103]
	v_mfma_f32_16x16x32_f16 v[76:79], v[152:155], v[198:201], v[76:79]
	v_mfma_f32_16x16x32_f16 v[84:87], v[144:147], v[198:201], v[84:87]
	v_mfma_f32_16x16x32_f16 v[64:67], v[152:155], v[212:215], v[64:67]
	v_mfma_f32_16x16x32_f16 v[68:71], v[144:147], v[212:215], v[68:71]
	v_mfma_f32_16x16x32_f16 v[108:111], v[156:159], v[180:183], v[108:111]
	v_mfma_f32_16x16x32_f16 v[116:119], v[148:151], v[180:183], v[116:119]
	v_mfma_f32_16x16x32_f16 v[92:95], v[156:159], v[194:197], v[92:95]
	v_mfma_f32_16x16x32_f16 v[100:103], v[148:151], v[194:197], v[100:103]
	v_mfma_f32_16x16x32_f16 v[76:79], v[156:159], v[208:211], v[76:79]
	v_mfma_f32_16x16x32_f16 v[84:87], v[148:151], v[208:211], v[84:87]
	v_mfma_f32_16x16x32_f16 v[64:67], v[156:159], v[216:219], v[64:67]
	v_mfma_f32_16x16x32_f16 v[68:71], v[148:151], v[216:219], v[68:71]
	s_barrier
	s_add_i32 s50, s91, s61
	s_mov_b32 m0, s50
	ds_read_b128 v[176:179], v193 offset:49152
	ds_read_b128 v[180:183], v193 offset:50176
	ds_read_b128 v[184:187], v193 offset:51200
	ds_read_b128 v[194:197], v193 offset:52224
	ds_read_b128 v[198:201], v193 offset:53248
	ds_read_b128 v[208:211], v193 offset:54272
	ds_read_b128 v[212:215], v193 offset:55296
	ds_read_b128 v[216:219], v193 offset:56320
	global_load_lds_dwordx4 v162, s[98:99]
	s_add_i32 m0, s50, 0x2000
	s_add_u32 s48, s48, 0x80080
	s_addc_u32 s49, s49, 0
	s_add_i32 s50, s92, s61
	global_load_lds_dwordx4 v166, s[98:99]
	s_mov_b32 m0, s50
	s_nop 0
	global_load_lds_dwordx4 v162, s[48:49]
	s_add_i32 m0, s50, 0x2000
	s_nop 0
	global_load_lds_dwordx4 v166, s[48:49]
	s_mov_b32 m0, s66
	s_nop 0
	global_load_lds_dwordx4 v160, s[100:101]
	s_mov_b32 m0, s67
	s_nop 0
	global_load_lds_dwordx4 v164, s[100:101]
	s_waitcnt vmcnt(8)
	s_waitcnt lgkmcnt(0)
	s_barrier
	s_waitcnt lgkmcnt(0)
	v_mfma_f32_16x16x32_f16 v[56:59], v[136:139], v[176:179], v[56:59]
	v_mfma_f32_16x16x32_f16 v[60:63], v[128:131], v[176:179], v[60:63]
	v_mfma_f32_16x16x32_f16 v[44:47], v[136:139], v[184:187], v[44:47]
	v_mfma_f32_16x16x32_f16 v[52:55], v[128:131], v[184:187], v[52:55]
	v_mfma_f32_16x16x32_f16 v[28:31], v[136:139], v[198:201], v[28:31]
	v_mfma_f32_16x16x32_f16 v[36:39], v[128:131], v[198:201], v[36:39]
	v_mfma_f32_16x16x32_f16 v[12:15], v[136:139], v[212:215], v[12:15]
	v_mfma_f32_16x16x32_f16 v[20:23], v[128:131], v[212:215], v[20:23]
	v_mfma_f32_16x16x32_f16 v[56:59], v[140:143], v[180:183], v[56:59]
	v_mfma_f32_16x16x32_f16 v[60:63], v[132:135], v[180:183], v[60:63]
	v_mfma_f32_16x16x32_f16 v[44:47], v[140:143], v[194:197], v[44:47]
	v_mfma_f32_16x16x32_f16 v[52:55], v[132:135], v[194:197], v[52:55]
	v_mfma_f32_16x16x32_f16 v[28:31], v[140:143], v[208:211], v[28:31]
	v_mfma_f32_16x16x32_f16 v[36:39], v[132:135], v[208:211], v[36:39]
	v_mfma_f32_16x16x32_f16 v[12:15], v[140:143], v[216:219], v[12:15]
	v_mfma_f32_16x16x32_f16 v[20:23], v[132:135], v[216:219], v[20:23]
	v_mfma_f32_16x16x32_f16 v[40:43], v[152:155], v[176:179], v[40:43]
	v_mfma_f32_16x16x32_f16 v[48:51], v[144:147], v[176:179], v[48:51]
	v_mfma_f32_16x16x32_f16 v[24:27], v[152:155], v[184:187], v[24:27]
	v_mfma_f32_16x16x32_f16 v[32:35], v[144:147], v[184:187], v[32:35]
	v_mfma_f32_16x16x32_f16 v[8:11], v[152:155], v[198:201], v[8:11]
	v_mfma_f32_16x16x32_f16 v[16:19], v[144:147], v[198:201], v[16:19]
	v_mfma_f32_16x16x32_f16 v[0:3], v[152:155], v[212:215], v[0:3]
	v_mfma_f32_16x16x32_f16 v[4:7], v[144:147], v[212:215], v[4:7]
	v_mfma_f32_16x16x32_f16 v[40:43], v[156:159], v[180:183], v[40:43]
	v_mfma_f32_16x16x32_f16 v[48:51], v[148:151], v[180:183], v[48:51]
	v_mfma_f32_16x16x32_f16 v[24:27], v[156:159], v[194:197], v[24:27]
	v_mfma_f32_16x16x32_f16 v[32:35], v[148:151], v[194:197], v[32:35]
	v_mfma_f32_16x16x32_f16 v[8:11], v[156:159], v[208:211], v[8:11]
	v_mfma_f32_16x16x32_f16 v[16:19], v[148:151], v[208:211], v[16:19]
	v_mfma_f32_16x16x32_f16 v[0:3], v[156:159], v[216:219], v[0:3]
	v_mfma_f32_16x16x32_f16 v[4:7], v[148:151], v[216:219], v[4:7]
	s_barrier
	s_add_i32 s90, s90, 2
	s_add_u32 s88, s88, 0x100
	s_addc_u32 s89, s89, 0
	s_add_u32 s44, s44, 0x100
	s_addc_u32 s45, s45, 0
	s_cmp_gt_u32 s90, 29
	s_cbranch_scc0 .LBB0_747
	s_and_b64 vcc, exec, s[20:21]
	s_cbranch_vccz .LBB0_750
	s_barrier

; #define PG8_WAIT_V(n) asm volatile("s_waitcnt vmcnt(" #n ")" ::: "memory")
; template <class Epi, class Sched, bool ALIGN_EPI = false, bool SP2 = false>
; __device__ __forceinline__ void gemm_phase(PG8_LAS unsigned char* lds, const Gemm g, const Sched& S, const Epi& E) {
;     ...
;     PG8_WAIT_V(0);
;     if constexpr (!ALIGN_EPI) { if (wr == 0) PG8_BAR; }
;     PG8_BAR;
; __global__ void __launch_bounds__(NWAVES * 64, 2) mega_fwd(Params P) {
;     ...
;     { WS_SETUP TID_SETUP
;             const float* gq = P.in[5]; const float* gkv = P.in[6];
;             for (int row = gw; row < MTOK; row += NGW) {
;                 const h16* hp = H2 + (size_t)row * ODD_INP;
;                 const h8 cq = *(const h8*)(hp + 3072 + 8 * lane); const h4 ck = *(const h4*)(hp + 3584 + 4 * lane);
;                 float xq[8], xk[4], sq = 0.f, sk = 0.f;
; #pragma unroll
;                 for (int e = 0; e < 8; ++e) { xq[e] = (float)cq[e]; sq += xq[e] * xq[e]; }
; #pragma unroll
;                 for (int e = 0; e < 4; ++e) { xk[e] = (float)ck[e]; sk += xk[e] * xk[e]; }
;                 const float rq = 1.f / sqrtf(wave_sum(sq) * (1.f / 512.f) + RMS_EPS), rk = 1.f / sqrtf(wave_sum(sk) * (1.f / 256.f) + RMS_EPS);
;                 const f32x4 g0 = *(const f32x4*)(gq + 8 * lane), g1 = *(const f32x4*)(gq + 8 * lane + 4), g2 = *(const f32x4*)(gkv + 4 * lane);
;                 u32x4 wq; wq.x = pk16(xq[0] * rq * g0.x, xq[1] * rq * g0.y); wq.y = pk16(xq[2] * rq * g0.z, xq[3] * rq * g0.w);
;                 wq.z = pk16(xq[4] * rq * g1.x, xq[5] * rq * g1.y); wq.w = pk16(xq[6] * rq * g1.z, xq[7] * rq * g1.w);
;                 *(u32x4*)(CQN + (size_t)row * 512 + 8 * lane) = wq;
;                 u32x2 wk; wk.x = pk16(xk[0] * rk * g2.x, xk[1] * rk * g2.y); wk.y = pk16(xk[2] * rk * g2.z, xk[3] * rk * g2.w);
;                 *(u32x2*)(CKVN + (size_t)row * 256 + 4 * lane) = wk;
;                 if (lane < 16) { const int pos = row & (SEQ - 1);
;                     const float x1 = (float)*(const _Float16*)(hp + 3840 + lane), x2 = (float)*(const _Float16*)(hp + 3856 + lane);
;                     const float c = ROPE[pos * 32 + lane], s = ROPE[pos * 32 + 16 + lane];
;                     *(_Float16*)(KR + (size_t)row * 32 + lane) = (_Float16)(x1 * c - x2 * s);
;                     *(_Float16*)(KR + (size_t)row * 32 + 16 + lane) = (_Float16)(x1 * s + x2 * c); }
;             }
.LBB0_806:
	s_or_b64 exec, exec, s[0:1]
	s_mov_b64 s[10:11], s[78:79]
	s_mov_b64 s[0:1], s[76:77]
	s_waitcnt lgkmcnt(0)
	s_barrier
	v_mov_b32_e32 v0, v204
	s_setprio 0
	s_nop 0
	v_readfirstlane_b32 s0, v0
	s_ashr_i32 s0, s0, 6
	s_add_i32 s12, s0, s95
	s_cmpk_gt_i32 s12, 0x3fff
	s_cbranch_scc1 .LBB0_811
	v_and_b32_e32 v18, 63, v0
	v_xor_b32_e32 v0, 1, v205
	v_cmp_lt_i32_e32 vcc, v0, v207
	s_add_u32 s14, s10, 0x100000
	v_mov_b32_e32 v1, 0
	v_cndmask_b32_e32 v0, v205, v0, vcc
	v_lshlrev_b32_e32 v19, 2, v0
	v_xor_b32_e32 v0, 2, v205
	v_cmp_lt_i32_e32 vcc, v0, v207
	s_addc_u32 s15, s11, 0
	s_ashr_i32 s13, s12, 31
	v_cndmask_b32_e32 v0, v205, v0, vcc
	v_lshlrev_b32_e32 v20, 2, v0
	v_xor_b32_e32 v0, 4, v205
	v_cmp_lt_i32_e32 vcc, v0, v207
	s_lshl_b64 s[8:9], s[12:13], 6
	v_lshlrev_b32_e32 v12, 1, v18
	v_cndmask_b32_e32 v0, v205, v0, vcc
	v_lshlrev_b32_e32 v21, 2, v0
	v_xor_b32_e32 v0, 8, v205
	v_cmp_lt_i32_e32 vcc, v0, v207
	v_mov_b32_e32 v13, v1
	v_lshlrev_b32_e32 v14, 3, v18
	v_cndmask_b32_e32 v0, v205, v0, vcc
	v_lshlrev_b32_e32 v22, 2, v0
	v_xor_b32_e32 v0, 16, v205
	v_cmp_lt_i32_e32 vcc, v0, v207
	v_lshl_add_u64 v[6:7], s[8:9], 0, v[12:13]
	s_lshl_b64 s[8:9], s[12:13], 9
	v_cndmask_b32_e32 v0, v205, v0, vcc
	v_cmp_lt_i32_e32 vcc, v206, v207
	v_lshlrev_b32_e32 v23, 2, v0
	v_or_b32_e32 v8, s8, v14
	v_cndmask_b32_e32 v0, v205, v206, vcc
	v_lshlrev_b32_e32 v24, 2, v0
	v_lshlrev_b32_e32 v0, 5, v18
	v_mov_b32_e32 v9, s9
	s_mov_b64 s[8:9], 0x18a00000
	v_lshl_add_u64 v[2:3], s[70:71], 0, v[0:1]
	v_lshlrev_b32_e32 v0, 4, v18
	v_lshl_add_u64 v[8:9], v[8:9], 0, s[8:9]
	s_lshl_b64 s[8:9], s[12:13], 10
	v_or_b32_e32 v10, s8, v0
	v_mov_b32_e32 v11, s9
	s_mov_b64 s[8:9], 0x17a00000
	v_lshl_add_u64 v[10:11], v[10:11], 0, s[8:9]
	s_lshl_b64 s[8:9], s[12:13], 13
	s_ashr_i32 s81, s80, 31
	v_or_b32_e32 v12, s8, v12
	v_mov_b32_e32 v13, s9
	v_or_b32_e32 v14, s8, v14
	v_mov_b32_e32 v15, s9
	s_mov_b64 s[24:25], 0xfa01c00
	v_or_b32_e32 v16, s8, v0
	v_mov_b32_e32 v17, s9
	s_mov_b64 s[8:9], 0xfa01800
	s_lshl_b32 s1, s2, 8
	s_lshl_b32 s0, s0, 5
	v_lshl_add_u64 v[4:5], s[72:73], 0, v[0:1]
	v_cmp_gt_u32_e64 s[6:7], 16, v18
	s_lshl_b64 s[16:17], s[80:81], 6
	s_lshl_b64 s[18:19], s[80:81], 9
	s_lshl_b64 s[20:21], s[80:81], 10
	s_lshl_b64 s[22:23], s[80:81], 13
	v_lshl_add_u64 v[14:15], v[14:15], 0, s[24:25]
	v_lshl_add_u64 v[16:17], v[16:17], 0, s[8:9]
	s_add_i32 s3, s1, s0
	s_lshl_b32 s13, s84, 8
	v_mov_b32_e32 v25, 0x358637bd
	s_mov_b32 s24, 0xf800000
	v_mov_b32_e32 v26, 0x260
	s_branch .LBB0_809

; #define PG8_WAIT_V(n) asm volatile("s_waitcnt vmcnt(" #n ")" ::: "memory")
; #define PG8_BAR __builtin_amdgcn_s_barrier()
; template <class Epi, class Sched, bool ALIGN_EPI = false, bool SP2 = false>
; __device__ __forceinline__ void gemm_phase(PG8_LAS unsigned char* lds, const Gemm g, const Sched& S, const Epi& E) {
;     ...
;     const int tid = tid_, wid = __builtin_amdgcn_readfirstlane(tid >> 6), lane = tid & 63, wr = wid >> 2, wc = wid & 3, fr = lane & 15, fq = lane >> 4;
;     const int K = g.K, nt = K / BK;
;     unsigned voffA[2], voffB[2];
; #pragma unroll
;     for (int i = 0; i < 2; ++i) { int R, C; stage_rc(tid * 16 + i * 8192, R, C); const int Rb = E.perm ? ((R & ~31) + perm32(R & 31)) : R;
;         voffA[i] = (unsigned)(R * K + C) * 2u; voffB[i] = (unsigned)(Rb * K + C) * 2u; }
;     const size_t kstep = (size_t)(BK * 2);
;     const size_t hstep = (size_t)HALF * K * 2;
;     const size_t tstep = 2 * hstep;
;     const unsigned ldsw = (unsigned)wid * 1024u;
;     const int aoff = lds_byte(wr * 64 + fr, fq * 8), boff = lds_byte(wc * 32 + fr, fq * 8);
;     ...
;     Unit cur, nxt; int ui = 0;
;     if (!S.next(0, cur)) return;
;     f32x4 acc[2][2][4][2];
; #pragma unroll
;     for (int a = 0; a < 2; ++a)
; #pragma unroll
;         for (int b = 0; b < 2; ++b)
; #pragma unroll
;             for (int m = 0; m < 4; ++m)
; #pragma unroll
;                 for (int n = 0; n < 2; ++n) acc[a][b][m][n] = (f32x4){0.f, 0.f, 0.f, 0.f};
;     bf16x8 At[4][2], B0[2][2], B1[2][2];
;     const char* cA = (const char*)g.A + (size_t)cur.pm * tstep; const char* cB = (const char*)g.Bt + (size_t)cur.pn * tstep;
;     S.a_ready(cur);
;     if constexpr (SP2) {
;         PG8_STAGE(PG8_SB(0, 0), cB, voffB); PG8_STAGE(PG8_SB(0, 1), cB + hstep, voffB); PG8_STAGE(PG8_SA(0, 0), cA, voffA); PG8_STAGE(PG8_SA(0, 1), cA + hstep, voffA);
;         if (wr == 1) PG8_BAR;
;         PG8_WAIT_V(2); PG8_BAR;
;         PG8_STAGE(PG8_SB(1, 0), cB + kstep, voffB); PG8_STAGE(PG8_SA(1, 0), cA + kstep, voffA); PG8_STAGE(PG8_SB(1, 1), cB + hstep + kstep, voffB);
;         PG8_WAIT_V(6); PG8_BAR;
;     } else {
;         PG8_STAGE(PG8_SB(0, 0), cB, voffB); PG8_STAGE(PG8_SA(0, 0), cA, voffA); PG8_STAGE(PG8_SB(0, 1), cB + hstep, voffB); PG8_STAGE(PG8_SA(0, 1), cA + hstep, voffA);
;         if (wr == 1) PG8_BAR;
;         PG8_WAIT_V(4); PG8_BAR;
.Lsprio_skip_6:
	s_waitcnt lgkmcnt(0)
	s_barrier
	s_cmpk_gt_i32 s2, 0x17f
	v_readfirstlane_b32 s17, v8
	s_cbranch_scc1 .LBB0_879
	v_lshlrev_b32_e32 v0, 4, v8
	v_add_u32_e32 v1, 0x2000, v0
	v_ashrrev_i32_e32 v2, 31, v1
	v_lshrrev_b32_e32 v2, 22, v2
	v_add_u32_e32 v2, v1, v2
	v_ashrrev_i32_e32 v9, 10, v2
	v_mul_i32_i24_e32 v3, 0x400, v9
	v_sub_u32_e32 v1, v1, v3
	v_lshrrev_b32_e32 v3, 4, v1
	s_add_u32 s3, s6, 0x17a00000
	v_bitop3_b32 v1, v3, v1, 32 bitop3:0x6c
	s_addc_u32 s34, s7, 0
	v_ashrrev_i32_e32 v3, 31, v1
	s_add_u32 s35, s6, 0x1200000
	v_lshrrev_b32_e32 v3, 26, v3
	s_addc_u32 s36, s7, 0
	v_add_u32_e32 v3, v1, v3
	s_ashr_i32 s38, s2, 31
	v_ashrrev_i32_e32 v10, 6, v3
	v_and_b32_e32 v3, 0xc0, v3
	s_lshr_b32 s0, s38, 29
	v_sub_u32_e32 v1, v1, v3
	v_mov_b32_e32 v3, 1
	s_add_i32 s0, s2, s0
	s_ashr_i32 s14, s17, 6
	v_lshlrev_b32_e32 v2, 5, v9
	v_ashrrev_i16_sdwa v1, v3, sext(v1) dst_sel:DWORD dst_unused:UNUSED_PAD src0_sel:DWORD src1_sel:BYTE_0
	s_ashr_i32 s1, s0, 3
	s_and_b32 s0, s0, -8
	s_ashr_i32 s18, s17, 8
	s_lshl_b32 s37, s14, 10
	v_and_b32_e32 v2, 32, v2
	v_bfe_i32 v11, v1, 0, 16
	s_sub_i32 s0, s2, s0
	v_add_u32_e32 v1, v2, v11
	v_lshlrev_b32_e32 v2, 3, v9
	s_cmp_lt_i32 s0, 0
	v_and_b32_e32 v2, 0x3ffff0, v2
	s_cselect_b32 s8, 49, 48
	v_add_lshl_u32 v2, v10, v2, 10
	s_mul_i32 s0, s0, s8
	v_lshl_add_u32 v168, v1, 1, v2
	v_bfe_i32 v2, v8, 27, 1
	s_add_i32 s0, s0, s1
	v_lshrrev_b32_e32 v2, 22, v2
	s_mul_hi_i32 s1, s0, 0x2aaaaaab
	v_add_u32_e32 v2, v0, v2
	s_lshr_b32 s8, s1, 31
	s_ashr_i32 s1, s1, 2
	v_and_b32_e32 v2, 0xfffffc00, v2
	s_add_i32 s1, s1, s8
	v_sub_u32_e32 v0, v0, v2
	s_lshl_b32 s8, s1, 2
	s_mul_i32 s1, s1, 24
	v_lshrrev_b32_e32 v2, 4, v0
	s_sub_i32 s0, s0, s1
	v_bitop3_b32 v0, v2, v0, 32 bitop3:0x6c
	s_bfe_i32 s1, s0, 0x80000
	v_ashrrev_i32_e32 v2, 31, v0
	s_bfe_u32 s1, s1, 0x2000d
	v_ashrrev_i32_e32 v1, 31, v8
	v_lshrrev_b32_e32 v2, 26, v2
	s_add_i32 s1, s0, s1
	v_lshrrev_b32_e32 v1, 26, v1
	v_add_u32_e32 v2, v0, v2
	s_bfe_i32 s9, s1, 0x80000
	s_and_b32 s1, s1, 0xfc
	v_add_u32_e32 v1, v8, v1
	v_ashrrev_i32_e32 v13, 6, v2
	v_and_b32_e32 v2, 0xc0, v2
	s_sub_i32 s0, s0, s1
	v_ashrrev_i32_e32 v12, 6, v1
	v_sub_u32_e32 v0, v0, v2
	s_sext_i32_i16 s9, s9
	s_sext_i32_i8 s0, s0
	v_lshlrev_b32_e32 v1, 5, v12
	v_ashrrev_i16_sdwa v0, v3, sext(v0) dst_sel:DWORD dst_unused:UNUSED_PAD src0_sel:DWORD src1_sel:BYTE_0
	s_lshr_b32 s16, s9, 2
	s_add_i32 s8, s8, s0
	v_and_b32_e32 v1, 32, v1
	v_bfe_i32 v14, v0, 0, 16
	s_ashr_i32 s9, s8, 31
	s_bfe_i64 s[10:11], s[16:17], 0x100000
	v_add_u32_e32 v0, v1, v14
	v_lshlrev_b32_e32 v1, 3, v12
	s_lshl_b64 s[0:1], s[8:9], 18
	s_lshl_b64 s[10:11], s[10:11], 18
	v_and_b32_e32 v1, 0x3ffff0, v1
	s_add_u32 s26, s35, s10
	v_add_lshl_u32 v1, v13, v1, 10
	s_addc_u32 s27, s36, s11
	s_add_i32 s39, s37, 0
	v_lshl_add_u32 v170, v0, 1, v1
	s_add_i32 m0, s39, 0x10000
	v_mov_b32_e32 v173, 0
	global_load_lds_dwordx4 v170, s[26:27]
	s_add_i32 m0, s39, 0x12000
	s_add_u32 s10, s26, 0x20000
	global_load_lds_dwordx4 v168, s[26:27]
	s_addc_u32 s11, s27, 0
	s_add_i32 m0, s39, 0x14000
	v_mov_b32_e32 v171, v173
	global_load_lds_dwordx4 v170, s[10:11]
	s_add_i32 m0, s39, 0x16000
	s_add_u32 s28, s3, s0
	s_addc_u32 s29, s34, s1
	s_add_i32 s40, s39, 0x2000
	global_load_lds_dwordx4 v168, s[10:11]
	s_mov_b32 m0, s39
	s_add_u32 s0, s28, 0x20000
	global_load_lds_dwordx4 v170, s[28:29]
	s_mov_b32 m0, s40
	s_addc_u32 s1, s29, 0
	s_add_i32 s41, s39, 0x4000
	global_load_lds_dwordx4 v168, s[28:29]
	s_mov_b32 m0, s41
	s_add_i32 s42, s39, 0x6000
	global_load_lds_dwordx4 v170, s[0:1]
	s_mov_b32 m0, s42
	v_mov_b32_e32 v169, v173
	global_load_lds_dwordx4 v168, s[0:1]
	s_cmp_eq_u32 s18, 1
	s_mov_b32 s43, 0
	v_lshl_add_u64 v[6:7], s[26:27], 0, v[170:171]
	v_lshl_add_u64 v[4:5], s[26:27], 0, v[168:169]
	v_lshl_add_u64 v[0:1], s[28:29], 0, v[170:171]
	s_cselect_b64 s[0:1], -1, 0
	s_cmp_lg_u32 s18, 1
	v_lshl_add_u64 v[2:3], s[28:29], 0, v[168:169]
	s_cbranch_scc1 .LBB0_866
	s_barrier

; #define PG8_STAGE(bufoff, gbase, voff) do { _Pragma("unroll") for (int _i = 0; _i < 2; ++_i) \
;         __builtin_amdgcn_global_load_lds((const unsigned*)((const char*)(gbase) + (voff)[_i]), (PG8_LAS unsigned*)(lds + (bufoff) + ldsw + _i * 8192), 16, 0, 0); } while (0)
; #define PG8_LDA(dst, b, h) do { _Pragma("unroll") for (int m = 0; m < 4; ++m) _Pragma("unroll") for (int k = 0; k < 2; ++k) dst[m][k] = *(const PG8_LAS bf16x8*)(lds + PG8_SA(b, h) + aoff + m * 2048 + k * 1024); } while (0)
; #define PG8_LDB(dst, b, h) do { _Pragma("unroll") for (int n = 0; n < 2; ++n) _Pragma("unroll") for (int k = 0; k < 2; ++k) dst[n][k] = *(const PG8_LAS bf16x8*)(lds + PG8_SB(b, h) + boff + n * 2048 + k * 1024); } while (0)
; #define PG8_MMA(ai, bj, At, Bt) do { __builtin_amdgcn_s_setprio(1); _Pragma("unroll") for (int m = 0; m < 4; ++m) _Pragma("unroll") for (int n = 0; n < 2; ++n) _Pragma("unroll") for (int k = 0; k < 2; ++k) \
;         acc[ai][bj][m][n] = __builtin_amdgcn_mfma_f32_16x16x32_f16(Bt[n][k], At[m][k], acc[ai][bj][m][n], 0, 0, 0); __builtin_amdgcn_s_setprio(0); } while (0)
; #define PG8_WAIT_V(n) asm volatile("s_waitcnt vmcnt(" #n ")" ::: "memory")
; #define PG8_WAIT_L(n) asm volatile("s_waitcnt lgkmcnt(" #n ")" ::: "memory")
; #define PG8_BAR __builtin_amdgcn_s_barrier()
; #define PG8_SCHED __builtin_amdgcn_sched_barrier(0)
; template <class Epi, class Sched, bool ALIGN_EPI = false, bool SP2 = false>
; __device__ __forceinline__ void gemm_phase(PG8_LAS unsigned char* lds, const Gemm g, const Sched& S, const Epi& E) {
;     ...
;             PG8_LDB(B0, 0, 0); PG8_LDB(B1, 0, 1); PG8_SCHED; PG8_LDA(At, 0, 0); PG8_STAGE(PG8_SA(1, 1), a1 + hstep, voffA);
;             PG8_WAIT_V(8); PG8_WAIT_L(0); PG8_BAR; PG8_MMA(0, 0, At, B0); PG8_MMA(0, 1, At, B1); PG8_BAR; PG8_SCHED;
;             PG8_LDA(At, 0, 1); PG8_STAGE(PG8_SB(0, 0), b2, voffB); PG8_STAGE(PG8_SB(0, 1), b2 + hstep, voffB); PG8_STAGE(PG8_SA(0, 0), a2, voffA);
;             PG8_WAIT_V(8); PG8_WAIT_L(0); PG8_BAR; PG8_MMA(1, 0, At, B0); PG8_MMA(1, 1, At, B1); PG8_BAR; PG8_SCHED;
.LBB0_872:
	ds_read_b128 v[128:131], v187
	ds_read_b128 v[132:135], v187 offset:1024
	ds_read_b128 v[136:139], v187 offset:2048
	ds_read_b128 v[140:143], v187 offset:3072
	ds_read_b128 v[144:147], v188
	ds_read_b128 v[148:151], v188 offset:1024
	ds_read_b128 v[152:155], v188 offset:2048
	ds_read_b128 v[156:159], v188 offset:3072
	s_add_u32 s28, s26, 0xfffe0080
	s_addc_u32 s29, s27, -1
	s_cmp_eq_u32 s65, 4
	s_cselect_b32 s31, s21, s29
	s_cselect_b32 s30, s61, s28
	s_cselect_b32 s29, s19, s64
	s_cselect_b32 s28, s62, s63
	s_add_i32 m0, s39, 0xc000
	ds_read_b128 v[160:163], v189
	ds_read_b128 v[164:167], v189 offset:1024
	ds_read_b128 v[192:195], v189 offset:2048
	ds_read_b128 v[196:199], v189 offset:3072
	ds_read_b128 v[200:203], v189 offset:4096
	ds_read_b128 v[208:211], v189 offset:5120
	ds_read_b128 v[212:215], v189 offset:6144
	ds_read_b128 v[216:219], v189 offset:7168
	global_load_lds_dwordx4 v178, s[26:27]
	s_add_i32 m0, s39, 0xe000
	s_nop 0
	global_load_lds_dwordx4 v176, s[26:27]
	s_waitcnt vmcnt(8)
	s_waitcnt lgkmcnt(0)
	s_barrier
	s_waitcnt lgkmcnt(0)
	v_mfma_f32_16x16x32_f16 v[120:123], v[136:139], v[160:163], v[120:123]
	v_mfma_f32_16x16x32_f16 v[124:127], v[128:131], v[160:163], v[124:127]
	v_mfma_f32_16x16x32_f16 v[104:107], v[136:139], v[192:195], v[104:107]
	v_mfma_f32_16x16x32_f16 v[108:111], v[128:131], v[192:195], v[108:111]
	v_mfma_f32_16x16x32_f16 v[88:91], v[136:139], v[200:203], v[88:91]
	v_mfma_f32_16x16x32_f16 v[92:95], v[128:131], v[200:203], v[92:95]
	v_mfma_f32_16x16x32_f16 v[72:75], v[136:139], v[212:215], v[72:75]
	v_mfma_f32_16x16x32_f16 v[76:79], v[128:131], v[212:215], v[76:79]
	v_mfma_f32_16x16x32_f16 v[120:123], v[140:143], v[164:167], v[120:123]
	v_mfma_f32_16x16x32_f16 v[124:127], v[132:135], v[164:167], v[124:127]
	v_mfma_f32_16x16x32_f16 v[104:107], v[140:143], v[196:199], v[104:107]
	v_mfma_f32_16x16x32_f16 v[108:111], v[132:135], v[196:199], v[108:111]
	v_mfma_f32_16x16x32_f16 v[88:91], v[140:143], v[208:211], v[88:91]
	v_mfma_f32_16x16x32_f16 v[92:95], v[132:135], v[208:211], v[92:95]
	v_mfma_f32_16x16x32_f16 v[72:75], v[140:143], v[216:219], v[72:75]
	v_mfma_f32_16x16x32_f16 v[76:79], v[132:135], v[216:219], v[76:79]
	v_mfma_f32_16x16x32_f16 v[112:115], v[152:155], v[160:163], v[112:115]
	v_mfma_f32_16x16x32_f16 v[116:119], v[144:147], v[160:163], v[116:119]
	v_mfma_f32_16x16x32_f16 v[96:99], v[152:155], v[192:195], v[96:99]
	v_mfma_f32_16x16x32_f16 v[100:103], v[144:147], v[192:195], v[100:103]
	v_mfma_f32_16x16x32_f16 v[80:83], v[152:155], v[200:203], v[80:83]
	v_mfma_f32_16x16x32_f16 v[84:87], v[144:147], v[200:203], v[84:87]
	v_mfma_f32_16x16x32_f16 v[64:67], v[152:155], v[212:215], v[64:67]
	v_mfma_f32_16x16x32_f16 v[68:71], v[144:147], v[212:215], v[68:71]
	v_mfma_f32_16x16x32_f16 v[112:115], v[156:159], v[164:167], v[112:115]
	v_mfma_f32_16x16x32_f16 v[116:119], v[148:151], v[164:167], v[116:119]
	v_mfma_f32_16x16x32_f16 v[96:99], v[156:159], v[196:199], v[96:99]
	v_mfma_f32_16x16x32_f16 v[100:103], v[148:151], v[196:199], v[100:103]
	v_mfma_f32_16x16x32_f16 v[80:83], v[156:159], v[208:211], v[80:83]
	v_mfma_f32_16x16x32_f16 v[84:87], v[148:151], v[208:211], v[84:87]
	v_mfma_f32_16x16x32_f16 v[64:67], v[156:159], v[216:219], v[64:67]
	v_mfma_f32_16x16x32_f16 v[68:71], v[148:151], v[216:219], v[68:71]
	s_barrier
	s_add_i32 s66, s49, s37
	s_add_u32 s98, s28, s14
	s_addc_u32 s99, s29, s15
	s_mov_b32 m0, s66
	ds_read_b128 v[160:163], v189 offset:16384
	ds_read_b128 v[164:167], v189 offset:17408
	ds_read_b128 v[192:195], v189 offset:18432
	ds_read_b128 v[196:199], v189 offset:19456
	ds_read_b128 v[200:203], v189 offset:20480
	ds_read_b128 v[208:211], v189 offset:21504
	ds_read_b128 v[212:215], v189 offset:22528
	ds_read_b128 v[216:219], v189 offset:23552
	global_load_lds_dwordx4 v170, s[28:29]
	s_add_i32 m0, s66, 0x2000
	s_add_u32 s66, s28, 0x20000
	s_addc_u32 s67, s29, 0
	s_add_i32 s68, s50, s37
	global_load_lds_dwordx4 v168, s[28:29]
	s_mov_b32 m0, s68
	s_nop 0
	global_load_lds_dwordx4 v170, s[66:67]
	s_add_i32 m0, s68, 0x2000
	s_nop 0
	global_load_lds_dwordx4 v168, s[66:67]
	s_add_u32 s100, s30, s14
	s_addc_u32 s101, s31, s15
	s_mov_b32 m0, s39
	s_nop 0
	global_load_lds_dwordx4 v170, s[30:31]
	s_mov_b32 m0, s40
	s_nop 0
	global_load_lds_dwordx4 v168, s[30:31]
	s_waitcnt vmcnt(8)
	s_waitcnt lgkmcnt(0)
	s_barrier
	s_waitcnt lgkmcnt(0)
	v_mfma_f32_16x16x32_f16 v[56:59], v[136:139], v[160:163], v[56:59]
	v_mfma_f32_16x16x32_f16 v[60:63], v[128:131], v[160:163], v[60:63]
	v_mfma_f32_16x16x32_f16 v[40:43], v[136:139], v[192:195], v[40:43]
	v_mfma_f32_16x16x32_f16 v[44:47], v[128:131], v[192:195], v[44:47]
	v_mfma_f32_16x16x32_f16 v[24:27], v[136:139], v[200:203], v[24:27]
	v_mfma_f32_16x16x32_f16 v[28:31], v[128:131], v[200:203], v[28:31]
	v_mfma_f32_16x16x32_f16 v[8:11], v[136:139], v[212:215], v[8:11]
	v_mfma_f32_16x16x32_f16 v[12:15], v[128:131], v[212:215], v[12:15]
	v_mfma_f32_16x16x32_f16 v[56:59], v[140:143], v[164:167], v[56:59]
	v_mfma_f32_16x16x32_f16 v[60:63], v[132:135], v[164:167], v[60:63]
	v_mfma_f32_16x16x32_f16 v[40:43], v[140:143], v[196:199], v[40:43]
	v_mfma_f32_16x16x32_f16 v[44:47], v[132:135], v[196:199], v[44:47]
	v_mfma_f32_16x16x32_f16 v[24:27], v[140:143], v[208:211], v[24:27]
	v_mfma_f32_16x16x32_f16 v[28:31], v[132:135], v[208:211], v[28:31]
	v_mfma_f32_16x16x32_f16 v[8:11], v[140:143], v[216:219], v[8:11]
	v_mfma_f32_16x16x32_f16 v[12:15], v[132:135], v[216:219], v[12:15]
	v_mfma_f32_16x16x32_f16 v[48:51], v[152:155], v[160:163], v[48:51]
	v_mfma_f32_16x16x32_f16 v[52:55], v[144:147], v[160:163], v[52:55]
	v_mfma_f32_16x16x32_f16 v[32:35], v[152:155], v[192:195], v[32:35]
	v_mfma_f32_16x16x32_f16 v[36:39], v[144:147], v[192:195], v[36:39]
	v_mfma_f32_16x16x32_f16 v[16:19], v[152:155], v[200:203], v[16:19]
	v_mfma_f32_16x16x32_f16 v[20:23], v[144:147], v[200:203], v[20:23]
	v_mfma_f32_16x16x32_f16 v[0:3], v[152:155], v[212:215], v[0:3]
	v_mfma_f32_16x16x32_f16 v[4:7], v[144:147], v[212:215], v[4:7]
	v_mfma_f32_16x16x32_f16 v[48:51], v[156:159], v[164:167], v[48:51]
	v_mfma_f32_16x16x32_f16 v[52:55], v[148:151], v[164:167], v[52:55]
	v_mfma_f32_16x16x32_f16 v[32:35], v[156:159], v[196:199], v[32:35]
	v_mfma_f32_16x16x32_f16 v[36:39], v[148:151], v[196:199], v[36:39]
	v_mfma_f32_16x16x32_f16 v[16:19], v[156:159], v[208:211], v[16:19]
	v_mfma_f32_16x16x32_f16 v[20:23], v[148:151], v[208:211], v[20:23]
	v_mfma_f32_16x16x32_f16 v[0:3], v[156:159], v[216:219], v[0:3]
	v_mfma_f32_16x16x32_f16 v[4:7], v[148:151], v[216:219], v[4:7]
	s_barrier
; #define PG8_STAGE(bufoff, gbase, voff) do { _Pragma("unroll") for (int _i = 0; _i < 2; ++_i) \
;         __builtin_amdgcn_global_load_lds((const unsigned*)((const char*)(gbase) + (voff)[_i]), (PG8_LAS unsigned*)(lds + (bufoff) + ldsw + _i * 8192), 16, 0, 0); } while (0)
; #define PG8_LDA(dst, b, h) do { _Pragma("unroll") for (int m = 0; m < 4; ++m) _Pragma("unroll") for (int k = 0; k < 2; ++k) dst[m][k] = *(const PG8_LAS bf16x8*)(lds + PG8_SA(b, h) + aoff + m * 2048 + k * 1024); } while (0)
; #define PG8_LDB(dst, b, h) do { _Pragma("unroll") for (int n = 0; n < 2; ++n) _Pragma("unroll") for (int k = 0; k < 2; ++k) dst[n][k] = *(const PG8_LAS bf16x8*)(lds + PG8_SB(b, h) + boff + n * 2048 + k * 1024); } while (0)
; #define PG8_MMA(ai, bj, At, Bt) do { __builtin_amdgcn_s_setprio(1); _Pragma("unroll") for (int m = 0; m < 4; ++m) _Pragma("unroll") for (int n = 0; n < 2; ++n) _Pragma("unroll") for (int k = 0; k < 2; ++k) \
;         acc[ai][bj][m][n] = __builtin_amdgcn_mfma_f32_16x16x32_f16(Bt[n][k], At[m][k], acc[ai][bj][m][n], 0, 0, 0); __builtin_amdgcn_s_setprio(0); } while (0)
; #define PG8_WAIT_V(n) asm volatile("s_waitcnt vmcnt(" #n ")" ::: "memory")
; #define PG8_WAIT_L(n) asm volatile("s_waitcnt lgkmcnt(" #n ")" ::: "memory")
; #define PG8_BAR __builtin_amdgcn_s_barrier()
; #define PG8_SCHED __builtin_amdgcn_sched_barrier(0)
; template <class Epi, class Sched, bool ALIGN_EPI = false, bool SP2 = false>
; __device__ __forceinline__ void gemm_phase(PG8_LAS unsigned char* lds, const Gemm g, const Sched& S, const Epi& E) {
;     ...
;             PG8_LDB(B0, 1, 0); PG8_LDB(B1, 1, 1); PG8_SCHED; PG8_LDA(At, 1, 0); PG8_STAGE(PG8_SA(0, 1), a2 + hstep, voffA);
;             PG8_WAIT_V(8); PG8_WAIT_L(0); PG8_BAR; PG8_MMA(0, 0, At, B0); PG8_MMA(0, 1, At, B1); PG8_BAR; PG8_SCHED;
;             PG8_LDA(At, 1, 1); PG8_STAGE(PG8_SB(1, 0), b3, voffB); PG8_STAGE(PG8_SB(1, 1), b3 + hstep, voffB); PG8_STAGE(PG8_SA(1, 0), a3, voffA);
;             PG8_WAIT_V(8); PG8_WAIT_L(0); PG8_BAR; PG8_MMA(1, 0, At, B0); PG8_MMA(1, 1, At, B1); PG8_BAR; PG8_SCHED;
	s_add_i32 s66, 0, 0x18000
	s_add_i32 s67, 0, 0x1c000
	v_add_u32_e32 v140, s66, v186
	v_add_u32_e32 v156, s67, v186
	ds_read_b128 v[128:131], v140
	ds_read_b128 v[132:135], v140 offset:1024
	ds_read_b128 v[136:139], v140 offset:2048
	ds_read_b128 v[140:143], v140 offset:3072
	ds_read_b128 v[144:147], v156
	ds_read_b128 v[148:151], v156 offset:1024
	ds_read_b128 v[152:155], v156 offset:2048
	ds_read_b128 v[156:159], v156 offset:3072
	s_add_u32 s30, s30, 0x20000
	s_addc_u32 s31, s31, 0
	s_mov_b32 m0, s41
	ds_read_b128 v[160:163], v189 offset:32768
	ds_read_b128 v[164:167], v189 offset:33792
	ds_read_b128 v[192:195], v189 offset:34816
	ds_read_b128 v[196:199], v189 offset:35840
	ds_read_b128 v[200:203], v189 offset:36864
	ds_read_b128 v[208:211], v189 offset:37888
	ds_read_b128 v[212:215], v189 offset:38912
	ds_read_b128 v[216:219], v189 offset:39936
	global_load_lds_dwordx4 v170, s[30:31]
	s_mov_b32 m0, s42
	s_nop 0
	global_load_lds_dwordx4 v168, s[30:31]
	s_waitcnt vmcnt(8)
	s_waitcnt lgkmcnt(0)
	s_barrier
	s_waitcnt lgkmcnt(0)
	v_mfma_f32_16x16x32_f16 v[120:123], v[136:139], v[160:163], v[120:123]
	v_mfma_f32_16x16x32_f16 v[124:127], v[128:131], v[160:163], v[124:127]
	v_mfma_f32_16x16x32_f16 v[104:107], v[136:139], v[192:195], v[104:107]
	v_mfma_f32_16x16x32_f16 v[108:111], v[128:131], v[192:195], v[108:111]
	v_mfma_f32_16x16x32_f16 v[88:91], v[136:139], v[200:203], v[88:91]
	v_mfma_f32_16x16x32_f16 v[92:95], v[128:131], v[200:203], v[92:95]
	v_mfma_f32_16x16x32_f16 v[72:75], v[136:139], v[212:215], v[72:75]
	v_mfma_f32_16x16x32_f16 v[76:79], v[128:131], v[212:215], v[76:79]
	v_mfma_f32_16x16x32_f16 v[120:123], v[140:143], v[164:167], v[120:123]
	v_mfma_f32_16x16x32_f16 v[124:127], v[132:135], v[164:167], v[124:127]
	v_mfma_f32_16x16x32_f16 v[104:107], v[140:143], v[196:199], v[104:107]
	v_mfma_f32_16x16x32_f16 v[108:111], v[132:135], v[196:199], v[108:111]
	v_mfma_f32_16x16x32_f16 v[88:91], v[140:143], v[208:211], v[88:91]
	v_mfma_f32_16x16x32_f16 v[92:95], v[132:135], v[208:211], v[92:95]
	v_mfma_f32_16x16x32_f16 v[72:75], v[140:143], v[216:219], v[72:75]
	v_mfma_f32_16x16x32_f16 v[76:79], v[132:135], v[216:219], v[76:79]
	v_mfma_f32_16x16x32_f16 v[112:115], v[152:155], v[160:163], v[112:115]
	v_mfma_f32_16x16x32_f16 v[116:119], v[144:147], v[160:163], v[116:119]
	v_mfma_f32_16x16x32_f16 v[96:99], v[152:155], v[192:195], v[96:99]
	v_mfma_f32_16x16x32_f16 v[100:103], v[144:147], v[192:195], v[100:103]
	v_mfma_f32_16x16x32_f16 v[80:83], v[152:155], v[200:203], v[80:83]
	v_mfma_f32_16x16x32_f16 v[84:87], v[144:147], v[200:203], v[84:87]
	v_mfma_f32_16x16x32_f16 v[64:67], v[152:155], v[212:215], v[64:67]
	v_mfma_f32_16x16x32_f16 v[68:71], v[144:147], v[212:215], v[68:71]
	v_mfma_f32_16x16x32_f16 v[112:115], v[156:159], v[164:167], v[112:115]
	v_mfma_f32_16x16x32_f16 v[116:119], v[148:151], v[164:167], v[116:119]
	v_mfma_f32_16x16x32_f16 v[96:99], v[156:159], v[196:199], v[96:99]
	v_mfma_f32_16x16x32_f16 v[100:103], v[148:151], v[196:199], v[100:103]
	v_mfma_f32_16x16x32_f16 v[80:83], v[156:159], v[208:211], v[80:83]
	v_mfma_f32_16x16x32_f16 v[84:87], v[148:151], v[208:211], v[84:87]
	v_mfma_f32_16x16x32_f16 v[64:67], v[156:159], v[216:219], v[64:67]
	v_mfma_f32_16x16x32_f16 v[68:71], v[148:151], v[216:219], v[68:71]
	s_barrier
	s_add_i32 s30, s66, s37
	s_mov_b32 m0, s30
	ds_read_b128 v[160:163], v189 offset:49152
	ds_read_b128 v[164:167], v189 offset:50176
	ds_read_b128 v[192:195], v189 offset:51200
	ds_read_b128 v[196:199], v189 offset:52224
	ds_read_b128 v[200:203], v189 offset:53248
	ds_read_b128 v[208:211], v189 offset:54272
	ds_read_b128 v[212:215], v189 offset:55296
	ds_read_b128 v[216:219], v189 offset:56320
	global_load_lds_dwordx4 v170, s[98:99]
	s_add_i32 m0, s30, 0x2000
	s_add_u32 s28, s28, 0x20080
	s_addc_u32 s29, s29, 0
	s_add_i32 s30, s67, s37
	global_load_lds_dwordx4 v168, s[98:99]
	s_mov_b32 m0, s30
	s_nop 0
	global_load_lds_dwordx4 v170, s[28:29]
	s_add_i32 m0, s30, 0x2000
	s_nop 0
	global_load_lds_dwordx4 v168, s[28:29]
	s_mov_b32 m0, s45
	s_nop 0
	global_load_lds_dwordx4 v170, s[100:101]
	s_mov_b32 m0, s48
	s_nop 0
	global_load_lds_dwordx4 v168, s[100:101]
	s_waitcnt vmcnt(8)
	s_waitcnt lgkmcnt(0)
	s_barrier
	s_waitcnt lgkmcnt(0)
	v_mfma_f32_16x16x32_f16 v[56:59], v[136:139], v[160:163], v[56:59]
	v_mfma_f32_16x16x32_f16 v[60:63], v[128:131], v[160:163], v[60:63]
	v_mfma_f32_16x16x32_f16 v[40:43], v[136:139], v[192:195], v[40:43]
	v_mfma_f32_16x16x32_f16 v[44:47], v[128:131], v[192:195], v[44:47]
	v_mfma_f32_16x16x32_f16 v[24:27], v[136:139], v[200:203], v[24:27]
	v_mfma_f32_16x16x32_f16 v[28:31], v[128:131], v[200:203], v[28:31]
	v_mfma_f32_16x16x32_f16 v[8:11], v[136:139], v[212:215], v[8:11]
	v_mfma_f32_16x16x32_f16 v[12:15], v[128:131], v[212:215], v[12:15]
	v_mfma_f32_16x16x32_f16 v[56:59], v[140:143], v[164:167], v[56:59]
	v_mfma_f32_16x16x32_f16 v[60:63], v[132:135], v[164:167], v[60:63]
	v_mfma_f32_16x16x32_f16 v[40:43], v[140:143], v[196:199], v[40:43]
	v_mfma_f32_16x16x32_f16 v[44:47], v[132:135], v[196:199], v[44:47]
	v_mfma_f32_16x16x32_f16 v[24:27], v[140:143], v[208:211], v[24:27]
	v_mfma_f32_16x16x32_f16 v[28:31], v[132:135], v[208:211], v[28:31]
	v_mfma_f32_16x16x32_f16 v[8:11], v[140:143], v[216:219], v[8:11]
	v_mfma_f32_16x16x32_f16 v[12:15], v[132:135], v[216:219], v[12:15]
	v_mfma_f32_16x16x32_f16 v[48:51], v[152:155], v[160:163], v[48:51]
	v_mfma_f32_16x16x32_f16 v[52:55], v[144:147], v[160:163], v[52:55]
	v_mfma_f32_16x16x32_f16 v[32:35], v[152:155], v[192:195], v[32:35]
	v_mfma_f32_16x16x32_f16 v[36:39], v[144:147], v[192:195], v[36:39]
	v_mfma_f32_16x16x32_f16 v[16:19], v[152:155], v[200:203], v[16:19]
	v_mfma_f32_16x16x32_f16 v[20:23], v[144:147], v[200:203], v[20:23]
	v_mfma_f32_16x16x32_f16 v[0:3], v[152:155], v[212:215], v[0:3]
	v_mfma_f32_16x16x32_f16 v[4:7], v[144:147], v[212:215], v[4:7]
	v_mfma_f32_16x16x32_f16 v[48:51], v[156:159], v[164:167], v[48:51]
	v_mfma_f32_16x16x32_f16 v[52:55], v[148:151], v[164:167], v[52:55]
	v_mfma_f32_16x16x32_f16 v[32:35], v[156:159], v[196:199], v[32:35]
	v_mfma_f32_16x16x32_f16 v[36:39], v[148:151], v[196:199], v[36:39]
	v_mfma_f32_16x16x32_f16 v[16:19], v[156:159], v[208:211], v[16:19]
	v_mfma_f32_16x16x32_f16 v[20:23], v[148:151], v[208:211], v[20:23]
	v_mfma_f32_16x16x32_f16 v[0:3], v[156:159], v[216:219], v[0:3]
	v_mfma_f32_16x16x32_f16 v[4:7], v[148:151], v[216:219], v[4:7]
	s_barrier
	s_add_i32 s65, s65, 2
	s_add_u32 s63, s63, 0x100
	s_addc_u32 s64, s64, 0
	s_add_u32 s26, s26, 0x100
	s_addc_u32 s27, s27, 0
	s_cmp_gt_u32 s65, 5
	s_cbranch_scc0 .LBB0_872
	s_and_b64 vcc, exec, s[16:17]
	s_cbranch_vccz .LBB0_875
	s_barrier

; #define WS_SETUP unsigned char* ws = P.ws; asm volatile("" : "+s"(ws)); float* R = P.out; asm volatile("" : "+s"(R)); (void)R;
; __global__ void __launch_bounds__(NWAVES * 64, 2) mega_fwd(Params P) {
;     ...
;     { WS_SETUP pg8::Gemm g{CKVN, (const h16*)(ws + WS_W_UKV), MTOK, UKV_N, 256}; pg8::EpiAny<0, 0> E{}; E.O = KV; E.ldc = UKV_N;
;       pg8::StaticOrder S; S.init(MTOK, UKV_N, G, (int)blockIdx.x, WGM_SMALL);
;       pg8::gemm_phase<pg8::EpiAny<0, 0>, pg8::StaticOrder, true, true>(lds, g, S, E); }
.LBB0_879:
	s_mov_b64 s[6:7], s[78:79]
	s_mov_b64 s[0:1], s[76:77]
	v_mov_b32_e32 v8, v204
	s_setprio 0
	v_readfirstlane_b32 s98, v204
	s_lshr_b32 s98, s98, 8
	s_cmp_lg_u32 s98, 0
	s_cbranch_scc0 .Lsprio_skip_7
	s_setprio 1
.Lsprio_skip_7:
	s_and_b64 vcc, exec, s[4:5]
	v_readfirstlane_b32 s13, v8
	s_cbranch_vccnz .LBB0_903
	s_ashr_i32 s3, s2, 31
	s_lshr_b32 s0, s3, 29
	s_add_i32 s9, s2, s0
	s_and_b32 s0, s9, -8
	s_sub_i32 s10, s2, s0
	s_cmp_gt_i32 s10, -1
	s_cbranch_scc0 .LBB0_882
	s_lshl_b32 s8, s10, 6
	s_cbranch_execz .LBB0_883
	s_branch .LBB0_884

; #define LAS __attribute__((address_space(3)))
; #define WS_SETUP unsigned char* ws = P.ws; asm volatile("" : "+s"(ws)); float* R = P.out; asm volatile("" : "+s"(R)); (void)R;
; template <int NC, bool SB>
; __device__ __forceinline__ void attn_task(const AttnArgs& a, LAS unsigned char* vl, int lane, f32x16 (&o)[2], float& lse2) {
;     static_assert(NC == 4, "the per-wave task handles 64-wide heads");
;     constexpr int VP = 144, KP = 144;
;     const int r32 = lane & 31, hi = lane >> 5;
;     h8 qf[4];
;     { const h16* qp = a.q + (long)(a.q0 + r32) * a.qstride + 8 * hi;
; #pragma unroll
;       for (int c = 0; c < 4; ++c) qf[c] = *(const h8*)(qp + 16 * c); }
; #pragma unroll
;     for (int r = 0; r < 16; ++r) { o[0][r] = 0.f; o[1][r] = 0.f; }
;     float m = a.sink2, l = (a.sink2 > -1e30f) ? 1.f : 0.f, carry = 0.f;
;     const int vrow = lane >> 3, vcc = lane & 7;
;     const int q4 = (lane & 15) >> 2, p4 = lane & 3, dblk = (lane >> 4) & 1;
;     LAS unsigned char* vrd = vl + (4 * hi + q4) * VP + dblk * 32 + p4 * 8;
;     LAS unsigned char* kl = vl + 32 * VP;
; __global__ void __launch_bounds__(NWAVES * 64, 2) mega_fwd(Params P) {
;     ...
;     { WS_SETUP TID_SETUP
;             for (int T = gw; T < 8192; T += NGW) {
;                 const int b = T >> 10, h = (T >> 6) & 15, qb = T & 63;
;                 AttnArgs a; f32x16 o[2]; float lse2;
;                 a.q0 = qb * 32; a.kt_hi = qb; a.kt_lo = 0; a.rmax = 1 << 30; a.slope2 = 0.f; a.sink2 = -INFINITY;
;                 const h16* base = H2 + (size_t)(b * SEQ) * ODD_INP + h * 64;
;                 a.q = base; a.k = base + 1024; a.v = base + 2048; a.qstride = a.kstride = a.vstride = ODD_INP; a.k2 = nullptr; a.k2stride = 0; a.c1 = 0.125f;
;                 attn_task<4, true>(a, wlds, lane, o, lse2);
;                 store_o16(o, Y2 + (size_t)(b * SEQ + a.q0 + (lane & 31)) * DM + h * 64, lane >> 5);
.LBB0_955:
	s_or_b64 exec, exec, s[0:1]
	s_mov_b64 s[48:49], s[78:79]
	s_mov_b64 s[0:1], s[76:77]
	s_waitcnt lgkmcnt(0)
	s_barrier
	v_mov_b32_e32 v0, v204
	s_setprio 0
	s_nop 0
	v_readfirstlane_b32 s1, v0
	s_ashr_i32 s0, s1, 6
	s_add_i32 s3, s0, s95
	s_cmpk_gt_i32 s3, 0x1fff
	s_cbranch_scc1 .LBB0_967
	s_lshl_b32 s0, s0, 14
	v_bfe_u32 v3, v0, 5, 1
	s_lshr_b32 s1, s1, 6
	s_add_i32 s0, s0, 0
	v_lshrrev_b32_e32 v6, 2, v0
	v_lshlrev_b32_e32 v4, 2, v3
	s_add_u32 s67, s48, 0xfa00000
	v_and_b32_e32 v160, 31, v0
	v_and_or_b32 v6, v6, 3, v4
	v_lshlrev_b32_e32 v7, 1, v0
	v_and_b32_e32 v1, 63, v0
	s_addc_u32 s70, s49, 0
	v_bfe_u32 v161, v0, 3, 3
	v_and_b32_e32 v5, 7, v0
	s_movk_i32 s6, 0x90
	v_mul_u32_u24_e32 v6, 0x90, v6
	v_and_b32_e32 v7, 32, v7
	v_lshlrev_b32_e32 v0, 3, v0
	v_mov_b32_e32 v8, s0
	v_sub_u32_e32 v9, v160, v4
	v_lshlrev_b32_e32 v2, 3, v3
	v_mov_b32_e32 v145, 0
	v_add3_u32 v6, s0, v6, v7
	v_and_b32_e32 v7, 24, v0
	v_lshlrev_b32_e32 v0, 3, v5
	v_lshl_add_u32 v5, v5, 4, s0
	v_mad_u32_u24 v8, v160, s6, v8
	v_lshlrev_b32_e32 v3, 4, v3
	v_cmp_gt_u32_e64 s[6:7], 32, v1
	v_mul_u32_u24_e32 v1, 0x90, v161
	v_cmp_lt_i32_e64 s[8:9], 1, v9
	v_cmp_lt_i32_e64 s[10:11], 0, v9
	v_cmp_lt_i32_e64 s[12:13], 3, v9
	v_cmp_lt_i32_e64 s[14:15], 2, v9
	v_cmp_lt_i32_e64 s[16:17], 9, v9
	v_cmp_lt_i32_e64 s[18:19], 8, v9
	v_cmp_lt_i32_e64 s[20:21], 11, v9
	v_cmp_lt_i32_e64 s[22:23], 10, v9
	v_cmp_lt_i32_e64 s[24:25], 17, v9
	v_cmp_lt_i32_e64 s[26:27], 16, v9
	v_cmp_lt_i32_e64 s[28:29], 19, v9
	v_cmp_lt_i32_e64 s[30:31], 18, v9
	v_cmp_lt_i32_e64 s[34:35], 25, v9
	v_cmp_lt_i32_e64 s[36:37], 24, v9
	v_cmp_lt_i32_e64 s[38:39], 27, v9
	v_cmp_lt_i32_e64 s[40:41], 26, v9
	s_add_u32 s60, s48, 0xba00000
	v_lshlrev_b32_e32 v9, 12, v161
	s_mov_b32 s51, 0
	v_or_b32_e32 v162, 0xffffffa0, v161
	s_addc_u32 s61, s49, 0
	s_add_i32 s71, s95, s1
	s_lshl_b32 s72, s84, 3
	v_lshlrev_b32_e32 v146, 1, v2
	v_mov_b32_e32 v147, v145
	v_lshlrev_b32_e32 v148, 1, v0
	v_mov_b32_e32 v149, v145
	s_mov_b64 s[62:63], 0x800
	s_mov_b64 s[64:65], 0x1000
	v_lshlrev_b32_e32 v163, 1, v9
	s_mov_b32 s66, 0x3e000000
	s_mov_b32 s73, 0xbfb8aa3b
	s_mov_b32 s74, 0x800000
	s_mov_b32 s75, 0x3f317217
	s_mov_b32 s81, 0x7f800000
	s_mov_b32 s82, 0x42200000
	v_lshlrev_b32_e32 v150, 1, v4
	v_add_u32_e32 v164, v5, v1
	v_add_u32_e32 v165, v8, v3
	v_mov_b32_e32 v166, 0x41b17218
	v_mov_b32_e32 v167, 0xff800000
	v_add_u32_e32 v168, v6, v7
	s_branch .LBB0_958

; __device__ __forceinline__ void mla_phase(const h16* Q2, const h16* KV, const h16* KR, h16* Y2, LAS unsigned char* lds, int G) {
;     ...
;     for (int slot = ((gridDim.x % 8 == 0) ? (int)((blockIdx.x % 8) * (gridDim.x / 8) + blockIdx.x / 8) : (int)blockIdx.x); slot < 256; slot += G) {
;         for (int ui = 0; ui < 4; ++ui) {
; __global__ void __launch_bounds__(NWAVES * 64, 2) mega_fwd(Params P) {
;     ...
;             __syncthreads();
;             mla_phase(Q2, KV, KR, Y2, lds, G);
.LBB0_967:
	v_readlane_b32 s0, v234, 6
	v_mov_b32_e32 v0, v204
	s_setprio 0
	v_readlane_b32 s1, v234, 7
	s_waitcnt lgkmcnt(0)
	s_barrier
	s_andn2_b64 vcc, exec, s[0:1]
	v_readfirstlane_b32 s0, v0
	s_cbranch_vccz .LBB0_969
	s_cmpk_gt_i32 s33, 0xff
	s_cbranch_scc0 .LBB0_970
	s_branch .LBB0_1004

; #define PG8_STAGE(bufoff, gbase, voff) do { _Pragma("unroll") for (int _i = 0; _i < 2; ++_i) \
;         __builtin_amdgcn_global_load_lds((const unsigned*)((const char*)(gbase) + (voff)[_i]), (PG8_LAS unsigned*)(lds + (bufoff) + ldsw + _i * 8192), 16, 0, 0); } while (0)
; #define PG8_LDA(dst, b, h) do { _Pragma("unroll") for (int m = 0; m < 4; ++m) _Pragma("unroll") for (int k = 0; k < 2; ++k) dst[m][k] = *(const PG8_LAS bf16x8*)(lds + PG8_SA(b, h) + aoff + m * 2048 + k * 1024); } while (0)
; #define PG8_LDB(dst, b, h) do { _Pragma("unroll") for (int n = 0; n < 2; ++n) _Pragma("unroll") for (int k = 0; k < 2; ++k) dst[n][k] = *(const PG8_LAS bf16x8*)(lds + PG8_SB(b, h) + boff + n * 2048 + k * 1024); } while (0)
; #define PG8_MMA(ai, bj, At, Bt) do { __builtin_amdgcn_s_setprio(1); _Pragma("unroll") for (int m = 0; m < 4; ++m) _Pragma("unroll") for (int n = 0; n < 2; ++n) _Pragma("unroll") for (int k = 0; k < 2; ++k) \
;         acc[ai][bj][m][n] = __builtin_amdgcn_mfma_f32_16x16x32_f16(Bt[n][k], At[m][k], acc[ai][bj][m][n], 0, 0, 0); __builtin_amdgcn_s_setprio(0); } while (0)
; #define PG8_WAIT_V(n) asm volatile("s_waitcnt vmcnt(" #n ")" ::: "memory")
; #define PG8_WAIT_L(n) asm volatile("s_waitcnt lgkmcnt(" #n ")" ::: "memory")
; #define PG8_BAR __builtin_amdgcn_s_barrier()
; #define PG8_SCHED __builtin_amdgcn_sched_barrier(0)
; template <class Epi, class Sched, bool ALIGN_EPI = false, bool SP2 = false>
; __device__ __forceinline__ void gemm_phase(PG8_LAS unsigned char* lds, const Gemm g, const Sched& S, const Epi& E) {
;     ...
;             PG8_LDB(B0, 0, 0); PG8_LDB(B1, 0, 1); PG8_SCHED; PG8_LDA(At, 0, 0); PG8_STAGE(PG8_SA(1, 1), a1 + hstep, voffA);
;             PG8_WAIT_V(8); PG8_WAIT_L(0); PG8_BAR; PG8_MMA(0, 0, At, B0); PG8_MMA(0, 1, At, B1); PG8_BAR; PG8_SCHED;
;             PG8_LDA(At, 0, 1); PG8_STAGE(PG8_SB(0, 0), b2, voffB); PG8_STAGE(PG8_SB(0, 1), b2 + hstep, voffB); PG8_STAGE(PG8_SA(0, 0), a2, voffA);
;             PG8_WAIT_V(8); PG8_WAIT_L(0); PG8_BAR; PG8_MMA(1, 0, At, B0); PG8_MMA(1, 1, At, B1); PG8_BAR; PG8_SCHED;
.LBB0_1075:
	ds_read_b128 v[128:131], v211
	ds_read_b128 v[132:135], v211 offset:1024
	ds_read_b128 v[136:139], v211 offset:2048
	ds_read_b128 v[140:143], v211 offset:3072
	ds_read_b128 v[144:147], v212
	ds_read_b128 v[148:151], v212 offset:1024
	ds_read_b128 v[152:155], v212 offset:2048
	ds_read_b128 v[156:159], v212 offset:3072
	s_add_u32 s42, s40, 0xfff80080
	s_addc_u32 s43, s41, -1
	s_cmp_eq_u32 s70, 28
	s_cselect_b32 s45, s29, s43
	s_cselect_b32 s44, s37, s42
	s_cselect_b32 s43, s27, s69
	s_cselect_b32 s42, s67, s68
	s_add_i32 m0, s39, 0xc000
	ds_read_b128 v[160:163], v213
	ds_read_b128 v[164:167], v213 offset:1024
	ds_read_b128 v[184:187], v213 offset:2048
	ds_read_b128 v[188:191], v213 offset:3072
	ds_read_b128 v[192:195], v213 offset:4096
	ds_read_b128 v[196:199], v213 offset:5120
	ds_read_b128 v[200:203], v213 offset:6144
	ds_read_b128 v[214:217], v213 offset:7168
	global_load_lds_dwordx4 v178, s[40:41]
	s_add_i32 m0, s39, 0xe000
	s_nop 0
	global_load_lds_dwordx4 v176, s[40:41]
	s_waitcnt vmcnt(8)
	s_waitcnt lgkmcnt(0)
	s_barrier
	s_waitcnt lgkmcnt(0)
	v_mfma_f32_16x16x32_f16 v[120:123], v[136:139], v[160:163], v[120:123]
	v_mfma_f32_16x16x32_f16 v[124:127], v[128:131], v[160:163], v[124:127]
	v_mfma_f32_16x16x32_f16 v[104:107], v[136:139], v[184:187], v[104:107]
	v_mfma_f32_16x16x32_f16 v[108:111], v[128:131], v[184:187], v[108:111]
	v_mfma_f32_16x16x32_f16 v[88:91], v[136:139], v[192:195], v[88:91]
	v_mfma_f32_16x16x32_f16 v[92:95], v[128:131], v[192:195], v[92:95]
	v_mfma_f32_16x16x32_f16 v[72:75], v[136:139], v[200:203], v[72:75]
	v_mfma_f32_16x16x32_f16 v[76:79], v[128:131], v[200:203], v[76:79]
	v_mfma_f32_16x16x32_f16 v[120:123], v[140:143], v[164:167], v[120:123]
	v_mfma_f32_16x16x32_f16 v[124:127], v[132:135], v[164:167], v[124:127]
	v_mfma_f32_16x16x32_f16 v[104:107], v[140:143], v[188:191], v[104:107]
	v_mfma_f32_16x16x32_f16 v[108:111], v[132:135], v[188:191], v[108:111]
	v_mfma_f32_16x16x32_f16 v[88:91], v[140:143], v[196:199], v[88:91]
	v_mfma_f32_16x16x32_f16 v[92:95], v[132:135], v[196:199], v[92:95]
	v_mfma_f32_16x16x32_f16 v[72:75], v[140:143], v[214:217], v[72:75]
	v_mfma_f32_16x16x32_f16 v[76:79], v[132:135], v[214:217], v[76:79]
	v_mfma_f32_16x16x32_f16 v[112:115], v[152:155], v[160:163], v[112:115]
	v_mfma_f32_16x16x32_f16 v[116:119], v[144:147], v[160:163], v[116:119]
	v_mfma_f32_16x16x32_f16 v[96:99], v[152:155], v[184:187], v[96:99]
	v_mfma_f32_16x16x32_f16 v[100:103], v[144:147], v[184:187], v[100:103]
	v_mfma_f32_16x16x32_f16 v[80:83], v[152:155], v[192:195], v[80:83]
	v_mfma_f32_16x16x32_f16 v[84:87], v[144:147], v[192:195], v[84:87]
	v_mfma_f32_16x16x32_f16 v[64:67], v[152:155], v[200:203], v[64:67]
	v_mfma_f32_16x16x32_f16 v[68:71], v[144:147], v[200:203], v[68:71]
	v_mfma_f32_16x16x32_f16 v[112:115], v[156:159], v[164:167], v[112:115]
	v_mfma_f32_16x16x32_f16 v[116:119], v[148:151], v[164:167], v[116:119]
	v_mfma_f32_16x16x32_f16 v[96:99], v[156:159], v[188:191], v[96:99]
	v_mfma_f32_16x16x32_f16 v[100:103], v[148:151], v[188:191], v[100:103]
	v_mfma_f32_16x16x32_f16 v[80:83], v[156:159], v[196:199], v[80:83]
	v_mfma_f32_16x16x32_f16 v[84:87], v[148:151], v[196:199], v[84:87]
	v_mfma_f32_16x16x32_f16 v[64:67], v[156:159], v[214:217], v[64:67]
	v_mfma_f32_16x16x32_f16 v[68:71], v[148:151], v[214:217], v[68:71]
	s_barrier
	s_add_i32 s71, s64, s48
	s_add_u32 s98, s42, s18
	s_addc_u32 s99, s43, s19
	s_mov_b32 m0, s71
	ds_read_b128 v[160:163], v213 offset:16384
	ds_read_b128 v[164:167], v213 offset:17408
	ds_read_b128 v[184:187], v213 offset:18432
	ds_read_b128 v[188:191], v213 offset:19456
	ds_read_b128 v[192:195], v213 offset:20480
	ds_read_b128 v[196:199], v213 offset:21504
	ds_read_b128 v[200:203], v213 offset:22528
	ds_read_b128 v[214:217], v213 offset:23552
	global_load_lds_dwordx4 v170, s[42:43]
	s_add_i32 m0, s71, 0x2000
	s_add_u32 s72, s42, 0x80000
	s_addc_u32 s73, s43, 0
	s_add_i32 s71, s65, s48
	global_load_lds_dwordx4 v174, s[42:43]
	s_mov_b32 m0, s71
	s_nop 0
	global_load_lds_dwordx4 v170, s[72:73]
	s_add_i32 m0, s71, 0x2000
	s_nop 0
	global_load_lds_dwordx4 v174, s[72:73]
	s_add_u32 s100, s44, s18
	s_addc_u32 s101, s45, s19
	s_mov_b32 m0, s39
	s_nop 0
	global_load_lds_dwordx4 v168, s[44:45]
	s_mov_b32 m0, s49
	s_nop 0
	global_load_lds_dwordx4 v172, s[44:45]
	s_waitcnt vmcnt(8)
	s_waitcnt lgkmcnt(0)
	s_barrier
	s_waitcnt lgkmcnt(0)
	v_mfma_f32_16x16x32_f16 v[56:59], v[136:139], v[160:163], v[56:59]
	v_mfma_f32_16x16x32_f16 v[60:63], v[128:131], v[160:163], v[60:63]
	v_mfma_f32_16x16x32_f16 v[40:43], v[136:139], v[184:187], v[40:43]
	v_mfma_f32_16x16x32_f16 v[44:47], v[128:131], v[184:187], v[44:47]
	v_mfma_f32_16x16x32_f16 v[24:27], v[136:139], v[192:195], v[24:27]
	v_mfma_f32_16x16x32_f16 v[28:31], v[128:131], v[192:195], v[28:31]
	v_mfma_f32_16x16x32_f16 v[8:11], v[136:139], v[200:203], v[8:11]
	v_mfma_f32_16x16x32_f16 v[12:15], v[128:131], v[200:203], v[12:15]
	v_mfma_f32_16x16x32_f16 v[56:59], v[140:143], v[164:167], v[56:59]
	v_mfma_f32_16x16x32_f16 v[60:63], v[132:135], v[164:167], v[60:63]
	v_mfma_f32_16x16x32_f16 v[40:43], v[140:143], v[188:191], v[40:43]
	v_mfma_f32_16x16x32_f16 v[44:47], v[132:135], v[188:191], v[44:47]
	v_mfma_f32_16x16x32_f16 v[24:27], v[140:143], v[196:199], v[24:27]
	v_mfma_f32_16x16x32_f16 v[28:31], v[132:135], v[196:199], v[28:31]
	v_mfma_f32_16x16x32_f16 v[8:11], v[140:143], v[214:217], v[8:11]
	v_mfma_f32_16x16x32_f16 v[12:15], v[132:135], v[214:217], v[12:15]
	v_mfma_f32_16x16x32_f16 v[48:51], v[152:155], v[160:163], v[48:51]
	v_mfma_f32_16x16x32_f16 v[52:55], v[144:147], v[160:163], v[52:55]
	v_mfma_f32_16x16x32_f16 v[32:35], v[152:155], v[184:187], v[32:35]
	v_mfma_f32_16x16x32_f16 v[36:39], v[144:147], v[184:187], v[36:39]
	v_mfma_f32_16x16x32_f16 v[16:19], v[152:155], v[192:195], v[16:19]
	v_mfma_f32_16x16x32_f16 v[20:23], v[144:147], v[192:195], v[20:23]
	v_mfma_f32_16x16x32_f16 v[0:3], v[152:155], v[200:203], v[0:3]
	v_mfma_f32_16x16x32_f16 v[4:7], v[144:147], v[200:203], v[4:7]
	v_mfma_f32_16x16x32_f16 v[48:51], v[156:159], v[164:167], v[48:51]
	v_mfma_f32_16x16x32_f16 v[52:55], v[148:151], v[164:167], v[52:55]
	v_mfma_f32_16x16x32_f16 v[32:35], v[156:159], v[188:191], v[32:35]
	v_mfma_f32_16x16x32_f16 v[36:39], v[148:151], v[188:191], v[36:39]
	v_mfma_f32_16x16x32_f16 v[16:19], v[156:159], v[196:199], v[16:19]
	v_mfma_f32_16x16x32_f16 v[20:23], v[148:151], v[196:199], v[20:23]
	v_mfma_f32_16x16x32_f16 v[0:3], v[156:159], v[214:217], v[0:3]
	v_mfma_f32_16x16x32_f16 v[4:7], v[148:151], v[214:217], v[4:7]
	s_barrier
; #define PG8_STAGE(bufoff, gbase, voff) do { _Pragma("unroll") for (int _i = 0; _i < 2; ++_i) \
;         __builtin_amdgcn_global_load_lds((const unsigned*)((const char*)(gbase) + (voff)[_i]), (PG8_LAS unsigned*)(lds + (bufoff) + ldsw + _i * 8192), 16, 0, 0); } while (0)
; #define PG8_LDA(dst, b, h) do { _Pragma("unroll") for (int m = 0; m < 4; ++m) _Pragma("unroll") for (int k = 0; k < 2; ++k) dst[m][k] = *(const PG8_LAS bf16x8*)(lds + PG8_SA(b, h) + aoff + m * 2048 + k * 1024); } while (0)
; #define PG8_LDB(dst, b, h) do { _Pragma("unroll") for (int n = 0; n < 2; ++n) _Pragma("unroll") for (int k = 0; k < 2; ++k) dst[n][k] = *(const PG8_LAS bf16x8*)(lds + PG8_SB(b, h) + boff + n * 2048 + k * 1024); } while (0)
; #define PG8_MMA(ai, bj, At, Bt) do { __builtin_amdgcn_s_setprio(1); _Pragma("unroll") for (int m = 0; m < 4; ++m) _Pragma("unroll") for (int n = 0; n < 2; ++n) _Pragma("unroll") for (int k = 0; k < 2; ++k) \
;         acc[ai][bj][m][n] = __builtin_amdgcn_mfma_f32_16x16x32_f16(Bt[n][k], At[m][k], acc[ai][bj][m][n], 0, 0, 0); __builtin_amdgcn_s_setprio(0); } while (0)
; #define PG8_WAIT_V(n) asm volatile("s_waitcnt vmcnt(" #n ")" ::: "memory")
; #define PG8_WAIT_L(n) asm volatile("s_waitcnt lgkmcnt(" #n ")" ::: "memory")
; #define PG8_BAR __builtin_amdgcn_s_barrier()
; #define PG8_SCHED __builtin_amdgcn_sched_barrier(0)
; template <class Epi, class Sched, bool ALIGN_EPI = false, bool SP2 = false>
; __device__ __forceinline__ void gemm_phase(PG8_LAS unsigned char* lds, const Gemm g, const Sched& S, const Epi& E) {
;     ...
;             PG8_LDB(B0, 1, 0); PG8_LDB(B1, 1, 1); PG8_SCHED; PG8_LDA(At, 1, 0); PG8_STAGE(PG8_SA(0, 1), a2 + hstep, voffA);
;             PG8_WAIT_V(8); PG8_WAIT_L(0); PG8_BAR; PG8_MMA(0, 0, At, B0); PG8_MMA(0, 1, At, B1); PG8_BAR; PG8_SCHED;
;             PG8_LDA(At, 1, 1); PG8_STAGE(PG8_SB(1, 0), b3, voffB); PG8_STAGE(PG8_SB(1, 1), b3 + hstep, voffB); PG8_STAGE(PG8_SA(1, 0), a3, voffA);
;             PG8_WAIT_V(8); PG8_WAIT_L(0); PG8_BAR; PG8_MMA(1, 0, At, B0); PG8_MMA(1, 1, At, B1); PG8_BAR; PG8_SCHED;
	s_add_i32 s71, 0, 0x18000
	s_add_i32 s72, 0, 0x1c000
	v_add_u32_e32 v140, s71, v209
	v_add_u32_e32 v156, s72, v209
	ds_read_b128 v[128:131], v140
	ds_read_b128 v[132:135], v140 offset:1024
	ds_read_b128 v[136:139], v140 offset:2048
	ds_read_b128 v[140:143], v140 offset:3072
	ds_read_b128 v[144:147], v156
	ds_read_b128 v[148:151], v156 offset:1024
	ds_read_b128 v[152:155], v156 offset:2048
	ds_read_b128 v[156:159], v156 offset:3072
	s_add_u32 s44, s44, 0x80000
	s_addc_u32 s45, s45, 0
	s_mov_b32 m0, s50
	ds_read_b128 v[160:163], v213 offset:32768
	ds_read_b128 v[164:167], v213 offset:33792
	ds_read_b128 v[184:187], v213 offset:34816
	ds_read_b128 v[188:191], v213 offset:35840
	ds_read_b128 v[192:195], v213 offset:36864
	ds_read_b128 v[196:199], v213 offset:37888
	ds_read_b128 v[200:203], v213 offset:38912
	ds_read_b128 v[214:217], v213 offset:39936
	global_load_lds_dwordx4 v168, s[44:45]
	s_mov_b32 m0, s51
	s_nop 0
	global_load_lds_dwordx4 v172, s[44:45]
	s_waitcnt vmcnt(8)
	s_waitcnt lgkmcnt(0)
	s_barrier
	s_waitcnt lgkmcnt(0)
	v_mfma_f32_16x16x32_f16 v[120:123], v[136:139], v[160:163], v[120:123]
	v_mfma_f32_16x16x32_f16 v[124:127], v[128:131], v[160:163], v[124:127]
	v_mfma_f32_16x16x32_f16 v[104:107], v[136:139], v[184:187], v[104:107]
	v_mfma_f32_16x16x32_f16 v[108:111], v[128:131], v[184:187], v[108:111]
	v_mfma_f32_16x16x32_f16 v[88:91], v[136:139], v[192:195], v[88:91]
	v_mfma_f32_16x16x32_f16 v[92:95], v[128:131], v[192:195], v[92:95]
	v_mfma_f32_16x16x32_f16 v[72:75], v[136:139], v[200:203], v[72:75]
	v_mfma_f32_16x16x32_f16 v[76:79], v[128:131], v[200:203], v[76:79]
	v_mfma_f32_16x16x32_f16 v[120:123], v[140:143], v[164:167], v[120:123]
	v_mfma_f32_16x16x32_f16 v[124:127], v[132:135], v[164:167], v[124:127]
	v_mfma_f32_16x16x32_f16 v[104:107], v[140:143], v[188:191], v[104:107]
	v_mfma_f32_16x16x32_f16 v[108:111], v[132:135], v[188:191], v[108:111]
	v_mfma_f32_16x16x32_f16 v[88:91], v[140:143], v[196:199], v[88:91]
	v_mfma_f32_16x16x32_f16 v[92:95], v[132:135], v[196:199], v[92:95]
	v_mfma_f32_16x16x32_f16 v[72:75], v[140:143], v[214:217], v[72:75]
	v_mfma_f32_16x16x32_f16 v[76:79], v[132:135], v[214:217], v[76:79]
	v_mfma_f32_16x16x32_f16 v[112:115], v[152:155], v[160:163], v[112:115]
	v_mfma_f32_16x16x32_f16 v[116:119], v[144:147], v[160:163], v[116:119]
	v_mfma_f32_16x16x32_f16 v[96:99], v[152:155], v[184:187], v[96:99]
	v_mfma_f32_16x16x32_f16 v[100:103], v[144:147], v[184:187], v[100:103]
	v_mfma_f32_16x16x32_f16 v[80:83], v[152:155], v[192:195], v[80:83]
	v_mfma_f32_16x16x32_f16 v[84:87], v[144:147], v[192:195], v[84:87]
	v_mfma_f32_16x16x32_f16 v[64:67], v[152:155], v[200:203], v[64:67]
	v_mfma_f32_16x16x32_f16 v[68:71], v[144:147], v[200:203], v[68:71]
	v_mfma_f32_16x16x32_f16 v[112:115], v[156:159], v[164:167], v[112:115]
	v_mfma_f32_16x16x32_f16 v[116:119], v[148:151], v[164:167], v[116:119]
	v_mfma_f32_16x16x32_f16 v[96:99], v[156:159], v[188:191], v[96:99]
	v_mfma_f32_16x16x32_f16 v[100:103], v[148:151], v[188:191], v[100:103]
	v_mfma_f32_16x16x32_f16 v[80:83], v[156:159], v[196:199], v[80:83]
	v_mfma_f32_16x16x32_f16 v[84:87], v[148:151], v[196:199], v[84:87]
	v_mfma_f32_16x16x32_f16 v[64:67], v[156:159], v[214:217], v[64:67]
	v_mfma_f32_16x16x32_f16 v[68:71], v[148:151], v[214:217], v[68:71]
	s_barrier
	s_add_i32 s44, s71, s48
	s_mov_b32 m0, s44
	ds_read_b128 v[160:163], v213 offset:49152
	ds_read_b128 v[164:167], v213 offset:50176
	ds_read_b128 v[184:187], v213 offset:51200
	ds_read_b128 v[188:191], v213 offset:52224
	ds_read_b128 v[192:195], v213 offset:53248
	ds_read_b128 v[196:199], v213 offset:54272
	ds_read_b128 v[200:203], v213 offset:55296
	ds_read_b128 v[214:217], v213 offset:56320
	global_load_lds_dwordx4 v170, s[98:99]
	s_add_i32 m0, s44, 0x2000
	s_add_u32 s42, s42, 0x80080
	s_addc_u32 s43, s43, 0
	s_add_i32 s44, s72, s48
	global_load_lds_dwordx4 v174, s[98:99]
	s_mov_b32 m0, s44
	s_nop 0
	global_load_lds_dwordx4 v170, s[42:43]
	s_add_i32 m0, s44, 0x2000
	s_nop 0
	global_load_lds_dwordx4 v174, s[42:43]
	s_mov_b32 m0, s61
	s_nop 0
	global_load_lds_dwordx4 v168, s[100:101]
	s_mov_b32 m0, s62
	s_nop 0
	global_load_lds_dwordx4 v172, s[100:101]
	s_waitcnt vmcnt(8)
	s_waitcnt lgkmcnt(0)
	s_barrier
	s_waitcnt lgkmcnt(0)
	v_mfma_f32_16x16x32_f16 v[56:59], v[136:139], v[160:163], v[56:59]
	v_mfma_f32_16x16x32_f16 v[60:63], v[128:131], v[160:163], v[60:63]
	v_mfma_f32_16x16x32_f16 v[40:43], v[136:139], v[184:187], v[40:43]
	v_mfma_f32_16x16x32_f16 v[44:47], v[128:131], v[184:187], v[44:47]
	v_mfma_f32_16x16x32_f16 v[24:27], v[136:139], v[192:195], v[24:27]
	v_mfma_f32_16x16x32_f16 v[28:31], v[128:131], v[192:195], v[28:31]
	v_mfma_f32_16x16x32_f16 v[8:11], v[136:139], v[200:203], v[8:11]
	v_mfma_f32_16x16x32_f16 v[12:15], v[128:131], v[200:203], v[12:15]
	v_mfma_f32_16x16x32_f16 v[56:59], v[140:143], v[164:167], v[56:59]
	v_mfma_f32_16x16x32_f16 v[60:63], v[132:135], v[164:167], v[60:63]
	v_mfma_f32_16x16x32_f16 v[40:43], v[140:143], v[188:191], v[40:43]
	v_mfma_f32_16x16x32_f16 v[44:47], v[132:135], v[188:191], v[44:47]
	v_mfma_f32_16x16x32_f16 v[24:27], v[140:143], v[196:199], v[24:27]
	v_mfma_f32_16x16x32_f16 v[28:31], v[132:135], v[196:199], v[28:31]
	v_mfma_f32_16x16x32_f16 v[8:11], v[140:143], v[214:217], v[8:11]
	v_mfma_f32_16x16x32_f16 v[12:15], v[132:135], v[214:217], v[12:15]
	v_mfma_f32_16x16x32_f16 v[48:51], v[152:155], v[160:163], v[48:51]
	v_mfma_f32_16x16x32_f16 v[52:55], v[144:147], v[160:163], v[52:55]
	v_mfma_f32_16x16x32_f16 v[32:35], v[152:155], v[184:187], v[32:35]
	v_mfma_f32_16x16x32_f16 v[36:39], v[144:147], v[184:187], v[36:39]
	v_mfma_f32_16x16x32_f16 v[16:19], v[152:155], v[192:195], v[16:19]
	v_mfma_f32_16x16x32_f16 v[20:23], v[144:147], v[192:195], v[20:23]
	v_mfma_f32_16x16x32_f16 v[0:3], v[152:155], v[200:203], v[0:3]
	v_mfma_f32_16x16x32_f16 v[4:7], v[144:147], v[200:203], v[4:7]
	v_mfma_f32_16x16x32_f16 v[48:51], v[156:159], v[164:167], v[48:51]
	v_mfma_f32_16x16x32_f16 v[52:55], v[148:151], v[164:167], v[52:55]
	v_mfma_f32_16x16x32_f16 v[32:35], v[156:159], v[188:191], v[32:35]
	v_mfma_f32_16x16x32_f16 v[36:39], v[148:151], v[188:191], v[36:39]
	v_mfma_f32_16x16x32_f16 v[16:19], v[156:159], v[196:199], v[16:19]
	v_mfma_f32_16x16x32_f16 v[20:23], v[148:151], v[196:199], v[20:23]
	v_mfma_f32_16x16x32_f16 v[0:3], v[156:159], v[214:217], v[0:3]
	v_mfma_f32_16x16x32_f16 v[4:7], v[148:151], v[214:217], v[4:7]
	s_barrier
	s_add_i32 s70, s70, 2
	s_add_u32 s68, s68, 0x100
	s_addc_u32 s69, s69, 0
	s_add_u32 s40, s40, 0x100
	s_addc_u32 s41, s41, 0
	s_cmp_gt_u32 s70, 29
	s_cbranch_scc0 .LBB0_1075
	s_and_b64 vcc, exec, s[20:21]
	s_cbranch_vccz .LBB0_1078
	s_barrier

; #define WS_SETUP unsigned char* ws = P.ws; asm volatile("" : "+s"(ws)); float* R = P.out; asm volatile("" : "+s"(R)); (void)R;
;     __host__ __device__ bool next(int i, Unit& u) const {
;     ...
;         int wgid = (int)L; { const int q = nwg / NXCD, r = nwg % NXCD, xcd = wgid % NXCD, off = wgid / NXCD; wgid = (xcd < r ? xcd * (q + 1) : r * (q + 1) + (xcd - r) * q) + off; }
;         const int nig = wgm * nN, gid = wgid / nig, fm = gid * wgm, gsz = (nM - fm) < wgm ? (nM - fm) : wgm;
;         u.pm = fm + ((wgid % nig) % gsz); u.pn = (wgid % nig) / gsz; return true;
; __global__ void __launch_bounds__(NWAVES * 64, 2) mega_fwd(Params P) {
;     ...
;     { WS_SETUP pg8::Gemm g{KV, (const h16*)(ws + WS_W_W1B), MTOK, DFF, DM}; pg8::EpiAny<1, 1> E{}; E.O = HID; E.ldc = DFF; E.st_in = STATS + 4 * MTOK; E.c1 = C1 + 12288; E.c2 = C2 + 12288;
;       pg8::StaticOrder S; S.init(MTOK, DFF, G, (int)blockIdx.x, WGM_UP);
;       pg8::gemm_phase<pg8::EpiAny<1, 1>, pg8::StaticOrder, true, true>(lds, g, S, E); }
.Lsprio_skip_9:
	s_waitcnt lgkmcnt(0)
	s_barrier
	s_andn2_b64 vcc, exec, s[52:53]
	v_readfirstlane_b32 s19, v8
	s_cbranch_vccnz .LBB0_1174
	s_ashr_i32 s3, s2, 31
	s_lshr_b32 s0, s3, 29
	s_add_i32 s9, s2, s0
	s_and_b32 s0, s9, -8
	s_sub_i32 s10, s2, s0
	s_cmp_gt_i32 s10, -1
	s_cbranch_scc0 .LBB0_1153
	s_lshl_b32 s8, s10, 8
	s_cbranch_execz .LBB0_1154
	s_branch .LBB0_1155

; #define PG8_STAGE(bufoff, gbase, voff) do { _Pragma("unroll") for (int _i = 0; _i < 2; ++_i) \
;         __builtin_amdgcn_global_load_lds((const unsigned*)((const char*)(gbase) + (voff)[_i]), (PG8_LAS unsigned*)(lds + (bufoff) + ldsw + _i * 8192), 16, 0, 0); } while (0)
; #define PG8_LDA(dst, b, h) do { _Pragma("unroll") for (int m = 0; m < 4; ++m) _Pragma("unroll") for (int k = 0; k < 2; ++k) dst[m][k] = *(const PG8_LAS bf16x8*)(lds + PG8_SA(b, h) + aoff + m * 2048 + k * 1024); } while (0)
; #define PG8_LDB(dst, b, h) do { _Pragma("unroll") for (int n = 0; n < 2; ++n) _Pragma("unroll") for (int k = 0; k < 2; ++k) dst[n][k] = *(const PG8_LAS bf16x8*)(lds + PG8_SB(b, h) + boff + n * 2048 + k * 1024); } while (0)
; #define PG8_MMA(ai, bj, At, Bt) do { __builtin_amdgcn_s_setprio(1); _Pragma("unroll") for (int m = 0; m < 4; ++m) _Pragma("unroll") for (int n = 0; n < 2; ++n) _Pragma("unroll") for (int k = 0; k < 2; ++k) \
;         acc[ai][bj][m][n] = __builtin_amdgcn_mfma_f32_16x16x32_f16(Bt[n][k], At[m][k], acc[ai][bj][m][n], 0, 0, 0); __builtin_amdgcn_s_setprio(0); } while (0)
; #define PG8_WAIT_V(n) asm volatile("s_waitcnt vmcnt(" #n ")" ::: "memory")
; #define PG8_WAIT_L(n) asm volatile("s_waitcnt lgkmcnt(" #n ")" ::: "memory")
; #define PG8_BAR __builtin_amdgcn_s_barrier()
; #define PG8_SCHED __builtin_amdgcn_sched_barrier(0)
; template <class Epi, class Sched, bool ALIGN_EPI = false, bool SP2 = false>
; __device__ __forceinline__ void gemm_phase(PG8_LAS unsigned char* lds, const Gemm g, const Sched& S, const Epi& E) {
;     ...
;             PG8_LDB(B0, 0, 0); PG8_LDB(B1, 0, 1); PG8_SCHED; PG8_LDA(At, 0, 0); PG8_STAGE(PG8_SA(1, 1), a1 + hstep, voffA);
;             PG8_WAIT_V(8); PG8_WAIT_L(0); PG8_BAR; PG8_MMA(0, 0, At, B0); PG8_MMA(0, 1, At, B1); PG8_BAR; PG8_SCHED;
;             PG8_LDA(At, 0, 1); PG8_STAGE(PG8_SB(0, 0), b2, voffB); PG8_STAGE(PG8_SB(0, 1), b2 + hstep, voffB); PG8_STAGE(PG8_SA(0, 0), a2, voffA);
;             PG8_WAIT_V(8); PG8_WAIT_L(0); PG8_BAR; PG8_MMA(1, 0, At, B0); PG8_MMA(1, 1, At, B1); PG8_BAR; PG8_SCHED;
.LBB0_1167:
	ds_read_b128 v[128:131], v198
	ds_read_b128 v[132:135], v198 offset:1024
	ds_read_b128 v[136:139], v198 offset:2048
	ds_read_b128 v[140:143], v198 offset:3072
	ds_read_b128 v[144:147], v199
	ds_read_b128 v[148:151], v199 offset:1024
	ds_read_b128 v[152:155], v199 offset:2048
	ds_read_b128 v[156:159], v199 offset:3072
	s_add_u32 s44, s42, 0xfff80080
	s_addc_u32 s45, s43, -1
	s_cmp_eq_u32 s81, 28
	s_cselect_b32 s49, s35, s45
	s_cselect_b32 s48, s72, s44
	s_cselect_b32 s45, s31, s75
	s_cselect_b32 s44, s73, s74
	s_add_i32 m0, s41, 0xc000
	ds_read_b128 v[176:179], v200
	ds_read_b128 v[180:183], v200 offset:1024
	ds_read_b128 v[184:187], v200 offset:2048
	ds_read_b128 v[188:191], v200 offset:3072
	ds_read_b128 v[208:211], v200 offset:4096
	ds_read_b128 v[212:215], v200 offset:5120
	ds_read_b128 v[216:219], v200 offset:6144
	ds_read_b128 v[220:223], v200 offset:7168
	global_load_lds_dwordx4 v170, s[42:43]
	s_add_i32 m0, s41, 0xe000
	s_nop 0
	global_load_lds_dwordx4 v168, s[42:43]
	s_waitcnt vmcnt(8)
	s_waitcnt lgkmcnt(0)
	s_barrier
	s_waitcnt lgkmcnt(0)
	v_mfma_f32_16x16x32_f16 v[120:123], v[136:139], v[176:179], v[120:123]
	v_mfma_f32_16x16x32_f16 v[124:127], v[128:131], v[176:179], v[124:127]
	v_mfma_f32_16x16x32_f16 v[104:107], v[136:139], v[184:187], v[104:107]
	v_mfma_f32_16x16x32_f16 v[108:111], v[128:131], v[184:187], v[108:111]
	v_mfma_f32_16x16x32_f16 v[88:91], v[136:139], v[208:211], v[88:91]
	v_mfma_f32_16x16x32_f16 v[92:95], v[128:131], v[208:211], v[92:95]
	v_mfma_f32_16x16x32_f16 v[72:75], v[136:139], v[216:219], v[72:75]
	v_mfma_f32_16x16x32_f16 v[76:79], v[128:131], v[216:219], v[76:79]
	v_mfma_f32_16x16x32_f16 v[120:123], v[140:143], v[180:183], v[120:123]
	v_mfma_f32_16x16x32_f16 v[124:127], v[132:135], v[180:183], v[124:127]
	v_mfma_f32_16x16x32_f16 v[104:107], v[140:143], v[188:191], v[104:107]
	v_mfma_f32_16x16x32_f16 v[108:111], v[132:135], v[188:191], v[108:111]
	v_mfma_f32_16x16x32_f16 v[88:91], v[140:143], v[212:215], v[88:91]
	v_mfma_f32_16x16x32_f16 v[92:95], v[132:135], v[212:215], v[92:95]
	v_mfma_f32_16x16x32_f16 v[72:75], v[140:143], v[220:223], v[72:75]
	v_mfma_f32_16x16x32_f16 v[76:79], v[132:135], v[220:223], v[76:79]
	v_mfma_f32_16x16x32_f16 v[112:115], v[152:155], v[176:179], v[112:115]
	v_mfma_f32_16x16x32_f16 v[116:119], v[144:147], v[176:179], v[116:119]
	v_mfma_f32_16x16x32_f16 v[96:99], v[152:155], v[184:187], v[96:99]
	v_mfma_f32_16x16x32_f16 v[100:103], v[144:147], v[184:187], v[100:103]
	v_mfma_f32_16x16x32_f16 v[80:83], v[152:155], v[208:211], v[80:83]
	v_mfma_f32_16x16x32_f16 v[84:87], v[144:147], v[208:211], v[84:87]
	v_mfma_f32_16x16x32_f16 v[64:67], v[152:155], v[216:219], v[64:67]
	v_mfma_f32_16x16x32_f16 v[68:71], v[144:147], v[216:219], v[68:71]
	v_mfma_f32_16x16x32_f16 v[112:115], v[156:159], v[180:183], v[112:115]
	v_mfma_f32_16x16x32_f16 v[116:119], v[148:151], v[180:183], v[116:119]
	v_mfma_f32_16x16x32_f16 v[96:99], v[156:159], v[188:191], v[96:99]
	v_mfma_f32_16x16x32_f16 v[100:103], v[148:151], v[188:191], v[100:103]
	v_mfma_f32_16x16x32_f16 v[80:83], v[156:159], v[212:215], v[80:83]
	v_mfma_f32_16x16x32_f16 v[84:87], v[148:151], v[212:215], v[84:87]
	v_mfma_f32_16x16x32_f16 v[64:67], v[156:159], v[220:223], v[64:67]
	v_mfma_f32_16x16x32_f16 v[68:71], v[148:151], v[220:223], v[68:71]
	s_barrier
	s_add_i32 s82, s65, s52
	s_add_u32 s98, s44, s16
	s_addc_u32 s99, s45, s17
	s_mov_b32 m0, s82
	ds_read_b128 v[176:179], v200 offset:16384
	ds_read_b128 v[180:183], v200 offset:17408
	ds_read_b128 v[184:187], v200 offset:18432
	ds_read_b128 v[188:191], v200 offset:19456
	ds_read_b128 v[208:211], v200 offset:20480
	ds_read_b128 v[212:215], v200 offset:21504
	ds_read_b128 v[216:219], v200 offset:22528
	ds_read_b128 v[220:223], v200 offset:23552
	global_load_lds_dwordx4 v162, s[44:45]
	s_add_i32 m0, s82, 0x2000
	s_add_u32 s82, s44, 0x80000
	s_addc_u32 s83, s45, 0
	s_add_i32 s86, s66, s52
	global_load_lds_dwordx4 v166, s[44:45]
	s_mov_b32 m0, s86
	s_nop 0
	global_load_lds_dwordx4 v162, s[82:83]
	s_add_i32 m0, s86, 0x2000
	s_nop 0
	global_load_lds_dwordx4 v166, s[82:83]
	s_add_u32 s100, s48, s16
	s_addc_u32 s101, s49, s17
	s_mov_b32 m0, s41
	s_nop 0
	global_load_lds_dwordx4 v160, s[48:49]
	s_mov_b32 m0, s53
	s_nop 0
	global_load_lds_dwordx4 v164, s[48:49]
	s_waitcnt vmcnt(8)
	s_waitcnt lgkmcnt(0)
	s_barrier
	s_waitcnt lgkmcnt(0)
	v_mfma_f32_16x16x32_f16 v[56:59], v[136:139], v[176:179], v[56:59]
	v_mfma_f32_16x16x32_f16 v[60:63], v[128:131], v[176:179], v[60:63]
	v_mfma_f32_16x16x32_f16 v[40:43], v[136:139], v[184:187], v[40:43]
	v_mfma_f32_16x16x32_f16 v[44:47], v[128:131], v[184:187], v[44:47]
	v_mfma_f32_16x16x32_f16 v[24:27], v[136:139], v[208:211], v[24:27]
	v_mfma_f32_16x16x32_f16 v[28:31], v[128:131], v[208:211], v[28:31]
	v_mfma_f32_16x16x32_f16 v[8:11], v[136:139], v[216:219], v[8:11]
	v_mfma_f32_16x16x32_f16 v[12:15], v[128:131], v[216:219], v[12:15]
	v_mfma_f32_16x16x32_f16 v[56:59], v[140:143], v[180:183], v[56:59]
	v_mfma_f32_16x16x32_f16 v[60:63], v[132:135], v[180:183], v[60:63]
	v_mfma_f32_16x16x32_f16 v[40:43], v[140:143], v[188:191], v[40:43]
	v_mfma_f32_16x16x32_f16 v[44:47], v[132:135], v[188:191], v[44:47]
	v_mfma_f32_16x16x32_f16 v[24:27], v[140:143], v[212:215], v[24:27]
	v_mfma_f32_16x16x32_f16 v[28:31], v[132:135], v[212:215], v[28:31]
	v_mfma_f32_16x16x32_f16 v[8:11], v[140:143], v[220:223], v[8:11]
	v_mfma_f32_16x16x32_f16 v[12:15], v[132:135], v[220:223], v[12:15]
	v_mfma_f32_16x16x32_f16 v[48:51], v[152:155], v[176:179], v[48:51]
	v_mfma_f32_16x16x32_f16 v[52:55], v[144:147], v[176:179], v[52:55]
	v_mfma_f32_16x16x32_f16 v[32:35], v[152:155], v[184:187], v[32:35]
	v_mfma_f32_16x16x32_f16 v[36:39], v[144:147], v[184:187], v[36:39]
	v_mfma_f32_16x16x32_f16 v[16:19], v[152:155], v[208:211], v[16:19]
	v_mfma_f32_16x16x32_f16 v[20:23], v[144:147], v[208:211], v[20:23]
	v_mfma_f32_16x16x32_f16 v[0:3], v[152:155], v[216:219], v[0:3]
	v_mfma_f32_16x16x32_f16 v[4:7], v[144:147], v[216:219], v[4:7]
	v_mfma_f32_16x16x32_f16 v[48:51], v[156:159], v[180:183], v[48:51]
	v_mfma_f32_16x16x32_f16 v[52:55], v[148:151], v[180:183], v[52:55]
	v_mfma_f32_16x16x32_f16 v[32:35], v[156:159], v[188:191], v[32:35]
	v_mfma_f32_16x16x32_f16 v[36:39], v[148:151], v[188:191], v[36:39]
	v_mfma_f32_16x16x32_f16 v[16:19], v[156:159], v[212:215], v[16:19]
	v_mfma_f32_16x16x32_f16 v[20:23], v[148:151], v[212:215], v[20:23]
	v_mfma_f32_16x16x32_f16 v[0:3], v[156:159], v[220:223], v[0:3]
	v_mfma_f32_16x16x32_f16 v[4:7], v[148:151], v[220:223], v[4:7]
	s_barrier
; #define PG8_STAGE(bufoff, gbase, voff) do { _Pragma("unroll") for (int _i = 0; _i < 2; ++_i) \
;         __builtin_amdgcn_global_load_lds((const unsigned*)((const char*)(gbase) + (voff)[_i]), (PG8_LAS unsigned*)(lds + (bufoff) + ldsw + _i * 8192), 16, 0, 0); } while (0)
; #define PG8_LDA(dst, b, h) do { _Pragma("unroll") for (int m = 0; m < 4; ++m) _Pragma("unroll") for (int k = 0; k < 2; ++k) dst[m][k] = *(const PG8_LAS bf16x8*)(lds + PG8_SA(b, h) + aoff + m * 2048 + k * 1024); } while (0)
; #define PG8_LDB(dst, b, h) do { _Pragma("unroll") for (int n = 0; n < 2; ++n) _Pragma("unroll") for (int k = 0; k < 2; ++k) dst[n][k] = *(const PG8_LAS bf16x8*)(lds + PG8_SB(b, h) + boff + n * 2048 + k * 1024); } while (0)
; #define PG8_MMA(ai, bj, At, Bt) do { __builtin_amdgcn_s_setprio(1); _Pragma("unroll") for (int m = 0; m < 4; ++m) _Pragma("unroll") for (int n = 0; n < 2; ++n) _Pragma("unroll") for (int k = 0; k < 2; ++k) \
;         acc[ai][bj][m][n] = __builtin_amdgcn_mfma_f32_16x16x32_f16(Bt[n][k], At[m][k], acc[ai][bj][m][n], 0, 0, 0); __builtin_amdgcn_s_setprio(0); } while (0)
; #define PG8_WAIT_V(n) asm volatile("s_waitcnt vmcnt(" #n ")" ::: "memory")
; #define PG8_WAIT_L(n) asm volatile("s_waitcnt lgkmcnt(" #n ")" ::: "memory")
; #define PG8_BAR __builtin_amdgcn_s_barrier()
; #define PG8_SCHED __builtin_amdgcn_sched_barrier(0)
; template <class Epi, class Sched, bool ALIGN_EPI = false, bool SP2 = false>
; __device__ __forceinline__ void gemm_phase(PG8_LAS unsigned char* lds, const Gemm g, const Sched& S, const Epi& E) {
;     ...
;             PG8_LDB(B0, 1, 0); PG8_LDB(B1, 1, 1); PG8_SCHED; PG8_LDA(At, 1, 0); PG8_STAGE(PG8_SA(0, 1), a2 + hstep, voffA);
;             PG8_WAIT_V(8); PG8_WAIT_L(0); PG8_BAR; PG8_MMA(0, 0, At, B0); PG8_MMA(0, 1, At, B1); PG8_BAR; PG8_SCHED;
;             PG8_LDA(At, 1, 1); PG8_STAGE(PG8_SB(1, 0), b3, voffB); PG8_STAGE(PG8_SB(1, 1), b3 + hstep, voffB); PG8_STAGE(PG8_SA(1, 0), a3, voffA);
;             PG8_WAIT_V(8); PG8_WAIT_L(0); PG8_BAR; PG8_MMA(1, 0, At, B0); PG8_MMA(1, 1, At, B1); PG8_BAR; PG8_SCHED;
	s_add_i32 s82, 0, 0x18000
	s_add_i32 s83, 0, 0x1c000
	v_add_u32_e32 v140, s82, v196
	v_add_u32_e32 v156, s83, v196
	ds_read_b128 v[128:131], v140
	ds_read_b128 v[132:135], v140 offset:1024
	ds_read_b128 v[136:139], v140 offset:2048
	ds_read_b128 v[140:143], v140 offset:3072
	ds_read_b128 v[144:147], v156
	ds_read_b128 v[148:151], v156 offset:1024
	ds_read_b128 v[152:155], v156 offset:2048
	ds_read_b128 v[156:159], v156 offset:3072
	s_add_u32 s48, s48, 0x80000
	s_addc_u32 s49, s49, 0
	s_mov_b32 m0, s60
	ds_read_b128 v[176:179], v200 offset:32768
	ds_read_b128 v[180:183], v200 offset:33792
	ds_read_b128 v[184:187], v200 offset:34816
	ds_read_b128 v[188:191], v200 offset:35840
	ds_read_b128 v[208:211], v200 offset:36864
	ds_read_b128 v[212:215], v200 offset:37888
	ds_read_b128 v[216:219], v200 offset:38912
	ds_read_b128 v[220:223], v200 offset:39936
	global_load_lds_dwordx4 v160, s[48:49]
	s_mov_b32 m0, s61
	s_nop 0
	global_load_lds_dwordx4 v164, s[48:49]
	s_waitcnt vmcnt(8)
	s_waitcnt lgkmcnt(0)
	s_barrier
	s_waitcnt lgkmcnt(0)
	v_mfma_f32_16x16x32_f16 v[120:123], v[136:139], v[176:179], v[120:123]
	v_mfma_f32_16x16x32_f16 v[124:127], v[128:131], v[176:179], v[124:127]
	v_mfma_f32_16x16x32_f16 v[104:107], v[136:139], v[184:187], v[104:107]
	v_mfma_f32_16x16x32_f16 v[108:111], v[128:131], v[184:187], v[108:111]
	v_mfma_f32_16x16x32_f16 v[88:91], v[136:139], v[208:211], v[88:91]
	v_mfma_f32_16x16x32_f16 v[92:95], v[128:131], v[208:211], v[92:95]
	v_mfma_f32_16x16x32_f16 v[72:75], v[136:139], v[216:219], v[72:75]
	v_mfma_f32_16x16x32_f16 v[76:79], v[128:131], v[216:219], v[76:79]
	v_mfma_f32_16x16x32_f16 v[120:123], v[140:143], v[180:183], v[120:123]
	v_mfma_f32_16x16x32_f16 v[124:127], v[132:135], v[180:183], v[124:127]
	v_mfma_f32_16x16x32_f16 v[104:107], v[140:143], v[188:191], v[104:107]
	v_mfma_f32_16x16x32_f16 v[108:111], v[132:135], v[188:191], v[108:111]
	v_mfma_f32_16x16x32_f16 v[88:91], v[140:143], v[212:215], v[88:91]
	v_mfma_f32_16x16x32_f16 v[92:95], v[132:135], v[212:215], v[92:95]
	v_mfma_f32_16x16x32_f16 v[72:75], v[140:143], v[220:223], v[72:75]
	v_mfma_f32_16x16x32_f16 v[76:79], v[132:135], v[220:223], v[76:79]
	v_mfma_f32_16x16x32_f16 v[112:115], v[152:155], v[176:179], v[112:115]
	v_mfma_f32_16x16x32_f16 v[116:119], v[144:147], v[176:179], v[116:119]
	v_mfma_f32_16x16x32_f16 v[96:99], v[152:155], v[184:187], v[96:99]
	v_mfma_f32_16x16x32_f16 v[100:103], v[144:147], v[184:187], v[100:103]
	v_mfma_f32_16x16x32_f16 v[80:83], v[152:155], v[208:211], v[80:83]
	v_mfma_f32_16x16x32_f16 v[84:87], v[144:147], v[208:211], v[84:87]
	v_mfma_f32_16x16x32_f16 v[64:67], v[152:155], v[216:219], v[64:67]
	v_mfma_f32_16x16x32_f16 v[68:71], v[144:147], v[216:219], v[68:71]
	v_mfma_f32_16x16x32_f16 v[112:115], v[156:159], v[180:183], v[112:115]
	v_mfma_f32_16x16x32_f16 v[116:119], v[148:151], v[180:183], v[116:119]
	v_mfma_f32_16x16x32_f16 v[96:99], v[156:159], v[188:191], v[96:99]
	v_mfma_f32_16x16x32_f16 v[100:103], v[148:151], v[188:191], v[100:103]
	v_mfma_f32_16x16x32_f16 v[80:83], v[156:159], v[212:215], v[80:83]
	v_mfma_f32_16x16x32_f16 v[84:87], v[148:151], v[212:215], v[84:87]
	v_mfma_f32_16x16x32_f16 v[64:67], v[156:159], v[220:223], v[64:67]
	v_mfma_f32_16x16x32_f16 v[68:71], v[148:151], v[220:223], v[68:71]
	s_barrier
	s_add_i32 s48, s82, s52
	s_mov_b32 m0, s48
	ds_read_b128 v[176:179], v200 offset:49152
	ds_read_b128 v[180:183], v200 offset:50176
	ds_read_b128 v[184:187], v200 offset:51200
	ds_read_b128 v[188:191], v200 offset:52224
	ds_read_b128 v[208:211], v200 offset:53248
	ds_read_b128 v[212:215], v200 offset:54272
	ds_read_b128 v[216:219], v200 offset:55296
	ds_read_b128 v[220:223], v200 offset:56320
	global_load_lds_dwordx4 v162, s[98:99]
	s_add_i32 m0, s48, 0x2000
	s_add_u32 s44, s44, 0x80080
	s_addc_u32 s45, s45, 0
	s_add_i32 s48, s83, s52
	global_load_lds_dwordx4 v166, s[98:99]
	s_mov_b32 m0, s48
	s_nop 0
	global_load_lds_dwordx4 v162, s[44:45]
	s_add_i32 m0, s48, 0x2000
	s_nop 0
	global_load_lds_dwordx4 v166, s[44:45]
	s_mov_b32 m0, s63
	s_nop 0
	global_load_lds_dwordx4 v160, s[100:101]
	s_mov_b32 m0, s64
	s_nop 0
	global_load_lds_dwordx4 v164, s[100:101]
	s_waitcnt vmcnt(8)
	s_waitcnt lgkmcnt(0)
	s_barrier
	s_waitcnt lgkmcnt(0)
	v_mfma_f32_16x16x32_f16 v[56:59], v[136:139], v[176:179], v[56:59]
	v_mfma_f32_16x16x32_f16 v[60:63], v[128:131], v[176:179], v[60:63]
	v_mfma_f32_16x16x32_f16 v[40:43], v[136:139], v[184:187], v[40:43]
	v_mfma_f32_16x16x32_f16 v[44:47], v[128:131], v[184:187], v[44:47]
	v_mfma_f32_16x16x32_f16 v[24:27], v[136:139], v[208:211], v[24:27]
	v_mfma_f32_16x16x32_f16 v[28:31], v[128:131], v[208:211], v[28:31]
	v_mfma_f32_16x16x32_f16 v[8:11], v[136:139], v[216:219], v[8:11]
	v_mfma_f32_16x16x32_f16 v[12:15], v[128:131], v[216:219], v[12:15]
	v_mfma_f32_16x16x32_f16 v[56:59], v[140:143], v[180:183], v[56:59]
	v_mfma_f32_16x16x32_f16 v[60:63], v[132:135], v[180:183], v[60:63]
	v_mfma_f32_16x16x32_f16 v[40:43], v[140:143], v[188:191], v[40:43]
	v_mfma_f32_16x16x32_f16 v[44:47], v[132:135], v[188:191], v[44:47]
	v_mfma_f32_16x16x32_f16 v[24:27], v[140:143], v[212:215], v[24:27]
	v_mfma_f32_16x16x32_f16 v[28:31], v[132:135], v[212:215], v[28:31]
	v_mfma_f32_16x16x32_f16 v[8:11], v[140:143], v[220:223], v[8:11]
	v_mfma_f32_16x16x32_f16 v[12:15], v[132:135], v[220:223], v[12:15]
	v_mfma_f32_16x16x32_f16 v[48:51], v[152:155], v[176:179], v[48:51]
	v_mfma_f32_16x16x32_f16 v[52:55], v[144:147], v[176:179], v[52:55]
	v_mfma_f32_16x16x32_f16 v[32:35], v[152:155], v[184:187], v[32:35]
	v_mfma_f32_16x16x32_f16 v[36:39], v[144:147], v[184:187], v[36:39]
	v_mfma_f32_16x16x32_f16 v[16:19], v[152:155], v[208:211], v[16:19]
	v_mfma_f32_16x16x32_f16 v[20:23], v[144:147], v[208:211], v[20:23]
	v_mfma_f32_16x16x32_f16 v[0:3], v[152:155], v[216:219], v[0:3]
	v_mfma_f32_16x16x32_f16 v[4:7], v[144:147], v[216:219], v[4:7]
	v_mfma_f32_16x16x32_f16 v[48:51], v[156:159], v[180:183], v[48:51]
	v_mfma_f32_16x16x32_f16 v[52:55], v[148:151], v[180:183], v[52:55]
	v_mfma_f32_16x16x32_f16 v[32:35], v[156:159], v[188:191], v[32:35]
	v_mfma_f32_16x16x32_f16 v[36:39], v[148:151], v[188:191], v[36:39]
	v_mfma_f32_16x16x32_f16 v[16:19], v[156:159], v[212:215], v[16:19]
	v_mfma_f32_16x16x32_f16 v[20:23], v[148:151], v[212:215], v[20:23]
	v_mfma_f32_16x16x32_f16 v[0:3], v[156:159], v[220:223], v[0:3]
	v_mfma_f32_16x16x32_f16 v[4:7], v[148:151], v[220:223], v[4:7]
	s_barrier
	s_add_i32 s81, s81, 2
	s_add_u32 s74, s74, 0x100
	s_addc_u32 s75, s75, 0
	s_add_u32 s42, s42, 0x100
	s_addc_u32 s43, s43, 0
	s_cmp_gt_u32 s81, 29
	s_cbranch_scc0 .LBB0_1167
	s_and_b64 vcc, exec, s[18:19]
	s_cbranch_vccz .LBB0_1170
	s_barrier

; #define WS_SETUP unsigned char* ws = P.ws; asm volatile("" : "+s"(ws)); float* R = P.out; asm volatile("" : "+s"(R)); (void)R;
;     __host__ __device__ bool next(int i, Unit& u) const {
;     ...
;         int wgid = (int)L; { const int q = nwg / NXCD, r = nwg % NXCD, xcd = wgid % NXCD, off = wgid / NXCD; wgid = (xcd < r ? xcd * (q + 1) : r * (q + 1) + (xcd - r) * q) + off; }
;         const int nig = wgm * nN, gid = wgid / nig, fm = gid * wgm, gsz = (nM - fm) < wgm ? (nM - fm) : wgm;
;         u.pm = fm + ((wgid % nig) % gsz); u.pn = (wgid % nig) / gsz; return true;
; __global__ void __launch_bounds__(NWAVES * 64, 2) mega_fwd(Params P) {
;     ...
;     { WS_SETUP pg8::Gemm g{HID, (const h16*)(ws + WS_W_W2B), MTOK, DM, DFF}; pg8::EpiAny<2, 3> E{}; E.xbase = KV; E.xb = XB  ; E.ldc = DM; E.alpha = ALPHA; E.st_in = STATS + 4 * MTOK; E.g = P.in[10] + DM; E.b = P.in[11] + DM;
;       pg8::StaticOrder S; S.init(MTOK, DM, G, (int)blockIdx.x, WGM_N2048);
;       pg8::gemm_phase<pg8::EpiAny<2, 3>, pg8::StaticOrder, true, true>(lds, g, S, E); }
.LBB0_1226:
	s_or_b64 exec, exec, s[0:1]
	s_mov_b64 s[10:11], s[78:79]
	s_mov_b64 s[0:1], s[76:77]
	v_mov_b32_e32 v8, v204
	s_setprio 0
	v_readfirstlane_b32 s98, v204
	s_lshr_b32 s98, s98, 8
	s_cmp_lg_u32 s98, 0
	s_cbranch_scc0 .Lsprio_skip_10
	s_setprio 1
.Lsprio_skip_10:
	s_waitcnt lgkmcnt(0)
	s_barrier
	s_and_b64 vcc, exec, s[4:5]
	v_readfirstlane_b32 s5, v8
	s_cbranch_vccnz .LBB0_1250
	s_ashr_i32 s3, s2, 31
	s_lshr_b32 s0, s3, 29
	s_add_i32 s7, s2, s0
	s_and_b32 s0, s7, -8
	s_sub_i32 s6, s2, s0
	s_cmp_gt_i32 s6, -1
	s_cbranch_scc0 .LBB0_1229
	s_lshl_b32 s4, s6, 6
	s_ashr_i32 s0, s7, 3
	s_cbranch_execz .LBB0_1230
	s_branch .LBB0_1231

; #define PG8_STAGE(bufoff, gbase, voff) do { _Pragma("unroll") for (int _i = 0; _i < 2; ++_i) \
;         __builtin_amdgcn_global_load_lds((const unsigned*)((const char*)(gbase) + (voff)[_i]), (PG8_LAS unsigned*)(lds + (bufoff) + ldsw + _i * 8192), 16, 0, 0); } while (0)
; #define PG8_LDA(dst, b, h) do { _Pragma("unroll") for (int m = 0; m < 4; ++m) _Pragma("unroll") for (int k = 0; k < 2; ++k) dst[m][k] = *(const PG8_LAS bf16x8*)(lds + PG8_SA(b, h) + aoff + m * 2048 + k * 1024); } while (0)
; #define PG8_LDB(dst, b, h) do { _Pragma("unroll") for (int n = 0; n < 2; ++n) _Pragma("unroll") for (int k = 0; k < 2; ++k) dst[n][k] = *(const PG8_LAS bf16x8*)(lds + PG8_SB(b, h) + boff + n * 2048 + k * 1024); } while (0)
; #define PG8_MMA(ai, bj, At, Bt) do { __builtin_amdgcn_s_setprio(1); _Pragma("unroll") for (int m = 0; m < 4; ++m) _Pragma("unroll") for (int n = 0; n < 2; ++n) _Pragma("unroll") for (int k = 0; k < 2; ++k) \
;         acc[ai][bj][m][n] = __builtin_amdgcn_mfma_f32_16x16x32_f16(Bt[n][k], At[m][k], acc[ai][bj][m][n], 0, 0, 0); __builtin_amdgcn_s_setprio(0); } while (0)
; #define PG8_WAIT_V(n) asm volatile("s_waitcnt vmcnt(" #n ")" ::: "memory")
; #define PG8_WAIT_L(n) asm volatile("s_waitcnt lgkmcnt(" #n ")" ::: "memory")
; #define PG8_BAR __builtin_amdgcn_s_barrier()
; #define PG8_SCHED __builtin_amdgcn_sched_barrier(0)
; template <class Epi, class Sched, bool ALIGN_EPI = false, bool SP2 = false>
; __device__ __forceinline__ void gemm_phase(PG8_LAS unsigned char* lds, const Gemm g, const Sched& S, const Epi& E) {
;     ...
;             PG8_LDB(B0, 0, 0); PG8_LDB(B1, 0, 1); PG8_SCHED; PG8_LDA(At, 0, 0); PG8_STAGE(PG8_SA(1, 1), a1 + hstep, voffA);
;             PG8_WAIT_V(8); PG8_WAIT_L(0); PG8_BAR; PG8_MMA(0, 0, At, B0); PG8_MMA(0, 1, At, B1); PG8_BAR; PG8_SCHED;
;             PG8_LDA(At, 0, 1); PG8_STAGE(PG8_SB(0, 0), b2, voffB); PG8_STAGE(PG8_SB(0, 1), b2 + hstep, voffB); PG8_STAGE(PG8_SA(0, 0), a2, voffA);
;             PG8_WAIT_V(8); PG8_WAIT_L(0); PG8_BAR; PG8_MMA(1, 0, At, B0); PG8_MMA(1, 1, At, B1); PG8_BAR; PG8_SCHED;
.LBB0_1243:
	ds_read_b128 v[128:131], v189
	ds_read_b128 v[132:135], v189 offset:1024
	ds_read_b128 v[136:139], v189 offset:2048
	ds_read_b128 v[140:143], v189 offset:3072
	ds_read_b128 v[144:147], v190
	ds_read_b128 v[148:151], v190 offset:1024
	ds_read_b128 v[152:155], v190 offset:2048
	ds_read_b128 v[156:159], v190 offset:3072
	s_add_u32 s34, s30, 0xffe00080
	s_addc_u32 s35, s31, -1
	s_cmpk_eq_i32 s61, 0x7c
	s_cselect_b32 s37, s23, s35
	s_cselect_b32 s36, s51, s34
	s_cselect_b32 s35, s21, s60
	s_cselect_b32 s34, s52, s53
	s_add_i32 m0, s29, 0xc000
	ds_read_b128 v[176:179], v191
	ds_read_b128 v[180:183], v191 offset:1024
	ds_read_b128 v[192:195], v191 offset:2048
	ds_read_b128 v[196:199], v191 offset:3072
	ds_read_b128 v[200:203], v191 offset:4096
	ds_read_b128 v[208:211], v191 offset:5120
	ds_read_b128 v[212:215], v191 offset:6144
	ds_read_b128 v[216:219], v191 offset:7168
	global_load_lds_dwordx4 v170, s[30:31]
	s_add_i32 m0, s29, 0xe000
	s_nop 0
	global_load_lds_dwordx4 v168, s[30:31]
	s_waitcnt vmcnt(8)
	s_waitcnt lgkmcnt(0)
	s_barrier
	s_waitcnt lgkmcnt(0)
	v_mfma_f32_16x16x32_f16 v[120:123], v[136:139], v[176:179], v[120:123]
	v_mfma_f32_16x16x32_f16 v[124:127], v[128:131], v[176:179], v[124:127]
	v_mfma_f32_16x16x32_f16 v[104:107], v[136:139], v[192:195], v[104:107]
	v_mfma_f32_16x16x32_f16 v[108:111], v[128:131], v[192:195], v[108:111]
	v_mfma_f32_16x16x32_f16 v[88:91], v[136:139], v[200:203], v[88:91]
	v_mfma_f32_16x16x32_f16 v[92:95], v[128:131], v[200:203], v[92:95]
	v_mfma_f32_16x16x32_f16 v[72:75], v[136:139], v[212:215], v[72:75]
	v_mfma_f32_16x16x32_f16 v[76:79], v[128:131], v[212:215], v[76:79]
	v_mfma_f32_16x16x32_f16 v[120:123], v[140:143], v[180:183], v[120:123]
	v_mfma_f32_16x16x32_f16 v[124:127], v[132:135], v[180:183], v[124:127]
	v_mfma_f32_16x16x32_f16 v[104:107], v[140:143], v[196:199], v[104:107]
	v_mfma_f32_16x16x32_f16 v[108:111], v[132:135], v[196:199], v[108:111]
	v_mfma_f32_16x16x32_f16 v[88:91], v[140:143], v[208:211], v[88:91]
	v_mfma_f32_16x16x32_f16 v[92:95], v[132:135], v[208:211], v[92:95]
	v_mfma_f32_16x16x32_f16 v[72:75], v[140:143], v[216:219], v[72:75]
	v_mfma_f32_16x16x32_f16 v[76:79], v[132:135], v[216:219], v[76:79]
	v_mfma_f32_16x16x32_f16 v[112:115], v[152:155], v[176:179], v[112:115]
	v_mfma_f32_16x16x32_f16 v[116:119], v[144:147], v[176:179], v[116:119]
	v_mfma_f32_16x16x32_f16 v[96:99], v[152:155], v[192:195], v[96:99]
	v_mfma_f32_16x16x32_f16 v[100:103], v[144:147], v[192:195], v[100:103]
	v_mfma_f32_16x16x32_f16 v[80:83], v[152:155], v[200:203], v[80:83]
	v_mfma_f32_16x16x32_f16 v[84:87], v[144:147], v[200:203], v[84:87]
	v_mfma_f32_16x16x32_f16 v[64:67], v[152:155], v[212:215], v[64:67]
	v_mfma_f32_16x16x32_f16 v[68:71], v[144:147], v[212:215], v[68:71]
	v_mfma_f32_16x16x32_f16 v[112:115], v[156:159], v[180:183], v[112:115]
	v_mfma_f32_16x16x32_f16 v[116:119], v[148:151], v[180:183], v[116:119]
	v_mfma_f32_16x16x32_f16 v[96:99], v[156:159], v[196:199], v[96:99]
	v_mfma_f32_16x16x32_f16 v[100:103], v[148:151], v[196:199], v[100:103]
	v_mfma_f32_16x16x32_f16 v[80:83], v[156:159], v[208:211], v[80:83]
	v_mfma_f32_16x16x32_f16 v[84:87], v[148:151], v[208:211], v[84:87]
	v_mfma_f32_16x16x32_f16 v[64:67], v[156:159], v[216:219], v[64:67]
	v_mfma_f32_16x16x32_f16 v[68:71], v[148:151], v[216:219], v[68:71]
	s_barrier
	s_add_i32 s62, s48, s39
	s_add_u32 s98, s34, s12
	s_addc_u32 s99, s35, s13
	s_mov_b32 m0, s62
	ds_read_b128 v[176:179], v191 offset:16384
	ds_read_b128 v[180:183], v191 offset:17408
	ds_read_b128 v[192:195], v191 offset:18432
	ds_read_b128 v[196:199], v191 offset:19456
	ds_read_b128 v[200:203], v191 offset:20480
	ds_read_b128 v[208:211], v191 offset:21504
	ds_read_b128 v[212:215], v191 offset:22528
	ds_read_b128 v[216:219], v191 offset:23552
	global_load_lds_dwordx4 v162, s[34:35]
	s_add_i32 m0, s62, 0x2000
	s_add_u32 s62, s34, 0x200000
	s_addc_u32 s63, s35, 0
	s_add_i32 s64, s49, s39
	global_load_lds_dwordx4 v166, s[34:35]
	s_mov_b32 m0, s64
	s_nop 0
	global_load_lds_dwordx4 v162, s[62:63]
	s_add_i32 m0, s64, 0x2000
	s_nop 0
	global_load_lds_dwordx4 v166, s[62:63]
	s_add_u32 s100, s36, s12
	s_addc_u32 s101, s37, s13
	s_mov_b32 m0, s29
	s_nop 0
	global_load_lds_dwordx4 v160, s[36:37]
	s_mov_b32 m0, s40
	s_nop 0
	global_load_lds_dwordx4 v164, s[36:37]
	s_waitcnt vmcnt(8)
	s_waitcnt lgkmcnt(0)
	s_barrier
	s_waitcnt lgkmcnt(0)
	v_mfma_f32_16x16x32_f16 v[56:59], v[136:139], v[176:179], v[56:59]
	v_mfma_f32_16x16x32_f16 v[60:63], v[128:131], v[176:179], v[60:63]
	v_mfma_f32_16x16x32_f16 v[40:43], v[136:139], v[192:195], v[40:43]
	v_mfma_f32_16x16x32_f16 v[44:47], v[128:131], v[192:195], v[44:47]
	v_mfma_f32_16x16x32_f16 v[24:27], v[136:139], v[200:203], v[24:27]
	v_mfma_f32_16x16x32_f16 v[28:31], v[128:131], v[200:203], v[28:31]
	v_mfma_f32_16x16x32_f16 v[8:11], v[136:139], v[212:215], v[8:11]
	v_mfma_f32_16x16x32_f16 v[12:15], v[128:131], v[212:215], v[12:15]
	v_mfma_f32_16x16x32_f16 v[56:59], v[140:143], v[180:183], v[56:59]
	v_mfma_f32_16x16x32_f16 v[60:63], v[132:135], v[180:183], v[60:63]
	v_mfma_f32_16x16x32_f16 v[40:43], v[140:143], v[196:199], v[40:43]
	v_mfma_f32_16x16x32_f16 v[44:47], v[132:135], v[196:199], v[44:47]
	v_mfma_f32_16x16x32_f16 v[24:27], v[140:143], v[208:211], v[24:27]
	v_mfma_f32_16x16x32_f16 v[28:31], v[132:135], v[208:211], v[28:31]
	v_mfma_f32_16x16x32_f16 v[8:11], v[140:143], v[216:219], v[8:11]
	v_mfma_f32_16x16x32_f16 v[12:15], v[132:135], v[216:219], v[12:15]
	v_mfma_f32_16x16x32_f16 v[48:51], v[152:155], v[176:179], v[48:51]
	v_mfma_f32_16x16x32_f16 v[52:55], v[144:147], v[176:179], v[52:55]
	v_mfma_f32_16x16x32_f16 v[32:35], v[152:155], v[192:195], v[32:35]
	v_mfma_f32_16x16x32_f16 v[36:39], v[144:147], v[192:195], v[36:39]
	v_mfma_f32_16x16x32_f16 v[16:19], v[152:155], v[200:203], v[16:19]
	v_mfma_f32_16x16x32_f16 v[20:23], v[144:147], v[200:203], v[20:23]
	v_mfma_f32_16x16x32_f16 v[0:3], v[152:155], v[212:215], v[0:3]
	v_mfma_f32_16x16x32_f16 v[4:7], v[144:147], v[212:215], v[4:7]
	v_mfma_f32_16x16x32_f16 v[48:51], v[156:159], v[180:183], v[48:51]
	v_mfma_f32_16x16x32_f16 v[52:55], v[148:151], v[180:183], v[52:55]
	v_mfma_f32_16x16x32_f16 v[32:35], v[156:159], v[196:199], v[32:35]
	v_mfma_f32_16x16x32_f16 v[36:39], v[148:151], v[196:199], v[36:39]
	v_mfma_f32_16x16x32_f16 v[16:19], v[156:159], v[208:211], v[16:19]
	v_mfma_f32_16x16x32_f16 v[20:23], v[148:151], v[208:211], v[20:23]
	v_mfma_f32_16x16x32_f16 v[0:3], v[156:159], v[216:219], v[0:3]
	v_mfma_f32_16x16x32_f16 v[4:7], v[148:151], v[216:219], v[4:7]
	s_barrier
; #define PG8_STAGE(bufoff, gbase, voff) do { _Pragma("unroll") for (int _i = 0; _i < 2; ++_i) \
;         __builtin_amdgcn_global_load_lds((const unsigned*)((const char*)(gbase) + (voff)[_i]), (PG8_LAS unsigned*)(lds + (bufoff) + ldsw + _i * 8192), 16, 0, 0); } while (0)
; #define PG8_LDA(dst, b, h) do { _Pragma("unroll") for (int m = 0; m < 4; ++m) _Pragma("unroll") for (int k = 0; k < 2; ++k) dst[m][k] = *(const PG8_LAS bf16x8*)(lds + PG8_SA(b, h) + aoff + m * 2048 + k * 1024); } while (0)
; #define PG8_LDB(dst, b, h) do { _Pragma("unroll") for (int n = 0; n < 2; ++n) _Pragma("unroll") for (int k = 0; k < 2; ++k) dst[n][k] = *(const PG8_LAS bf16x8*)(lds + PG8_SB(b, h) + boff + n * 2048 + k * 1024); } while (0)
; #define PG8_MMA(ai, bj, At, Bt) do { __builtin_amdgcn_s_setprio(1); _Pragma("unroll") for (int m = 0; m < 4; ++m) _Pragma("unroll") for (int n = 0; n < 2; ++n) _Pragma("unroll") for (int k = 0; k < 2; ++k) \
;         acc[ai][bj][m][n] = __builtin_amdgcn_mfma_f32_16x16x32_f16(Bt[n][k], At[m][k], acc[ai][bj][m][n], 0, 0, 0); __builtin_amdgcn_s_setprio(0); } while (0)
; #define PG8_WAIT_V(n) asm volatile("s_waitcnt vmcnt(" #n ")" ::: "memory")
; #define PG8_WAIT_L(n) asm volatile("s_waitcnt lgkmcnt(" #n ")" ::: "memory")
; #define PG8_BAR __builtin_amdgcn_s_barrier()
; #define PG8_SCHED __builtin_amdgcn_sched_barrier(0)
; template <class Epi, class Sched, bool ALIGN_EPI = false, bool SP2 = false>
; __device__ __forceinline__ void gemm_phase(PG8_LAS unsigned char* lds, const Gemm g, const Sched& S, const Epi& E) {
;     ...
;             PG8_LDB(B0, 1, 0); PG8_LDB(B1, 1, 1); PG8_SCHED; PG8_LDA(At, 1, 0); PG8_STAGE(PG8_SA(0, 1), a2 + hstep, voffA);
;             PG8_WAIT_V(8); PG8_WAIT_L(0); PG8_BAR; PG8_MMA(0, 0, At, B0); PG8_MMA(0, 1, At, B1); PG8_BAR; PG8_SCHED;
;             PG8_LDA(At, 1, 1); PG8_STAGE(PG8_SB(1, 0), b3, voffB); PG8_STAGE(PG8_SB(1, 1), b3 + hstep, voffB); PG8_STAGE(PG8_SA(1, 0), a3, voffA);
;             PG8_WAIT_V(8); PG8_WAIT_L(0); PG8_BAR; PG8_MMA(1, 0, At, B0); PG8_MMA(1, 1, At, B1); PG8_BAR; PG8_SCHED;
	s_add_i32 s62, 0, 0x18000
	s_add_i32 s63, 0, 0x1c000
	v_add_u32_e32 v140, s62, v187
	v_add_u32_e32 v156, s63, v187
	ds_read_b128 v[128:131], v140
	ds_read_b128 v[132:135], v140 offset:1024
	ds_read_b128 v[136:139], v140 offset:2048
	ds_read_b128 v[140:143], v140 offset:3072
	ds_read_b128 v[144:147], v156
	ds_read_b128 v[148:151], v156 offset:1024
	ds_read_b128 v[152:155], v156 offset:2048
	ds_read_b128 v[156:159], v156 offset:3072
	s_add_u32 s36, s36, 0x200000
	s_addc_u32 s37, s37, 0
	s_mov_b32 m0, s41
	ds_read_b128 v[176:179], v191 offset:32768
	ds_read_b128 v[180:183], v191 offset:33792
	ds_read_b128 v[192:195], v191 offset:34816
	ds_read_b128 v[196:199], v191 offset:35840
	ds_read_b128 v[200:203], v191 offset:36864
	ds_read_b128 v[208:211], v191 offset:37888
	ds_read_b128 v[212:215], v191 offset:38912
	ds_read_b128 v[216:219], v191 offset:39936
	global_load_lds_dwordx4 v160, s[36:37]
	s_mov_b32 m0, s42
	s_nop 0
	global_load_lds_dwordx4 v164, s[36:37]
	s_waitcnt vmcnt(8)
	s_waitcnt lgkmcnt(0)
	s_barrier
	s_waitcnt lgkmcnt(0)
	v_mfma_f32_16x16x32_f16 v[120:123], v[136:139], v[176:179], v[120:123]
	v_mfma_f32_16x16x32_f16 v[124:127], v[128:131], v[176:179], v[124:127]
	v_mfma_f32_16x16x32_f16 v[104:107], v[136:139], v[192:195], v[104:107]
	v_mfma_f32_16x16x32_f16 v[108:111], v[128:131], v[192:195], v[108:111]
	v_mfma_f32_16x16x32_f16 v[88:91], v[136:139], v[200:203], v[88:91]
	v_mfma_f32_16x16x32_f16 v[92:95], v[128:131], v[200:203], v[92:95]
	v_mfma_f32_16x16x32_f16 v[72:75], v[136:139], v[212:215], v[72:75]
	v_mfma_f32_16x16x32_f16 v[76:79], v[128:131], v[212:215], v[76:79]
	v_mfma_f32_16x16x32_f16 v[120:123], v[140:143], v[180:183], v[120:123]
	v_mfma_f32_16x16x32_f16 v[124:127], v[132:135], v[180:183], v[124:127]
	v_mfma_f32_16x16x32_f16 v[104:107], v[140:143], v[196:199], v[104:107]
	v_mfma_f32_16x16x32_f16 v[108:111], v[132:135], v[196:199], v[108:111]
	v_mfma_f32_16x16x32_f16 v[88:91], v[140:143], v[208:211], v[88:91]
	v_mfma_f32_16x16x32_f16 v[92:95], v[132:135], v[208:211], v[92:95]
	v_mfma_f32_16x16x32_f16 v[72:75], v[140:143], v[216:219], v[72:75]
	v_mfma_f32_16x16x32_f16 v[76:79], v[132:135], v[216:219], v[76:79]
	v_mfma_f32_16x16x32_f16 v[112:115], v[152:155], v[176:179], v[112:115]
	v_mfma_f32_16x16x32_f16 v[116:119], v[144:147], v[176:179], v[116:119]
	v_mfma_f32_16x16x32_f16 v[96:99], v[152:155], v[192:195], v[96:99]
	v_mfma_f32_16x16x32_f16 v[100:103], v[144:147], v[192:195], v[100:103]
	v_mfma_f32_16x16x32_f16 v[80:83], v[152:155], v[200:203], v[80:83]
	v_mfma_f32_16x16x32_f16 v[84:87], v[144:147], v[200:203], v[84:87]
	v_mfma_f32_16x16x32_f16 v[64:67], v[152:155], v[212:215], v[64:67]
	v_mfma_f32_16x16x32_f16 v[68:71], v[144:147], v[212:215], v[68:71]
	v_mfma_f32_16x16x32_f16 v[112:115], v[156:159], v[180:183], v[112:115]
	v_mfma_f32_16x16x32_f16 v[116:119], v[148:151], v[180:183], v[116:119]
	v_mfma_f32_16x16x32_f16 v[96:99], v[156:159], v[196:199], v[96:99]
	v_mfma_f32_16x16x32_f16 v[100:103], v[148:151], v[196:199], v[100:103]
	v_mfma_f32_16x16x32_f16 v[80:83], v[156:159], v[208:211], v[80:83]
	v_mfma_f32_16x16x32_f16 v[84:87], v[148:151], v[208:211], v[84:87]
	v_mfma_f32_16x16x32_f16 v[64:67], v[156:159], v[216:219], v[64:67]
	v_mfma_f32_16x16x32_f16 v[68:71], v[148:151], v[216:219], v[68:71]
	s_barrier
	s_add_i32 s36, s62, s39
	s_mov_b32 m0, s36
	ds_read_b128 v[176:179], v191 offset:49152
	ds_read_b128 v[180:183], v191 offset:50176
	ds_read_b128 v[192:195], v191 offset:51200
	ds_read_b128 v[196:199], v191 offset:52224
	ds_read_b128 v[200:203], v191 offset:53248
	ds_read_b128 v[208:211], v191 offset:54272
	ds_read_b128 v[212:215], v191 offset:55296
	ds_read_b128 v[216:219], v191 offset:56320
	global_load_lds_dwordx4 v162, s[98:99]
	s_add_i32 m0, s36, 0x2000
	s_add_u32 s34, s34, 0x200080
	s_addc_u32 s35, s35, 0
	s_add_i32 s36, s63, s39
	global_load_lds_dwordx4 v166, s[98:99]
	s_mov_b32 m0, s36
	s_nop 0
	global_load_lds_dwordx4 v162, s[34:35]
	s_add_i32 m0, s36, 0x2000
	s_nop 0
	global_load_lds_dwordx4 v166, s[34:35]
	s_mov_b32 m0, s44
	s_nop 0
	global_load_lds_dwordx4 v160, s[100:101]
	s_mov_b32 m0, s45
	s_nop 0
	global_load_lds_dwordx4 v164, s[100:101]
	s_waitcnt vmcnt(8)
	s_waitcnt lgkmcnt(0)
	s_barrier
	s_waitcnt lgkmcnt(0)
	v_mfma_f32_16x16x32_f16 v[56:59], v[136:139], v[176:179], v[56:59]
	v_mfma_f32_16x16x32_f16 v[60:63], v[128:131], v[176:179], v[60:63]
	v_mfma_f32_16x16x32_f16 v[40:43], v[136:139], v[192:195], v[40:43]
	v_mfma_f32_16x16x32_f16 v[44:47], v[128:131], v[192:195], v[44:47]
	v_mfma_f32_16x16x32_f16 v[24:27], v[136:139], v[200:203], v[24:27]
	v_mfma_f32_16x16x32_f16 v[28:31], v[128:131], v[200:203], v[28:31]
	v_mfma_f32_16x16x32_f16 v[8:11], v[136:139], v[212:215], v[8:11]
	v_mfma_f32_16x16x32_f16 v[12:15], v[128:131], v[212:215], v[12:15]
	v_mfma_f32_16x16x32_f16 v[56:59], v[140:143], v[180:183], v[56:59]
	v_mfma_f32_16x16x32_f16 v[60:63], v[132:135], v[180:183], v[60:63]
	v_mfma_f32_16x16x32_f16 v[40:43], v[140:143], v[196:199], v[40:43]
	v_mfma_f32_16x16x32_f16 v[44:47], v[132:135], v[196:199], v[44:47]
	v_mfma_f32_16x16x32_f16 v[24:27], v[140:143], v[208:211], v[24:27]
	v_mfma_f32_16x16x32_f16 v[28:31], v[132:135], v[208:211], v[28:31]
	v_mfma_f32_16x16x32_f16 v[8:11], v[140:143], v[216:219], v[8:11]
	v_mfma_f32_16x16x32_f16 v[12:15], v[132:135], v[216:219], v[12:15]
	v_mfma_f32_16x16x32_f16 v[48:51], v[152:155], v[176:179], v[48:51]
	v_mfma_f32_16x16x32_f16 v[52:55], v[144:147], v[176:179], v[52:55]
	v_mfma_f32_16x16x32_f16 v[32:35], v[152:155], v[192:195], v[32:35]
	v_mfma_f32_16x16x32_f16 v[36:39], v[144:147], v[192:195], v[36:39]
	v_mfma_f32_16x16x32_f16 v[16:19], v[152:155], v[200:203], v[16:19]
	v_mfma_f32_16x16x32_f16 v[20:23], v[144:147], v[200:203], v[20:23]
	v_mfma_f32_16x16x32_f16 v[0:3], v[152:155], v[212:215], v[0:3]
	v_mfma_f32_16x16x32_f16 v[4:7], v[144:147], v[212:215], v[4:7]
	v_mfma_f32_16x16x32_f16 v[48:51], v[156:159], v[180:183], v[48:51]
	v_mfma_f32_16x16x32_f16 v[52:55], v[148:151], v[180:183], v[52:55]
	v_mfma_f32_16x16x32_f16 v[32:35], v[156:159], v[196:199], v[32:35]
	v_mfma_f32_16x16x32_f16 v[36:39], v[148:151], v[196:199], v[36:39]
	v_mfma_f32_16x16x32_f16 v[16:19], v[156:159], v[208:211], v[16:19]
	v_mfma_f32_16x16x32_f16 v[20:23], v[148:151], v[208:211], v[20:23]
	v_mfma_f32_16x16x32_f16 v[0:3], v[156:159], v[216:219], v[0:3]
	v_mfma_f32_16x16x32_f16 v[4:7], v[148:151], v[216:219], v[4:7]
	s_barrier
	s_add_i32 s61, s61, 2
	s_add_u32 s53, s53, 0x100
	s_addc_u32 s60, s60, 0
	s_add_u32 s30, s30, 0x100
	s_addc_u32 s31, s31, 0
	s_cmpk_gt_u32 s61, 0x7d
	s_cbranch_scc0 .LBB0_1243
	s_and_b64 vcc, exec, s[14:15]
	s_cbranch_vccz .LBB0_1246
	s_barrier
